# P5 EpiZ epilogue rewritten (tile-uniform activation dispatch, one-float row sums via atomics from P3 epilogue, header-loaded shift vector) on top of v18
# speedup vs baseline: 1.0536x; 1.0142x over previous
; #define SEAM(k) do { if (IN(k) && IN((k) + 1)) { if (a.ph_hi > 4096) cg::this_grid().sync(); else xcd_barrier(xbar); } } while (0)
; __global__ void __launch_bounds__(512, 2) fwd_kernel(Args a) {
;     ...
;     if (IN(1)) { norm_mod_phase(a.in[I_X], a.in[I_CTX], MALL, a.in[I_N1G], mod, 0, 1, XN, gw, NGW, lane);
;         shiftw_phase((const bf16_t*)(ws + WS_WIN), ZW, mod, 3, (float*)(ws + WS_SHW1), gw, NGW, lane, true); shiftw_phase((const bf16_t*)(ws + WS_W2A), NFF2, mod, 6, (float*)(ws + WS_SHW2), NGW - 1 - gw, NGW, lane, false); } SEAM(1);
.LBB0_120:
	v_lshl_add_u32 v252, s92, 6, v146
	v_lshlrev_b32_e32 v252, 2, v252
	v_mov_b32_e32 v253, 0
	s_add_u32 s98, s88, 0x3c900000
	s_addc_u32 s99, s89, 0
	v_cmp_gt_u32_e32 vcc, 0x44000, v252
	s_nop 4
	s_and_saveexec_b64 s[100:101], vcc
	global_store_dword v252, v253, s[98:99]
	s_or_b64 exec, exec, s[100:101]
	v_lshl_add_u32 v252, s92, 6, v146
	v_lshlrev_b32_e32 v252, 2, v252
	v_mov_b32_e32 v253, 0
	s_add_u32 s98, s88, 0x3ce00000
	s_addc_u32 s99, s89, 0
	v_cmp_gt_u32_e32 vcc, 0x40000, v252
	s_nop 4
	s_and_saveexec_b64 s[100:101], vcc
	global_store_dword v252, v253, s[98:99]
	s_or_b64 exec, exec, s[100:101]
	s_cmp_gt_i32 s91, 1
	s_cselect_b64 s[0:1], -1, 0
	s_and_b64 s[4:5], s[6:7], s[0:1]
	s_andn2_b64 vcc, exec, s[4:5]
	s_cbranch_vccnz .LBB0_184
	s_cmpk_lt_u32 s91, 0x1001
	s_mov_b64 s[4:5], -1
	s_cbranch_scc0 .LBB0_171
	s_waitcnt vmcnt(0)
	s_waitcnt lgkmcnt(0)
	s_barrier
	s_mov_b64 s[4:5], exec
	v_readlane_b32 s6, v242, 3
	v_readlane_b32 s7, v242, 4
	s_and_b64 s[6:7], s[4:5], s[6:7]
	s_mov_b64 exec, s[6:7]
	s_cbranch_execz .LBB0_170
	s_add_i32 s6, 0, 0x23fc0
	v_mov_b32_e32 v2, s6
	s_waitcnt vmcnt(0) expcnt(0) lgkmcnt(0)
	ds_read_b32 v4, v2
	s_add_i32 s6, 0, 0x23fc4
	v_mov_b32_e32 v2, s6
	ds_read_b32 v2, v2
	s_waitcnt lgkmcnt(1)
	v_cmp_ne_u32_e32 vcc, 0, v4
	s_cbranch_vccnz .LBB0_138
	v_readlane_b32 s6, v242, 0
	v_readlane_b32 s7, v242, 1
	s_load_dwordx2 s[12:13], s[6:7], 0x4
	s_add_u32 s6, s88, 0x1000
	s_addc_u32 s7, s89, 0
	s_add_u32 s8, s88, 0x1100
	s_addc_u32 s9, s89, 0
	s_waitcnt lgkmcnt(0)
	s_mul_i32 s33, s12, s50
	s_add_u32 s12, s88, 0x1200
	s_mul_i32 s33, s33, s13
	s_addc_u32 s13, s89, 0
	s_add_u32 s24, s88, 0x1300
	s_addc_u32 s25, s89, 0
	s_mov_b32 s34, 1
	v_mov_b32_e32 v18, 0
	s_branch .LBB0_126

; DEV u32x4 pack8v(const f32x4 a, const f32x4 b) { u32x4 w; w.x = cvt_pk_bf16(a[0], a[1]); w.y = cvt_pk_bf16(a[2], a[3]); w.z = cvt_pk_bf16(b[0], b[1]); w.w = cvt_pk_bf16(b[2], b[3]); return w; }
;     DEV void operator()(const f32x4 (&acc)[2][2][4][2], const Unit& u, int wr, int wc, int fr, int fq) const {
;     ...
;         const bool lat = u.pm < MLAT / 256; const int b = lat ? (u.pm >> 4) : 16;
;         const float* res = lat ? res_lat : res_ctx; float* out = lat ? out_lat : out_ctx;
;         const int grow0 = u.pm * 256 + wr * 64 + fr, row0 = (lat ? grow0 : grow0 - MLAT), col0 = u.pn * 256 + wc * 32 + (PERM ? 8 : 4) * fq;
;         float ss[8];
; #pragma unroll
;         for (int i = 0; i < 8; ++i) ss[i] = 0.f;
; #pragma unroll
;         for (int bj = 0; bj < 2; ++bj) {
;             f32x4 gv[2], gs[2];
; #pragma unroll
;             for (int n = 0; n < 2; ++n) { gv[n] = *(const f32x4*)(mod + (size_t)b * NMOD + gate_i * D + col0 + bj * 128 + NS * n) * coef;
;                 if (has_xn) gs[n] = *(const f32x4*)(g + col0 + bj * 128 + 4 * n) * (*(const f32x4*)(mod + (size_t)b * NMOD + scale_i * D + col0 + bj * 128 + 4 * n) + 1.f); }
; #pragma unroll
;             for (int ai = 0; ai < 2; ++ai)
; #pragma unroll
;                 for (int m = 0; m < 4; ++m) {
;                     const size_t p = (size_t)(row0 + ai * 128 + m * 16) * D + col0 + bj * 128;
;                     const f32x4 r0 = *(const f32x4*)(res + p), r1 = *(const f32x4*)(res + p + NS);
;                     const f32x4 o0 = r0 + gv[0] * acc[ai][bj][m][0], o1 = r1 + gv[1] * acc[ai][bj][m][1];
;                     *(f32x4*)(out + p) = o0; *(f32x4*)(out + p + NS) = o1;
;                     if (has_xn) { ss[ai * 4 + m] += (o0[0] * o0[0] + o0[1] * o0[1]) + (o0[2] * o0[2] + o0[3] * o0[3]) + (o1[0] * o1[0] + o1[1] * o1[1]) + (o1[2] * o1[2] + o1[3] * o1[3]);
;                         *(u32x4*)(xn + (size_t)(grow0 + ai * 128 + m * 16) * D + col0 + bj * 128) = pack8v(o0 * gs[0], o1 * gs[1]); }
.Lp3e_common:
	s_add_u32 s12, s94, s40
	s_addc_u32 s13, s95, 0
	s_add_u32 s16, s12, 0x4000
	s_addc_u32 s17, s13, 0
	s_add_u32 s12, s12, 0x2000
	s_addc_u32 s13, s13, 0
	s_lshl_b32 s41, s82, 8
	s_or_b32 s41, s41, s67
	v_lshl_add_u32 v180, v226, 3, s41
	v_add_u32_e32 v181, s39, v147
	v_lshlrev_b32_e32 v225, 2, v180
	v_lshl_add_u32 v224, v181, 12, v225
	v_add_u32_e32 v182, s38, v147
	v_lshlrev_b32_e32 v183, 1, v180
	v_lshl_add_u32 v240, v182, 11, v183
	v_mov_b32_e32 v241, 0
	v_mov_b32_e32 v243, 0
	v_mov_b32_e32 v252, 0
	v_mov_b32_e32 v253, 0
	v_mov_b32_e32 v254, 0
	v_mov_b32_e32 v255, 0
	v_mov_b32_e32 v248, 0
	v_mov_b32_e32 v249, 0
	global_load_dwordx4 v[148:151], v225, s[12:13] offset:0
	global_load_dwordx4 v[152:155], v225, s[12:13] offset:16
	global_load_dwordx4 v[156:159], v225, s[12:13] offset:512
	global_load_dwordx4 v[160:163], v225, s[12:13] offset:528
	global_load_dwordx4 v[164:167], v225, s[18:19] offset:0
	global_load_dwordx4 v[168:171], v225, s[18:19] offset:16
	global_load_dwordx4 v[172:175], v225, s[18:19] offset:512
	global_load_dwordx4 v[176:179], v225, s[18:19] offset:528
	global_load_dwordx4 v[212:215], v225, s[16:17] offset:0
	global_load_dwordx4 v[216:219], v225, s[16:17] offset:16
	global_load_dwordx4 v[220:223], v225, s[16:17] offset:512
	global_load_dwordx4 v[232:235], v225, s[16:17] offset:528
	global_load_dwordx4 v[180:183], v224, s[8:9] offset:0
	global_load_dwordx4 v[184:187], v224, s[8:9] offset:16
	global_load_dwordx4 v[188:191], v224, s[8:9] offset:512
	global_load_dwordx4 v[192:195], v224, s[8:9] offset:528
	s_add_u32 s14, s8, 0x10000
	s_addc_u32 s15, s9, 0
	global_load_dwordx4 v[196:199], v224, s[14:15] offset:0
	global_load_dwordx4 v[200:203], v224, s[14:15] offset:16
	global_load_dwordx4 v[204:207], v224, s[14:15] offset:512
	global_load_dwordx4 v[208:211], v224, s[14:15] offset:528
	s_waitcnt vmcnt(8)
	v_pk_mul_f32 v[148:149], v[148:149], 0.5 op_sel_hi:[1,0]
	v_pk_mul_f32 v[150:151], v[150:151], 0.5 op_sel_hi:[1,0]
	v_pk_mul_f32 v[152:153], v[152:153], 0.5 op_sel_hi:[1,0]
	v_pk_mul_f32 v[154:155], v[154:155], 0.5 op_sel_hi:[1,0]
	v_pk_mul_f32 v[156:157], v[156:157], 0.5 op_sel_hi:[1,0]
	v_pk_mul_f32 v[158:159], v[158:159], 0.5 op_sel_hi:[1,0]
	v_pk_mul_f32 v[160:161], v[160:161], 0.5 op_sel_hi:[1,0]
	v_pk_mul_f32 v[162:163], v[162:163], 0.5 op_sel_hi:[1,0]
	v_pk_add_f32 v[212:213], v[212:213], 1.0 op_sel_hi:[1,0]
	v_pk_add_f32 v[214:215], v[214:215], 1.0 op_sel_hi:[1,0]
	v_pk_mul_f32 v[164:165], v[164:165], v[212:213]
	v_pk_mul_f32 v[166:167], v[166:167], v[214:215]
	v_pk_add_f32 v[216:217], v[216:217], 1.0 op_sel_hi:[1,0]
	v_pk_add_f32 v[218:219], v[218:219], 1.0 op_sel_hi:[1,0]
	v_pk_mul_f32 v[168:169], v[168:169], v[216:217]
	v_pk_mul_f32 v[170:171], v[170:171], v[218:219]
	v_pk_add_f32 v[220:221], v[220:221], 1.0 op_sel_hi:[1,0]
	v_pk_add_f32 v[222:223], v[222:223], 1.0 op_sel_hi:[1,0]
	v_pk_mul_f32 v[172:173], v[172:173], v[220:221]
	v_pk_mul_f32 v[174:175], v[174:175], v[222:223]
	v_pk_add_f32 v[232:233], v[232:233], 1.0 op_sel_hi:[1,0]
	v_pk_add_f32 v[234:235], v[234:235], 1.0 op_sel_hi:[1,0]
	v_pk_mul_f32 v[176:177], v[176:177], v[232:233]
	v_pk_mul_f32 v[178:179], v[178:179], v[234:235]
	s_add_u32 s14, s8, 0x20000
	s_addc_u32 s15, s9, 0
	global_load_dwordx4 v[212:215], v224, s[14:15] offset:0
	global_load_dwordx4 v[216:219], v224, s[14:15] offset:16
	global_load_dwordx4 v[220:223], v224, s[14:15] offset:512
	global_load_dwordx4 v[232:235], v224, s[14:15] offset:528
	s_waitcnt vmcnt(8)
	v_pk_fma_f32 v[126:127], v[126:127], v[148:149], v[180:181]
	v_pk_fma_f32 v[128:129], v[128:129], v[150:151], v[182:183]
	v_pk_fma_f32 v[122:123], v[122:123], v[152:153], v[184:185]
	v_pk_fma_f32 v[124:125], v[124:125], v[154:155], v[186:187]
	v_pk_fma_f32 v[62:63], v[62:63], v[156:157], v[188:189]
	v_pk_fma_f32 v[64:65], v[64:65], v[158:159], v[190:191]
	v_pk_fma_f32 v[58:59], v[58:59], v[160:161], v[192:193]
	v_pk_fma_f32 v[60:61], v[60:61], v[162:163], v[194:195]
	global_store_dwordx4 v224, v[126:129], s[10:11] offset:0
	global_store_dwordx4 v224, v[122:125], s[10:11] offset:16
	global_store_dwordx4 v224, v[62:65], s[10:11] offset:512
	global_store_dwordx4 v224, v[58:61], s[10:11] offset:528
	v_fmac_f32_e32 v241, v126, v126
	v_fmac_f32_e32 v241, v127, v127
	v_fmac_f32_e32 v241, v128, v128
	v_fmac_f32_e32 v241, v129, v129
	v_pk_mul_f32 v[180:181], v[126:127], v[164:165]
	v_pk_mul_f32 v[182:183], v[128:129], v[166:167]
	v_fmac_f32_e32 v241, v122, v122
	v_fmac_f32_e32 v241, v123, v123
	v_fmac_f32_e32 v241, v124, v124
	v_fmac_f32_e32 v241, v125, v125
	v_pk_mul_f32 v[184:185], v[122:123], v[168:169]
	v_pk_mul_f32 v[186:187], v[124:125], v[170:171]
	v_cvt_pk_bf16_f32 v180, v180, v181
	v_cvt_pk_bf16_f32 v181, v182, v183
	v_cvt_pk_bf16_f32 v182, v184, v185
	v_cvt_pk_bf16_f32 v183, v186, v187
	global_store_dwordx4 v240, v[180:183], s[60:61] offset:0
	v_fmac_f32_e32 v241, v62, v62
	v_fmac_f32_e32 v241, v63, v63
	v_fmac_f32_e32 v241, v64, v64
	v_fmac_f32_e32 v241, v65, v65
	v_pk_mul_f32 v[188:189], v[62:63], v[172:173]
	v_pk_mul_f32 v[190:191], v[64:65], v[174:175]
	v_fmac_f32_e32 v241, v58, v58
	v_fmac_f32_e32 v241, v59, v59
	v_fmac_f32_e32 v241, v60, v60
	v_fmac_f32_e32 v241, v61, v61
	v_pk_mul_f32 v[192:193], v[58:59], v[176:177]
	v_pk_mul_f32 v[194:195], v[60:61], v[178:179]
	v_cvt_pk_bf16_f32 v188, v188, v189
	v_cvt_pk_bf16_f32 v189, v190, v191
	v_cvt_pk_bf16_f32 v190, v192, v193
	v_cvt_pk_bf16_f32 v191, v194, v195
	global_store_dwordx4 v240, v[188:191], s[60:61] offset:256
	s_nop 0
	s_add_u32 s14, s8, 0x30000
	s_addc_u32 s15, s9, 0
	global_load_dwordx4 v[180:183], v224, s[14:15] offset:0
	global_load_dwordx4 v[184:187], v224, s[14:15] offset:16
	global_load_dwordx4 v[188:191], v224, s[14:15] offset:512
	global_load_dwordx4 v[192:195], v224, s[14:15] offset:528
	s_waitcnt vmcnt(14)
; DEV u32x4 pack8v(const f32x4 a, const f32x4 b) { u32x4 w; w.x = cvt_pk_bf16(a[0], a[1]); w.y = cvt_pk_bf16(a[2], a[3]); w.z = cvt_pk_bf16(b[0], b[1]); w.w = cvt_pk_bf16(b[2], b[3]); return w; }
;     DEV void operator()(const f32x4 (&acc)[2][2][4][2], const Unit& u, int wr, int wc, int fr, int fq) const {
;     ...
;             for (int ai = 0; ai < 2; ++ai)
; #pragma unroll
;                 for (int m = 0; m < 4; ++m) {
;                     const size_t p = (size_t)(row0 + ai * 128 + m * 16) * D + col0 + bj * 128;
;                     const f32x4 r0 = *(const f32x4*)(res + p), r1 = *(const f32x4*)(res + p + NS);
;                     const f32x4 o0 = r0 + gv[0] * acc[ai][bj][m][0], o1 = r1 + gv[1] * acc[ai][bj][m][1];
;                     *(f32x4*)(out + p) = o0; *(f32x4*)(out + p + NS) = o1;
;                     if (has_xn) { ss[ai * 4 + m] += (o0[0] * o0[0] + o0[1] * o0[1]) + (o0[2] * o0[2] + o0[3] * o0[3]) + (o1[0] * o1[0] + o1[1] * o1[1]) + (o1[2] * o1[2] + o1[3] * o1[3]);
;                         *(u32x4*)(xn + (size_t)(grow0 + ai * 128 + m * 16) * D + col0 + bj * 128) = pack8v(o0 * gs[0], o1 * gs[1]); }
	v_pk_fma_f32 v[82:83], v[82:83], v[148:149], v[196:197]
	v_pk_fma_f32 v[84:85], v[84:85], v[150:151], v[198:199]
	v_pk_fma_f32 v[74:75], v[74:75], v[152:153], v[200:201]
	v_pk_fma_f32 v[76:77], v[76:77], v[154:155], v[202:203]
	v_pk_fma_f32 v[54:55], v[54:55], v[156:157], v[204:205]
	v_pk_fma_f32 v[56:57], v[56:57], v[158:159], v[206:207]
	v_pk_fma_f32 v[50:51], v[50:51], v[160:161], v[208:209]
	v_pk_fma_f32 v[52:53], v[52:53], v[162:163], v[210:211]
	s_add_u32 s14, s10, 0x10000
	s_addc_u32 s15, s11, 0
	global_store_dwordx4 v224, v[82:85], s[14:15] offset:0
	global_store_dwordx4 v224, v[74:77], s[14:15] offset:16
	global_store_dwordx4 v224, v[54:57], s[14:15] offset:512
	global_store_dwordx4 v224, v[50:53], s[14:15] offset:528
	s_add_u32 s20, s60, 0x8000
	s_addc_u32 s21, s61, 0
	v_fmac_f32_e32 v243, v82, v82
	v_fmac_f32_e32 v243, v83, v83
	v_fmac_f32_e32 v243, v84, v84
	v_fmac_f32_e32 v243, v85, v85
	v_pk_mul_f32 v[196:197], v[82:83], v[164:165]
	v_pk_mul_f32 v[198:199], v[84:85], v[166:167]
	v_fmac_f32_e32 v243, v74, v74
	v_fmac_f32_e32 v243, v75, v75
	v_fmac_f32_e32 v243, v76, v76
	v_fmac_f32_e32 v243, v77, v77
	v_pk_mul_f32 v[200:201], v[74:75], v[168:169]
	v_pk_mul_f32 v[202:203], v[76:77], v[170:171]
	v_cvt_pk_bf16_f32 v196, v196, v197
	v_cvt_pk_bf16_f32 v197, v198, v199
	v_cvt_pk_bf16_f32 v198, v200, v201
	v_cvt_pk_bf16_f32 v199, v202, v203
	global_store_dwordx4 v240, v[196:199], s[20:21] offset:0
	v_fmac_f32_e32 v243, v54, v54
	v_fmac_f32_e32 v243, v55, v55
	v_fmac_f32_e32 v243, v56, v56
	v_fmac_f32_e32 v243, v57, v57
	v_pk_mul_f32 v[204:205], v[54:55], v[172:173]
	v_pk_mul_f32 v[206:207], v[56:57], v[174:175]
	v_fmac_f32_e32 v243, v50, v50
	v_fmac_f32_e32 v243, v51, v51
	v_fmac_f32_e32 v243, v52, v52
	v_fmac_f32_e32 v243, v53, v53
	v_pk_mul_f32 v[208:209], v[50:51], v[176:177]
	v_pk_mul_f32 v[210:211], v[52:53], v[178:179]
	v_cvt_pk_bf16_f32 v204, v204, v205
	v_cvt_pk_bf16_f32 v205, v206, v207
	v_cvt_pk_bf16_f32 v206, v208, v209
	v_cvt_pk_bf16_f32 v207, v210, v211
	global_store_dwordx4 v240, v[204:207], s[20:21] offset:256
	s_nop 0
	s_add_u32 s14, s8, 0x80000
	s_addc_u32 s15, s9, 0
	global_load_dwordx4 v[196:199], v224, s[14:15] offset:0
	global_load_dwordx4 v[200:203], v224, s[14:15] offset:16
	global_load_dwordx4 v[204:207], v224, s[14:15] offset:512
	global_load_dwordx4 v[208:211], v224, s[14:15] offset:528
	s_waitcnt vmcnt(20)
	v_pk_fma_f32 v[94:95], v[94:95], v[148:149], v[212:213]
	v_pk_fma_f32 v[96:97], v[96:97], v[150:151], v[214:215]
	v_pk_fma_f32 v[90:91], v[90:91], v[152:153], v[216:217]
	v_pk_fma_f32 v[92:93], v[92:93], v[154:155], v[218:219]
	v_pk_fma_f32 v[46:47], v[46:47], v[156:157], v[220:221]
	v_pk_fma_f32 v[48:49], v[48:49], v[158:159], v[222:223]
	v_pk_fma_f32 v[42:43], v[42:43], v[160:161], v[232:233]
	v_pk_fma_f32 v[44:45], v[44:45], v[162:163], v[234:235]
	s_add_u32 s14, s10, 0x20000
	s_addc_u32 s15, s11, 0
	global_store_dwordx4 v224, v[94:97], s[14:15] offset:0
	global_store_dwordx4 v224, v[90:93], s[14:15] offset:16
	global_store_dwordx4 v224, v[46:49], s[14:15] offset:512
	global_store_dwordx4 v224, v[42:45], s[14:15] offset:528
	s_add_u32 s20, s60, 0x10000
	s_addc_u32 s21, s61, 0
	v_fmac_f32_e32 v252, v94, v94
	v_fmac_f32_e32 v252, v95, v95
	v_fmac_f32_e32 v252, v96, v96
	v_fmac_f32_e32 v252, v97, v97
	v_pk_mul_f32 v[212:213], v[94:95], v[164:165]
	v_pk_mul_f32 v[214:215], v[96:97], v[166:167]
	v_fmac_f32_e32 v252, v90, v90
	v_fmac_f32_e32 v252, v91, v91
	v_fmac_f32_e32 v252, v92, v92
	v_fmac_f32_e32 v252, v93, v93
	v_pk_mul_f32 v[216:217], v[90:91], v[168:169]
	v_pk_mul_f32 v[218:219], v[92:93], v[170:171]
	v_cvt_pk_bf16_f32 v212, v212, v213
	v_cvt_pk_bf16_f32 v213, v214, v215
	v_cvt_pk_bf16_f32 v214, v216, v217
	v_cvt_pk_bf16_f32 v215, v218, v219
	global_store_dwordx4 v240, v[212:215], s[20:21] offset:0
	v_fmac_f32_e32 v252, v46, v46
	v_fmac_f32_e32 v252, v47, v47
	v_fmac_f32_e32 v252, v48, v48
	v_fmac_f32_e32 v252, v49, v49
	v_pk_mul_f32 v[220:221], v[46:47], v[172:173]
	v_pk_mul_f32 v[222:223], v[48:49], v[174:175]
	v_fmac_f32_e32 v252, v42, v42
	v_fmac_f32_e32 v252, v43, v43
	v_fmac_f32_e32 v252, v44, v44
	v_fmac_f32_e32 v252, v45, v45
	v_pk_mul_f32 v[232:233], v[42:43], v[176:177]
	v_pk_mul_f32 v[234:235], v[44:45], v[178:179]
	v_cvt_pk_bf16_f32 v220, v220, v221
	v_cvt_pk_bf16_f32 v221, v222, v223
	v_cvt_pk_bf16_f32 v222, v232, v233
	v_cvt_pk_bf16_f32 v223, v234, v235
	global_store_dwordx4 v240, v[220:223], s[20:21] offset:256
	s_nop 0
	s_add_u32 s14, s8, 0x90000
	s_addc_u32 s15, s9, 0
	global_load_dwordx4 v[212:215], v224, s[14:15] offset:0
	global_load_dwordx4 v[216:219], v224, s[14:15] offset:16
	global_load_dwordx4 v[220:223], v224, s[14:15] offset:512
	global_load_dwordx4 v[232:235], v224, s[14:15] offset:528
	s_waitcnt vmcnt(20)
; DEV u32x4 pack8v(const f32x4 a, const f32x4 b) { u32x4 w; w.x = cvt_pk_bf16(a[0], a[1]); w.y = cvt_pk_bf16(a[2], a[3]); w.z = cvt_pk_bf16(b[0], b[1]); w.w = cvt_pk_bf16(b[2], b[3]); return w; }
;     DEV void operator()(const f32x4 (&acc)[2][2][4][2], const Unit& u, int wr, int wc, int fr, int fq) const {
;     ...
;         for (int bj = 0; bj < 2; ++bj) {
;             f32x4 gv[2], gs[2];
; #pragma unroll
;             for (int n = 0; n < 2; ++n) { gv[n] = *(const f32x4*)(mod + (size_t)b * NMOD + gate_i * D + col0 + bj * 128 + NS * n) * coef;
;                 if (has_xn) gs[n] = *(const f32x4*)(g + col0 + bj * 128 + 4 * n) * (*(const f32x4*)(mod + (size_t)b * NMOD + scale_i * D + col0 + bj * 128 + 4 * n) + 1.f); }
; #pragma unroll
;             for (int ai = 0; ai < 2; ++ai)
; #pragma unroll
;                 for (int m = 0; m < 4; ++m) {
;                     const size_t p = (size_t)(row0 + ai * 128 + m * 16) * D + col0 + bj * 128;
;                     const f32x4 r0 = *(const f32x4*)(res + p), r1 = *(const f32x4*)(res + p + NS);
;                     const f32x4 o0 = r0 + gv[0] * acc[ai][bj][m][0], o1 = r1 + gv[1] * acc[ai][bj][m][1];
;                     *(f32x4*)(out + p) = o0; *(f32x4*)(out + p + NS) = o1;
;                     if (has_xn) { ss[ai * 4 + m] += (o0[0] * o0[0] + o0[1] * o0[1]) + (o0[2] * o0[2] + o0[3] * o0[3]) + (o1[0] * o1[0] + o1[1] * o1[1]) + (o1[2] * o1[2] + o1[3] * o1[3]);
;                         *(u32x4*)(xn + (size_t)(grow0 + ai * 128 + m * 16) * D + col0 + bj * 128) = pack8v(o0 * gs[0], o1 * gs[1]); }
	v_pk_fma_f32 v[110:111], v[110:111], v[148:149], v[180:181]
	v_pk_fma_f32 v[112:113], v[112:113], v[150:151], v[182:183]
	v_pk_fma_f32 v[106:107], v[106:107], v[152:153], v[184:185]
	v_pk_fma_f32 v[108:109], v[108:109], v[154:155], v[186:187]
	v_pk_fma_f32 v[38:39], v[38:39], v[156:157], v[188:189]
	v_pk_fma_f32 v[40:41], v[40:41], v[158:159], v[190:191]
	v_pk_fma_f32 v[34:35], v[34:35], v[160:161], v[192:193]
	v_pk_fma_f32 v[36:37], v[36:37], v[162:163], v[194:195]
	s_add_u32 s14, s10, 0x30000
	s_addc_u32 s15, s11, 0
	global_store_dwordx4 v224, v[110:113], s[14:15] offset:0
	global_store_dwordx4 v224, v[106:109], s[14:15] offset:16
	global_store_dwordx4 v224, v[38:41], s[14:15] offset:512
	global_store_dwordx4 v224, v[34:37], s[14:15] offset:528
	s_add_u32 s20, s60, 0x18000
	s_addc_u32 s21, s61, 0
	v_fmac_f32_e32 v253, v110, v110
	v_fmac_f32_e32 v253, v111, v111
	v_fmac_f32_e32 v253, v112, v112
	v_fmac_f32_e32 v253, v113, v113
	v_pk_mul_f32 v[180:181], v[110:111], v[164:165]
	v_pk_mul_f32 v[182:183], v[112:113], v[166:167]
	v_fmac_f32_e32 v253, v106, v106
	v_fmac_f32_e32 v253, v107, v107
	v_fmac_f32_e32 v253, v108, v108
	v_fmac_f32_e32 v253, v109, v109
	v_pk_mul_f32 v[184:185], v[106:107], v[168:169]
	v_pk_mul_f32 v[186:187], v[108:109], v[170:171]
	v_cvt_pk_bf16_f32 v180, v180, v181
	v_cvt_pk_bf16_f32 v181, v182, v183
	v_cvt_pk_bf16_f32 v182, v184, v185
	v_cvt_pk_bf16_f32 v183, v186, v187
	global_store_dwordx4 v240, v[180:183], s[20:21] offset:0
	v_fmac_f32_e32 v253, v38, v38
	v_fmac_f32_e32 v253, v39, v39
	v_fmac_f32_e32 v253, v40, v40
	v_fmac_f32_e32 v253, v41, v41
	v_pk_mul_f32 v[188:189], v[38:39], v[172:173]
	v_pk_mul_f32 v[190:191], v[40:41], v[174:175]
	v_fmac_f32_e32 v253, v34, v34
	v_fmac_f32_e32 v253, v35, v35
	v_fmac_f32_e32 v253, v36, v36
	v_fmac_f32_e32 v253, v37, v37
	v_pk_mul_f32 v[192:193], v[34:35], v[176:177]
	v_pk_mul_f32 v[194:195], v[36:37], v[178:179]
	v_cvt_pk_bf16_f32 v188, v188, v189
	v_cvt_pk_bf16_f32 v189, v190, v191
	v_cvt_pk_bf16_f32 v190, v192, v193
	v_cvt_pk_bf16_f32 v191, v194, v195
	global_store_dwordx4 v240, v[188:191], s[20:21] offset:256
	s_nop 0
	s_add_u32 s14, s8, 0xa0000
	s_addc_u32 s15, s9, 0
	global_load_dwordx4 v[180:183], v224, s[14:15] offset:0
	global_load_dwordx4 v[184:187], v224, s[14:15] offset:16
	global_load_dwordx4 v[188:191], v224, s[14:15] offset:512
	global_load_dwordx4 v[192:195], v224, s[14:15] offset:528
	s_waitcnt vmcnt(20)
	v_pk_fma_f32 v[118:119], v[118:119], v[148:149], v[196:197]
	v_pk_fma_f32 v[120:121], v[120:121], v[150:151], v[198:199]
	v_pk_fma_f32 v[114:115], v[114:115], v[152:153], v[200:201]
	v_pk_fma_f32 v[116:117], v[116:117], v[154:155], v[202:203]
	v_pk_fma_f32 v[30:31], v[30:31], v[156:157], v[204:205]
	v_pk_fma_f32 v[32:33], v[32:33], v[158:159], v[206:207]
	v_pk_fma_f32 v[26:27], v[26:27], v[160:161], v[208:209]
	v_pk_fma_f32 v[28:29], v[28:29], v[162:163], v[210:211]
	s_add_u32 s14, s10, 0x80000
	s_addc_u32 s15, s11, 0
	global_store_dwordx4 v224, v[118:121], s[14:15] offset:0
	global_store_dwordx4 v224, v[114:117], s[14:15] offset:16
	global_store_dwordx4 v224, v[30:33], s[14:15] offset:512
	global_store_dwordx4 v224, v[26:29], s[14:15] offset:528
	s_add_u32 s20, s60, 0x40000
	s_addc_u32 s21, s61, 0
	v_fmac_f32_e32 v254, v118, v118
	v_fmac_f32_e32 v254, v119, v119
	v_fmac_f32_e32 v254, v120, v120
	v_fmac_f32_e32 v254, v121, v121
	v_pk_mul_f32 v[196:197], v[118:119], v[164:165]
	v_pk_mul_f32 v[198:199], v[120:121], v[166:167]
	v_fmac_f32_e32 v254, v114, v114
	v_fmac_f32_e32 v254, v115, v115
	v_fmac_f32_e32 v254, v116, v116
	v_fmac_f32_e32 v254, v117, v117
	v_pk_mul_f32 v[200:201], v[114:115], v[168:169]
	v_pk_mul_f32 v[202:203], v[116:117], v[170:171]
	v_cvt_pk_bf16_f32 v196, v196, v197
	v_cvt_pk_bf16_f32 v197, v198, v199
	v_cvt_pk_bf16_f32 v198, v200, v201
	v_cvt_pk_bf16_f32 v199, v202, v203
	global_store_dwordx4 v240, v[196:199], s[20:21] offset:0
	v_fmac_f32_e32 v254, v30, v30
	v_fmac_f32_e32 v254, v31, v31
	v_fmac_f32_e32 v254, v32, v32
	v_fmac_f32_e32 v254, v33, v33
	v_pk_mul_f32 v[204:205], v[30:31], v[172:173]
	v_pk_mul_f32 v[206:207], v[32:33], v[174:175]
	v_fmac_f32_e32 v254, v26, v26
	v_fmac_f32_e32 v254, v27, v27
	v_fmac_f32_e32 v254, v28, v28
	v_fmac_f32_e32 v254, v29, v29
	v_pk_mul_f32 v[208:209], v[26:27], v[176:177]
	v_pk_mul_f32 v[210:211], v[28:29], v[178:179]
	v_cvt_pk_bf16_f32 v204, v204, v205
	v_cvt_pk_bf16_f32 v205, v206, v207
	v_cvt_pk_bf16_f32 v206, v208, v209
	v_cvt_pk_bf16_f32 v207, v210, v211
	global_store_dwordx4 v240, v[204:207], s[20:21] offset:256
	s_nop 0
	s_add_u32 s14, s8, 0xb0000
	s_addc_u32 s15, s9, 0
	global_load_dwordx4 v[196:199], v224, s[14:15] offset:0
	global_load_dwordx4 v[200:203], v224, s[14:15] offset:16
	global_load_dwordx4 v[204:207], v224, s[14:15] offset:512
	global_load_dwordx4 v[208:211], v224, s[14:15] offset:528
	s_waitcnt vmcnt(20)
; DEV u32x4 pack8v(const f32x4 a, const f32x4 b) { u32x4 w; w.x = cvt_pk_bf16(a[0], a[1]); w.y = cvt_pk_bf16(a[2], a[3]); w.z = cvt_pk_bf16(b[0], b[1]); w.w = cvt_pk_bf16(b[2], b[3]); return w; }
;     DEV void operator()(const f32x4 (&acc)[2][2][4][2], const Unit& u, int wr, int wc, int fr, int fq) const {
;     ...
;         for (int bj = 0; bj < 2; ++bj) {
;             f32x4 gv[2], gs[2];
; #pragma unroll
;             for (int n = 0; n < 2; ++n) { gv[n] = *(const f32x4*)(mod + (size_t)b * NMOD + gate_i * D + col0 + bj * 128 + NS * n) * coef;
;                 if (has_xn) gs[n] = *(const f32x4*)(g + col0 + bj * 128 + 4 * n) * (*(const f32x4*)(mod + (size_t)b * NMOD + scale_i * D + col0 + bj * 128 + 4 * n) + 1.f); }
; #pragma unroll
;             for (int ai = 0; ai < 2; ++ai)
; #pragma unroll
;                 for (int m = 0; m < 4; ++m) {
;                     const size_t p = (size_t)(row0 + ai * 128 + m * 16) * D + col0 + bj * 128;
;                     const f32x4 r0 = *(const f32x4*)(res + p), r1 = *(const f32x4*)(res + p + NS);
;                     const f32x4 o0 = r0 + gv[0] * acc[ai][bj][m][0], o1 = r1 + gv[1] * acc[ai][bj][m][1];
;                     *(f32x4*)(out + p) = o0; *(f32x4*)(out + p + NS) = o1;
;                     if (has_xn) { ss[ai * 4 + m] += (o0[0] * o0[0] + o0[1] * o0[1]) + (o0[2] * o0[2] + o0[3] * o0[3]) + (o1[0] * o1[0] + o1[1] * o1[1]) + (o1[2] * o1[2] + o1[3] * o1[3]);
;                         *(u32x4*)(xn + (size_t)(grow0 + ai * 128 + m * 16) * D + col0 + bj * 128) = pack8v(o0 * gs[0], o1 * gs[1]); }
	v_pk_fma_f32 v[102:103], v[102:103], v[148:149], v[212:213]
	v_pk_fma_f32 v[104:105], v[104:105], v[150:151], v[214:215]
	v_pk_fma_f32 v[98:99], v[98:99], v[152:153], v[216:217]
	v_pk_fma_f32 v[100:101], v[100:101], v[154:155], v[218:219]
	v_pk_fma_f32 v[22:23], v[22:23], v[156:157], v[220:221]
	v_pk_fma_f32 v[24:25], v[24:25], v[158:159], v[222:223]
	v_pk_fma_f32 v[18:19], v[18:19], v[160:161], v[232:233]
	v_pk_fma_f32 v[20:21], v[20:21], v[162:163], v[234:235]
	s_add_u32 s14, s10, 0x90000
	s_addc_u32 s15, s11, 0
	global_store_dwordx4 v224, v[102:105], s[14:15] offset:0
	global_store_dwordx4 v224, v[98:101], s[14:15] offset:16
	global_store_dwordx4 v224, v[22:25], s[14:15] offset:512
	global_store_dwordx4 v224, v[18:21], s[14:15] offset:528
	s_add_u32 s20, s60, 0x48000
	s_addc_u32 s21, s61, 0
	v_fmac_f32_e32 v255, v102, v102
	v_fmac_f32_e32 v255, v103, v103
	v_fmac_f32_e32 v255, v104, v104
	v_fmac_f32_e32 v255, v105, v105
	v_pk_mul_f32 v[212:213], v[102:103], v[164:165]
	v_pk_mul_f32 v[214:215], v[104:105], v[166:167]
	v_fmac_f32_e32 v255, v98, v98
	v_fmac_f32_e32 v255, v99, v99
	v_fmac_f32_e32 v255, v100, v100
	v_fmac_f32_e32 v255, v101, v101
	v_pk_mul_f32 v[216:217], v[98:99], v[168:169]
	v_pk_mul_f32 v[218:219], v[100:101], v[170:171]
	v_cvt_pk_bf16_f32 v212, v212, v213
	v_cvt_pk_bf16_f32 v213, v214, v215
	v_cvt_pk_bf16_f32 v214, v216, v217
	v_cvt_pk_bf16_f32 v215, v218, v219
	global_store_dwordx4 v240, v[212:215], s[20:21] offset:0
	v_fmac_f32_e32 v255, v22, v22
	v_fmac_f32_e32 v255, v23, v23
	v_fmac_f32_e32 v255, v24, v24
	v_fmac_f32_e32 v255, v25, v25
	v_pk_mul_f32 v[220:221], v[22:23], v[172:173]
	v_pk_mul_f32 v[222:223], v[24:25], v[174:175]
	v_fmac_f32_e32 v255, v18, v18
	v_fmac_f32_e32 v255, v19, v19
	v_fmac_f32_e32 v255, v20, v20
	v_fmac_f32_e32 v255, v21, v21
	v_pk_mul_f32 v[232:233], v[18:19], v[176:177]
	v_pk_mul_f32 v[234:235], v[20:21], v[178:179]
	v_cvt_pk_bf16_f32 v220, v220, v221
	v_cvt_pk_bf16_f32 v221, v222, v223
	v_cvt_pk_bf16_f32 v222, v232, v233
	v_cvt_pk_bf16_f32 v223, v234, v235
	global_store_dwordx4 v240, v[220:223], s[20:21] offset:256
	s_nop 0
	s_waitcnt vmcnt(16)
	v_pk_fma_f32 v[86:87], v[86:87], v[148:149], v[180:181]
	v_pk_fma_f32 v[88:89], v[88:89], v[150:151], v[182:183]
	v_pk_fma_f32 v[78:79], v[78:79], v[152:153], v[184:185]
	v_pk_fma_f32 v[80:81], v[80:81], v[154:155], v[186:187]
	v_pk_fma_f32 v[14:15], v[14:15], v[156:157], v[188:189]
	v_pk_fma_f32 v[16:17], v[16:17], v[158:159], v[190:191]
	v_pk_fma_f32 v[10:11], v[10:11], v[160:161], v[192:193]
	v_pk_fma_f32 v[12:13], v[12:13], v[162:163], v[194:195]
	s_add_u32 s14, s10, 0xa0000
	s_addc_u32 s15, s11, 0
	global_store_dwordx4 v224, v[86:89], s[14:15] offset:0
	global_store_dwordx4 v224, v[78:81], s[14:15] offset:16
	global_store_dwordx4 v224, v[14:17], s[14:15] offset:512
	global_store_dwordx4 v224, v[10:13], s[14:15] offset:528
	s_add_u32 s20, s60, 0x50000
	s_addc_u32 s21, s61, 0
	v_fmac_f32_e32 v248, v86, v86
	v_fmac_f32_e32 v248, v87, v87
	v_fmac_f32_e32 v248, v88, v88
	v_fmac_f32_e32 v248, v89, v89
	v_pk_mul_f32 v[180:181], v[86:87], v[164:165]
	v_pk_mul_f32 v[182:183], v[88:89], v[166:167]
	v_fmac_f32_e32 v248, v78, v78
	v_fmac_f32_e32 v248, v79, v79
	v_fmac_f32_e32 v248, v80, v80
	v_fmac_f32_e32 v248, v81, v81
	v_pk_mul_f32 v[184:185], v[78:79], v[168:169]
	v_pk_mul_f32 v[186:187], v[80:81], v[170:171]
	v_cvt_pk_bf16_f32 v180, v180, v181
	v_cvt_pk_bf16_f32 v181, v182, v183
	v_cvt_pk_bf16_f32 v182, v184, v185
	v_cvt_pk_bf16_f32 v183, v186, v187
	global_store_dwordx4 v240, v[180:183], s[20:21] offset:0
	v_fmac_f32_e32 v248, v14, v14
	v_fmac_f32_e32 v248, v15, v15
	v_fmac_f32_e32 v248, v16, v16
	v_fmac_f32_e32 v248, v17, v17
	v_pk_mul_f32 v[188:189], v[14:15], v[172:173]
	v_pk_mul_f32 v[190:191], v[16:17], v[174:175]
	v_fmac_f32_e32 v248, v10, v10
	v_fmac_f32_e32 v248, v11, v11
	v_fmac_f32_e32 v248, v12, v12
	v_fmac_f32_e32 v248, v13, v13
	v_pk_mul_f32 v[192:193], v[10:11], v[176:177]
	v_pk_mul_f32 v[194:195], v[12:13], v[178:179]
	v_cvt_pk_bf16_f32 v188, v188, v189
	v_cvt_pk_bf16_f32 v189, v190, v191
	v_cvt_pk_bf16_f32 v190, v192, v193
	v_cvt_pk_bf16_f32 v191, v194, v195
	global_store_dwordx4 v240, v[188:191], s[20:21] offset:256
	s_nop 0
	s_waitcnt vmcnt(12)
; DEV u32x4 pack8v(const f32x4 a, const f32x4 b) { u32x4 w; w.x = cvt_pk_bf16(a[0], a[1]); w.y = cvt_pk_bf16(a[2], a[3]); w.z = cvt_pk_bf16(b[0], b[1]); w.w = cvt_pk_bf16(b[2], b[3]); return w; }
;     DEV void operator()(const f32x4 (&acc)[2][2][4][2], const Unit& u, int wr, int wc, int fr, int fq) const {
;     ...
;                     const f32x4 r0 = *(const f32x4*)(res + p), r1 = *(const f32x4*)(res + p + NS);
;                     const f32x4 o0 = r0 + gv[0] * acc[ai][bj][m][0], o1 = r1 + gv[1] * acc[ai][bj][m][1];
;                     *(f32x4*)(out + p) = o0; *(f32x4*)(out + p + NS) = o1;
;                     if (has_xn) { ss[ai * 4 + m] += (o0[0] * o0[0] + o0[1] * o0[1]) + (o0[2] * o0[2] + o0[3] * o0[3]) + (o1[0] * o1[0] + o1[1] * o1[1]) + (o1[2] * o1[2] + o1[3] * o1[3]);
;                         *(u32x4*)(xn + (size_t)(grow0 + ai * 128 + m * 16) * D + col0 + bj * 128) = pack8v(o0 * gs[0], o1 * gs[1]); }
;     ...
;         if (has_xn) {
; #pragma unroll
;             for (int i = 0; i < 8; ++i) { float v = ss[i]; v += __shfl_xor(v, 16); v += __shfl_xor(v, 32); if (fq == 0) rs[(size_t)(grow0 + (i >> 2) * 128 + (i & 3) * 16) * 16 + u.pn * 4 + wc] = v; }
;         }
	v_pk_fma_f32 v[70:71], v[70:71], v[148:149], v[196:197]
	v_pk_fma_f32 v[72:73], v[72:73], v[150:151], v[198:199]
	v_pk_fma_f32 v[66:67], v[66:67], v[152:153], v[200:201]
	v_pk_fma_f32 v[68:69], v[68:69], v[154:155], v[202:203]
	v_pk_fma_f32 v[6:7], v[6:7], v[156:157], v[204:205]
	v_pk_fma_f32 v[8:9], v[8:9], v[158:159], v[206:207]
	v_pk_fma_f32 v[2:3], v[2:3], v[160:161], v[208:209]
	v_pk_fma_f32 v[4:5], v[4:5], v[162:163], v[210:211]
	s_add_u32 s14, s10, 0xb0000
	s_addc_u32 s15, s11, 0
	global_store_dwordx4 v224, v[70:73], s[14:15] offset:0
	global_store_dwordx4 v224, v[66:69], s[14:15] offset:16
	global_store_dwordx4 v224, v[6:9], s[14:15] offset:512
	global_store_dwordx4 v224, v[2:5], s[14:15] offset:528
	s_add_u32 s20, s60, 0x58000
	s_addc_u32 s21, s61, 0
	v_fmac_f32_e32 v249, v70, v70
	v_fmac_f32_e32 v249, v71, v71
	v_fmac_f32_e32 v249, v72, v72
	v_fmac_f32_e32 v249, v73, v73
	v_pk_mul_f32 v[196:197], v[70:71], v[164:165]
	v_pk_mul_f32 v[198:199], v[72:73], v[166:167]
	v_fmac_f32_e32 v249, v66, v66
	v_fmac_f32_e32 v249, v67, v67
	v_fmac_f32_e32 v249, v68, v68
	v_fmac_f32_e32 v249, v69, v69
	v_pk_mul_f32 v[200:201], v[66:67], v[168:169]
	v_pk_mul_f32 v[202:203], v[68:69], v[170:171]
	v_cvt_pk_bf16_f32 v196, v196, v197
	v_cvt_pk_bf16_f32 v197, v198, v199
	v_cvt_pk_bf16_f32 v198, v200, v201
	v_cvt_pk_bf16_f32 v199, v202, v203
	global_store_dwordx4 v240, v[196:199], s[20:21] offset:0
	v_fmac_f32_e32 v249, v6, v6
	v_fmac_f32_e32 v249, v7, v7
	v_fmac_f32_e32 v249, v8, v8
	v_fmac_f32_e32 v249, v9, v9
	v_pk_mul_f32 v[204:205], v[6:7], v[172:173]
	v_pk_mul_f32 v[206:207], v[8:9], v[174:175]
	v_fmac_f32_e32 v249, v2, v2
	v_fmac_f32_e32 v249, v3, v3
	v_fmac_f32_e32 v249, v4, v4
	v_fmac_f32_e32 v249, v5, v5
	v_pk_mul_f32 v[208:209], v[2:3], v[176:177]
	v_pk_mul_f32 v[210:211], v[4:5], v[178:179]
	v_cvt_pk_bf16_f32 v204, v204, v205
	v_cvt_pk_bf16_f32 v205, v206, v207
	v_cvt_pk_bf16_f32 v206, v208, v209
	v_cvt_pk_bf16_f32 v207, v210, v211
	global_store_dwordx4 v240, v[204:207], s[20:21] offset:256
	s_nop 0
	s_nop 1
	v_xor_b32_e32 v180, 16, v231
	v_xor_b32_e32 v181, 32, v231
	v_lshlrev_b32_e32 v180, 2, v180
	v_lshlrev_b32_e32 v181, 2, v181
	ds_bpermute_b32 v196, v180, v241
	ds_bpermute_b32 v197, v180, v243
	ds_bpermute_b32 v198, v180, v252
	ds_bpermute_b32 v199, v180, v253
	ds_bpermute_b32 v200, v180, v254
	ds_bpermute_b32 v201, v180, v255
	ds_bpermute_b32 v202, v180, v248
	ds_bpermute_b32 v203, v180, v249
	s_waitcnt lgkmcnt(0)
	v_add_f32_e32 v241, v241, v196
	v_add_f32_e32 v243, v243, v197
	v_add_f32_e32 v252, v252, v198
	v_add_f32_e32 v253, v253, v199
	v_add_f32_e32 v254, v254, v200
	v_add_f32_e32 v255, v255, v201
	v_add_f32_e32 v248, v248, v202
	v_add_f32_e32 v249, v249, v203
	ds_bpermute_b32 v196, v181, v241
	ds_bpermute_b32 v197, v181, v243
	ds_bpermute_b32 v198, v181, v252
	ds_bpermute_b32 v199, v181, v253
	ds_bpermute_b32 v200, v181, v254
	ds_bpermute_b32 v201, v181, v255
	ds_bpermute_b32 v202, v181, v248
	ds_bpermute_b32 v203, v181, v249
	s_waitcnt lgkmcnt(0)
	v_add_f32_e32 v241, v241, v196
	v_add_f32_e32 v243, v243, v197
	v_add_f32_e32 v252, v252, v198
	v_add_f32_e32 v253, v253, v199
	v_add_f32_e32 v254, v254, v200
	v_add_f32_e32 v255, v255, v201
	v_add_f32_e32 v248, v248, v202
	v_add_f32_e32 v249, v249, v203
	v_add_u32_e32 v182, s38, v147
	v_lshlrev_b32_e32 v182, 6, v182
	s_lshl_b32 s41, s82, 4
	s_add_u32 s14, s76, s41
	s_addc_u32 s15, s77, 0
	s_add_u32 s20, s14, 0x2000
	s_addc_u32 s21, s15, 0
	v_cmp_eq_u32_e32 vcc, 0, v226
	s_nop 4
	s_and_saveexec_b64 s[22:23], vcc
	v_lshrrev_b32_e32 v182, 4, v182
	s_add_u32 s14, s88, 0x3c900000
	s_addc_u32 s15, s89, 0
	global_atomic_add_f32 v182, v241, s[14:15] offset:0
	global_atomic_add_f32 v182, v243, s[14:15] offset:64
	global_atomic_add_f32 v182, v252, s[14:15] offset:128
	global_atomic_add_f32 v182, v253, s[14:15] offset:192
	global_atomic_add_f32 v182, v254, s[14:15] offset:512
	global_atomic_add_f32 v182, v255, s[14:15] offset:576
	global_atomic_add_f32 v182, v248, s[14:15] offset:640
	global_atomic_add_f32 v182, v249, s[14:15] offset:704
	s_or_b64 exec, exec, s[22:23]
	s_and_b64 vcc, exec, s[4:5]
	s_mov_b64 s[4:5], -1
	s_cbranch_vccnz .LBB0_371
	s_andn2_b64 vcc, exec, s[62:63]
	s_cbranch_vccnz .LBB0_370
	s_barrier
	s_branch .LBB0_370

;     __host__ __device__ bool next(int i, Unit& u) const {
;         const long L = (long)i * G + c; if (L >= nwg) return false;
;         int wgid = (int)L; { const int q = nwg / NXCD, r = nwg % NXCD, xcd = wgid % NXCD, off = wgid / NXCD; wgid = (xcd < r ? xcd * (q + 1) : r * (q + 1) + (xcd - r) * q) + off; }
;         const int nig = WGM * nN, gid = wgid / nig, fm = gid * WGM, gsz = (nM - fm) < WGM ? (nM - fm) : WGM;
;         u.pm = fm + ((wgid % nig) % gsz); u.pn = (wgid % nig) / gsz; return true;
;     DEV void operator()(const f32x4 (&acc)[2][2][4][2], const Unit& u, int wr, int wc, int fr, int fq) const {
;     ...
;         if (FUSED) { const int b = u.pm >> 4; const float* sp = shw + (size_t)b * NFF2 + u.pn * 256 + wc * 32 + 8 * fq;
;             sg[0] = *(const f32x4*)sp; sg[1] = *(const f32x4*)(sp + 4); su[0] = *(const f32x4*)(sp + 128); su[1] = *(const f32x4*)(sp + 132); }
;     DEV void operator()(const f32x4 (&acc)[2][2][4][2], const Unit& u, int wr, int wc, int fr, int fq) const {
;     ...
;         float rstd8[8]; row_rstd8(rs, row0, fq, rstd8);
.LBB0_478:
	s_lshl_b32 s100, s6, 8
	s_add_u32 s100, s100, s73
	v_add_u32_e32 v252, s100, v147
	v_lshlrev_b32_e32 v252, 2, v252
	s_add_u32 s98, s88, 0x3c900000
	s_addc_u32 s99, s89, 0
	global_load_dword v243, v252, s[98:99] offset:0
	global_load_dword v244, v252, s[98:99] offset:64
	global_load_dword v245, v252, s[98:99] offset:128
	global_load_dword v246, v252, s[98:99] offset:192
	global_load_dword v247, v252, s[98:99] offset:512
	global_load_dword v248, v252, s[98:99] offset:576
	global_load_dword v249, v252, s[98:99] offset:640
	global_load_dword v250, v252, s[98:99] offset:704
	s_ashr_i32 s100, s6, 4
	s_min_i32 s100, s100, 16
	s_mul_i32 s100, s100, 0x2c00
	s_lshl_b32 s101, s10, 10
	s_add_u32 s100, s100, s101
	s_lshl_b32 s101, s74, 2
	s_add_u32 s100, s100, s101
	s_add_u32 s98, s88, 0x3d200000
	s_addc_u32 s99, s89, 0
	s_add_u32 s98, s98, s100
	s_addc_u32 s99, s99, 0
	v_and_b32_e32 v253, 31, v204
	v_lshrrev_b32_e32 v254, 5, v204
	v_lshl_add_u32 v253, v254, 7, v253
	v_lshlrev_b32_e32 v253, 2, v253
	global_load_dword v251, v253, s[98:99]
	s_add_i32 s93, s93, 1
	s_mul_i32 s4, s93, s77
	s_mul_hi_u32 s5, s93, s50
	s_add_i32 s5, s5, s4
	s_mul_i32 s4, s93, s50
	s_add_u32 s42, s4, s2
	s_addc_u32 s43, s5, s78
	v_cmp_gt_i64_e32 vcc, s[42:43], v[162:163]
	v_cmp_lt_i64_e64 s[4:5], s[42:43], v[160:161]
	s_cbranch_vccnz .LBB0_480
	s_ashr_i32 s7, s42, 31
	s_lshr_b32 s7, s7, 29
	s_add_i32 s7, s42, s7
	s_ashr_i32 s11, s7, 3
	s_and_b32 s7, s7, -8
	s_sub_i32 s7, s42, s7
	s_cmp_lt_i32 s7, 0
	s_cselect_b32 s12, s79, 0x176
	s_mul_i32 s7, s7, s12
	s_add_i32 s7, s7, s11
	s_mul_hi_i32 s11, s7, 0x2e8ba2e9
	s_lshr_b32 s12, s11, 31
	s_ashr_i32 s11, s11, 4
	s_add_i32 s11, s11, s12
	s_lshl_b32 s12, s11, 3
	s_sub_i32 s33, 0x110, s12
	s_min_i32 s33, s33, 8
	s_abs_i32 s38, s33
	v_cvt_f32_u32_e32 v2, s38
	s_sub_i32 s40, 0, s38
	s_mulk_i32 s11, 0x58
	s_sub_i32 s7, s7, s11
	v_rcp_iflag_f32_e32 v2, v2
	s_abs_i32 s11, s7
	s_xor_b32 s39, s7, s33
	s_ashr_i32 s39, s39, 31
	v_mul_f32_e32 v2, 0x4f7ffffe, v2
	v_cvt_u32_f32_e32 v2, v2
	s_nop 0
	v_readfirstlane_b32 s41, v2
	s_mul_i32 s40, s40, s41
	s_mul_hi_u32 s40, s41, s40
	s_add_i32 s41, s41, s40
	s_mul_hi_u32 s40, s11, s41
	s_mul_i32 s41, s40, s38
	s_sub_i32 s11, s11, s41
	s_add_i32 s42, s40, 1
	s_sub_i32 s41, s11, s38
	s_cmp_ge_u32 s11, s38
	s_cselect_b32 s40, s42, s40
	s_cselect_b32 s11, s41, s11
	s_add_i32 s41, s40, 1
	s_cmp_ge_u32 s11, s38
	s_cselect_b32 s11, s41, s40
	s_xor_b32 s11, s11, s39
	s_sub_i32 s38, s11, s39
	s_mul_i32 s11, s38, s33
	s_sub_i32 s7, s7, s11
	s_add_i32 s40, s12, s7

; DEV float silu_f(float x) { return x * __builtin_amdgcn_rcpf(1.f + __expf(-x)); }
; DEV float gelu_f(float x) { const float t = 1.5957691216f * (x + 0.044715f * x * x * x); return x * __builtin_amdgcn_rcpf(1.f + __expf(-t)); }
; DEV u32x4 pack8(const float (&f)[8]) { u32x4 w; w.x = cvt_pk_bf16(f[0], f[1]); w.y = cvt_pk_bf16(f[2], f[3]); w.z = cvt_pk_bf16(f[4], f[5]); w.w = cvt_pk_bf16(f[6], f[7]); return w; }
;     DEV void operator()(const f32x4 (&acc)[2][2][4][2], const Unit& u, int wr, int wc, int fr, int fq) const {
;         asm volatile("" : "+v"(fr), "+v"(fq));
;         const int pn = u.pn; const int act = (pn < 4 || pn >= 10) ? 0 : (pn < 6 ? 1 : 2); const bool stat = (pn == 8 || pn == 9);
;         const int row0 = u.pm * 256 + wr * 64 + fr, col0 = pn * 256 + wc * 32 + 8 * fq; const int b = u.pm < MLAT / 256 ? (u.pm >> 4) : 16;
;         f32x4 sw[2][2];
; #pragma unroll
;         for (int bj = 0; bj < 2; ++bj)
; #pragma unroll
;             for (int n = 0; n < 2; ++n) sw[bj][n] = *(const f32x4*)(shw + (size_t)b * ZW + col0 + bj * 128 + 4 * n);
;         float rstd8[8]; row_rstd8(rs, row0, fq, rstd8);
; #pragma unroll
;         for (int ai = 0; ai < 2; ++ai)
; #pragma unroll
;             for (int m = 0; m < 4; ++m) {
;                 const int row = row0 + ai * 128 + m * 16; float ss = 0.f; const float rstd = rstd8[ai * 4 + m];
; #pragma unroll
;                 for (int bj = 0; bj < 2; ++bj) {
;                     float v[8];
; #pragma unroll
;                     for (int n = 0; n < 2; ++n)
; #pragma unroll
;                         for (int j = 0; j < 4; ++j) { float x = acc[ai][bj][m][n][j] * rstd + sw[bj][n][j]; if (act == 1) x = silu_f(x); else if (act == 2) x = gelu_f(x); v[4 * n + j] = x; ss += x * x; }
;                     *(u32x4*)(Z + (size_t)row * ZW + col0 + bj * 128) = pack8(v);
;                 }
;                 if (stat) { ss += __shfl_xor(ss, 16); ss += __shfl_xor(ss, 32); if (fq == 0) rowss[(size_t)row * 8 + (pn - 8) * 4 + wc] = ss; }
;             }
;     }
.LBB0_484:
	s_waitcnt vmcnt(8)
	v_mov_b32_e32 v174, 0x358637bd
	s_mov_b32 s7, 0x3a800000
	v_fma_f32 v243, v243, s7, v174
	v_fma_f32 v244, v244, s7, v174
	v_fma_f32 v245, v245, s7, v174
	v_fma_f32 v246, v246, s7, v174
	v_fma_f32 v247, v247, s7, v174
	v_fma_f32 v248, v248, s7, v174
	v_fma_f32 v249, v249, s7, v174
	v_fma_f32 v250, v250, s7, v174
	v_rsq_f32_e32 v243, v243
	v_rsq_f32_e32 v244, v244
	v_rsq_f32_e32 v245, v245
	v_rsq_f32_e32 v246, v246
	v_rsq_f32_e32 v247, v247
	v_rsq_f32_e32 v248, v248
	v_rsq_f32_e32 v249, v249
	v_rsq_f32_e32 v250, v250
	s_lshl_b32 s11, s73, 4
	s_lshl_b32 s7, s74, 3
	s_add_u32 s11, s11, s7
	s_add_u32 s11, s11, 0x20000
	v_lshl_add_u32 v175, v204, 2, s11
	ds_write_b32 v175, v251
	v_lshl_add_u32 v176, v165, 5, s11
	s_lshl_b32 s12, s6, 8
	s_add_u32 s12, s12, s73
	s_lshl_b32 s7, s10, 8
	s_or_b32 s7, s7, s74
	v_add_u32_e32 v177, s12, v147
	v_mul_u32_u24_e32 v178, 0x1600, v177
	v_lshl_add_u32 v179, v165, 3, s7
	v_lshl_add_u32 v178, v179, 1, v178
	s_add_u32 s48, s88, 0xc800000
	s_addc_u32 s49, s89, 0
	s_mov_b32 s33, 0x3d372713
	v_mov_b32_e32 v183, 0
	v_mov_b32_e32 v184, 0
	v_mov_b32_e32 v185, 0
	v_mov_b32_e32 v186, 0
	v_mov_b32_e32 v187, 0
	v_mov_b32_e32 v188, 0
	v_mov_b32_e32 v189, 0
	v_mov_b32_e32 v190, 0
	s_waitcnt lgkmcnt(0)
	ds_read_b128 v[22:25], v176
	ds_read_b128 v[30:33], v176 offset:16
	ds_read_b128 v[38:41], v176 offset:128
	ds_read_b128 v[46:49], v176 offset:144
	s_waitcnt lgkmcnt(0)
	s_cmp_lt_i32 s10, 4
	s_cbranch_scc1 .Lp5_act0
	s_cmp_gt_i32 s10, 9
	s_cbranch_scc1 .Lp5_act0
	s_cmp_lt_i32 s10, 6
	s_cbranch_scc1 .Lp5_act1
.Lp5_act2:
	v_fma_f32 v142, v142, v243, v22
	v_fma_f32 v143, v143, v243, v23
	v_fma_f32 v144, v144, v243, v24
	v_fma_f32 v145, v145, v243, v25
	v_fma_f32 v138, v138, v243, v30
	v_fma_f32 v139, v139, v243, v31
	v_fma_f32 v140, v140, v243, v32
	v_fma_f32 v141, v141, v243, v33
	v_mul_f32_e32 v166, v142, v142
	v_mul_f32_e32 v167, v143, v143
	v_mul_f32_e32 v168, v144, v144
	v_mul_f32_e32 v169, v145, v145
	v_mul_f32_e32 v170, v138, v138
	v_mul_f32_e32 v171, v139, v139
	v_mul_f32_e32 v172, v140, v140
	v_mul_f32_e32 v173, v141, v141
	v_fma_f32 v166, v166, s33, 1.0
	v_fma_f32 v167, v167, s33, 1.0
	v_fma_f32 v168, v168, s33, 1.0
	v_fma_f32 v169, v169, s33, 1.0
	v_fma_f32 v170, v170, s33, 1.0
	v_fma_f32 v171, v171, s33, 1.0
	v_fma_f32 v172, v172, s33, 1.0
	v_fma_f32 v173, v173, s33, 1.0
	v_mul_f32_e32 v166, v166, v142
	v_mul_f32_e32 v167, v167, v143
	v_mul_f32_e32 v168, v168, v144
	v_mul_f32_e32 v169, v169, v145
	v_mul_f32_e32 v170, v170, v138
	v_mul_f32_e32 v171, v171, v139
	v_mul_f32_e32 v172, v172, v140
	v_mul_f32_e32 v173, v173, v141
	v_mul_f32_e32 v166, 0xc0135761, v166
	v_mul_f32_e32 v167, 0xc0135761, v167
	v_mul_f32_e32 v168, 0xc0135761, v168
	v_mul_f32_e32 v169, 0xc0135761, v169
	v_mul_f32_e32 v170, 0xc0135761, v170
	v_mul_f32_e32 v171, 0xc0135761, v171
	v_mul_f32_e32 v172, 0xc0135761, v172
	v_mul_f32_e32 v173, 0xc0135761, v173
	v_exp_f32_e32 v166, v166
	v_exp_f32_e32 v167, v167
	v_exp_f32_e32 v168, v168
	v_exp_f32_e32 v169, v169
	v_exp_f32_e32 v170, v170
	v_exp_f32_e32 v171, v171
	v_exp_f32_e32 v172, v172
	v_exp_f32_e32 v173, v173
	v_add_f32_e32 v166, 1.0, v166
	v_add_f32_e32 v167, 1.0, v167
	v_add_f32_e32 v168, 1.0, v168
	v_add_f32_e32 v169, 1.0, v169
	v_add_f32_e32 v170, 1.0, v170
	v_add_f32_e32 v171, 1.0, v171
	v_add_f32_e32 v172, 1.0, v172
	v_add_f32_e32 v173, 1.0, v173
	v_rcp_f32_e32 v166, v166
	v_rcp_f32_e32 v167, v167
	v_rcp_f32_e32 v168, v168
	v_rcp_f32_e32 v169, v169
	v_rcp_f32_e32 v170, v170
	v_rcp_f32_e32 v171, v171
	v_rcp_f32_e32 v172, v172
	v_rcp_f32_e32 v173, v173
	v_mul_f32_e32 v142, v142, v166
	v_mul_f32_e32 v143, v143, v167
	v_mul_f32_e32 v144, v144, v168
	v_mul_f32_e32 v145, v145, v169
	v_mul_f32_e32 v138, v138, v170
	v_mul_f32_e32 v139, v139, v171
	v_mul_f32_e32 v140, v140, v172
	v_mul_f32_e32 v141, v141, v173
	v_fmac_f32_e32 v183, v142, v142
	v_fmac_f32_e32 v183, v143, v143
	v_fmac_f32_e32 v183, v144, v144
	v_fmac_f32_e32 v183, v145, v145
	v_fmac_f32_e32 v183, v138, v138
	v_fmac_f32_e32 v183, v139, v139
	v_fmac_f32_e32 v183, v140, v140
	v_fmac_f32_e32 v183, v141, v141
	v_cvt_pk_bf16_f32 v166, v142, v143
	v_cvt_pk_bf16_f32 v167, v144, v145
	v_cvt_pk_bf16_f32 v168, v138, v139
	v_cvt_pk_bf16_f32 v169, v140, v141
	global_store_dwordx4 v178, v[166:169], s[48:49] offset:0
	s_nop 1
	v_fma_f32 v134, v134, v243, v38
	v_fma_f32 v135, v135, v243, v39
	v_fma_f32 v136, v136, v243, v40
	v_fma_f32 v137, v137, v243, v41
	v_fma_f32 v130, v130, v243, v46
	v_fma_f32 v131, v131, v243, v47
	v_fma_f32 v132, v132, v243, v48
	v_fma_f32 v133, v133, v243, v49
	v_mul_f32_e32 v166, v134, v134
	v_mul_f32_e32 v167, v135, v135
	v_mul_f32_e32 v168, v136, v136
	v_mul_f32_e32 v169, v137, v137
	v_mul_f32_e32 v170, v130, v130
	v_mul_f32_e32 v171, v131, v131
	v_mul_f32_e32 v172, v132, v132
	v_mul_f32_e32 v173, v133, v133
	v_fma_f32 v166, v166, s33, 1.0
	v_fma_f32 v167, v167, s33, 1.0
	v_fma_f32 v168, v168, s33, 1.0
	v_fma_f32 v169, v169, s33, 1.0
	v_fma_f32 v170, v170, s33, 1.0
	v_fma_f32 v171, v171, s33, 1.0
	v_fma_f32 v172, v172, s33, 1.0
	v_fma_f32 v173, v173, s33, 1.0
	v_mul_f32_e32 v166, v166, v134
	v_mul_f32_e32 v167, v167, v135
	v_mul_f32_e32 v168, v168, v136
	v_mul_f32_e32 v169, v169, v137
	v_mul_f32_e32 v170, v170, v130
	v_mul_f32_e32 v171, v171, v131
	v_mul_f32_e32 v172, v172, v132
	v_mul_f32_e32 v173, v173, v133
	v_mul_f32_e32 v166, 0xc0135761, v166
	v_mul_f32_e32 v167, 0xc0135761, v167
	v_mul_f32_e32 v168, 0xc0135761, v168
	v_mul_f32_e32 v169, 0xc0135761, v169
	v_mul_f32_e32 v170, 0xc0135761, v170
	v_mul_f32_e32 v171, 0xc0135761, v171
	v_mul_f32_e32 v172, 0xc0135761, v172
	v_mul_f32_e32 v173, 0xc0135761, v173
; DEV float silu_f(float x) { return x * __builtin_amdgcn_rcpf(1.f + __expf(-x)); }
; DEV float gelu_f(float x) { const float t = 1.5957691216f * (x + 0.044715f * x * x * x); return x * __builtin_amdgcn_rcpf(1.f + __expf(-t)); }
; DEV u32x4 pack8(const float (&f)[8]) { u32x4 w; w.x = cvt_pk_bf16(f[0], f[1]); w.y = cvt_pk_bf16(f[2], f[3]); w.z = cvt_pk_bf16(f[4], f[5]); w.w = cvt_pk_bf16(f[6], f[7]); return w; }
;     DEV void operator()(const f32x4 (&acc)[2][2][4][2], const Unit& u, int wr, int wc, int fr, int fq) const {
;     ...
; #pragma unroll
;         for (int ai = 0; ai < 2; ++ai)
; #pragma unroll
;             for (int m = 0; m < 4; ++m) {
;                 const int row = row0 + ai * 128 + m * 16; float ss = 0.f; const float rstd = rstd8[ai * 4 + m];
; #pragma unroll
;                 for (int bj = 0; bj < 2; ++bj) {
;                     float v[8];
; #pragma unroll
;                     for (int n = 0; n < 2; ++n)
; #pragma unroll
;                         for (int j = 0; j < 4; ++j) { float x = acc[ai][bj][m][n][j] * rstd + sw[bj][n][j]; if (act == 1) x = silu_f(x); else if (act == 2) x = gelu_f(x); v[4 * n + j] = x; ss += x * x; }
;                     *(u32x4*)(Z + (size_t)row * ZW + col0 + bj * 128) = pack8(v);
	v_exp_f32_e32 v166, v166
	v_exp_f32_e32 v167, v167
	v_exp_f32_e32 v168, v168
	v_exp_f32_e32 v169, v169
	v_exp_f32_e32 v170, v170
	v_exp_f32_e32 v171, v171
	v_exp_f32_e32 v172, v172
	v_exp_f32_e32 v173, v173
	v_add_f32_e32 v166, 1.0, v166
	v_add_f32_e32 v167, 1.0, v167
	v_add_f32_e32 v168, 1.0, v168
	v_add_f32_e32 v169, 1.0, v169
	v_add_f32_e32 v170, 1.0, v170
	v_add_f32_e32 v171, 1.0, v171
	v_add_f32_e32 v172, 1.0, v172
	v_add_f32_e32 v173, 1.0, v173
	v_rcp_f32_e32 v166, v166
	v_rcp_f32_e32 v167, v167
	v_rcp_f32_e32 v168, v168
	v_rcp_f32_e32 v169, v169
	v_rcp_f32_e32 v170, v170
	v_rcp_f32_e32 v171, v171
	v_rcp_f32_e32 v172, v172
	v_rcp_f32_e32 v173, v173
	v_mul_f32_e32 v134, v134, v166
	v_mul_f32_e32 v135, v135, v167
	v_mul_f32_e32 v136, v136, v168
	v_mul_f32_e32 v137, v137, v169
	v_mul_f32_e32 v130, v130, v170
	v_mul_f32_e32 v131, v131, v171
	v_mul_f32_e32 v132, v132, v172
	v_mul_f32_e32 v133, v133, v173
	v_fmac_f32_e32 v183, v134, v134
	v_fmac_f32_e32 v183, v135, v135
	v_fmac_f32_e32 v183, v136, v136
	v_fmac_f32_e32 v183, v137, v137
	v_fmac_f32_e32 v183, v130, v130
	v_fmac_f32_e32 v183, v131, v131
	v_fmac_f32_e32 v183, v132, v132
	v_fmac_f32_e32 v183, v133, v133
	v_cvt_pk_bf16_f32 v166, v134, v135
	v_cvt_pk_bf16_f32 v167, v136, v137
	v_cvt_pk_bf16_f32 v168, v130, v131
	v_cvt_pk_bf16_f32 v169, v132, v133
	global_store_dwordx4 v178, v[166:169], s[48:49] offset:256
	s_nop 1
	s_add_u32 s46, s48, 0x16000
	s_addc_u32 s47, s49, 0
	v_fma_f32 v126, v126, v244, v22
	v_fma_f32 v127, v127, v244, v23
	v_fma_f32 v128, v128, v244, v24
	v_fma_f32 v129, v129, v244, v25
	v_fma_f32 v122, v122, v244, v30
	v_fma_f32 v123, v123, v244, v31
	v_fma_f32 v124, v124, v244, v32
	v_fma_f32 v125, v125, v244, v33
	v_mul_f32_e32 v166, v126, v126
	v_mul_f32_e32 v167, v127, v127
	v_mul_f32_e32 v168, v128, v128
	v_mul_f32_e32 v169, v129, v129
	v_mul_f32_e32 v170, v122, v122
	v_mul_f32_e32 v171, v123, v123
	v_mul_f32_e32 v172, v124, v124
	v_mul_f32_e32 v173, v125, v125
	v_fma_f32 v166, v166, s33, 1.0
	v_fma_f32 v167, v167, s33, 1.0
	v_fma_f32 v168, v168, s33, 1.0
	v_fma_f32 v169, v169, s33, 1.0
	v_fma_f32 v170, v170, s33, 1.0
	v_fma_f32 v171, v171, s33, 1.0
	v_fma_f32 v172, v172, s33, 1.0
	v_fma_f32 v173, v173, s33, 1.0
	v_mul_f32_e32 v166, v166, v126
	v_mul_f32_e32 v167, v167, v127
	v_mul_f32_e32 v168, v168, v128
	v_mul_f32_e32 v169, v169, v129
	v_mul_f32_e32 v170, v170, v122
	v_mul_f32_e32 v171, v171, v123
	v_mul_f32_e32 v172, v172, v124
	v_mul_f32_e32 v173, v173, v125
	v_mul_f32_e32 v166, 0xc0135761, v166
	v_mul_f32_e32 v167, 0xc0135761, v167
	v_mul_f32_e32 v168, 0xc0135761, v168
	v_mul_f32_e32 v169, 0xc0135761, v169
	v_mul_f32_e32 v170, 0xc0135761, v170
	v_mul_f32_e32 v171, 0xc0135761, v171
	v_mul_f32_e32 v172, 0xc0135761, v172
	v_mul_f32_e32 v173, 0xc0135761, v173
	v_exp_f32_e32 v166, v166
	v_exp_f32_e32 v167, v167
	v_exp_f32_e32 v168, v168
	v_exp_f32_e32 v169, v169
	v_exp_f32_e32 v170, v170
	v_exp_f32_e32 v171, v171
	v_exp_f32_e32 v172, v172
	v_exp_f32_e32 v173, v173
	v_add_f32_e32 v166, 1.0, v166
	v_add_f32_e32 v167, 1.0, v167
	v_add_f32_e32 v168, 1.0, v168
	v_add_f32_e32 v169, 1.0, v169
	v_add_f32_e32 v170, 1.0, v170
	v_add_f32_e32 v171, 1.0, v171
	v_add_f32_e32 v172, 1.0, v172
	v_add_f32_e32 v173, 1.0, v173
	v_rcp_f32_e32 v166, v166
	v_rcp_f32_e32 v167, v167
	v_rcp_f32_e32 v168, v168
	v_rcp_f32_e32 v169, v169
	v_rcp_f32_e32 v170, v170
	v_rcp_f32_e32 v171, v171
	v_rcp_f32_e32 v172, v172
	v_rcp_f32_e32 v173, v173
	v_mul_f32_e32 v126, v126, v166
	v_mul_f32_e32 v127, v127, v167
	v_mul_f32_e32 v128, v128, v168
	v_mul_f32_e32 v129, v129, v169
	v_mul_f32_e32 v122, v122, v170
	v_mul_f32_e32 v123, v123, v171
	v_mul_f32_e32 v124, v124, v172
	v_mul_f32_e32 v125, v125, v173
	v_fmac_f32_e32 v184, v126, v126
	v_fmac_f32_e32 v184, v127, v127
	v_fmac_f32_e32 v184, v128, v128
	v_fmac_f32_e32 v184, v129, v129
	v_fmac_f32_e32 v184, v122, v122
	v_fmac_f32_e32 v184, v123, v123
	v_fmac_f32_e32 v184, v124, v124
	v_fmac_f32_e32 v184, v125, v125
	v_cvt_pk_bf16_f32 v166, v126, v127
	v_cvt_pk_bf16_f32 v167, v128, v129
	v_cvt_pk_bf16_f32 v168, v122, v123
	v_cvt_pk_bf16_f32 v169, v124, v125
	global_store_dwordx4 v178, v[166:169], s[46:47] offset:0
	s_nop 1
	v_fma_f32 v118, v118, v244, v38
	v_fma_f32 v119, v119, v244, v39
	v_fma_f32 v120, v120, v244, v40
	v_fma_f32 v121, v121, v244, v41
	v_fma_f32 v114, v114, v244, v46
	v_fma_f32 v115, v115, v244, v47
	v_fma_f32 v116, v116, v244, v48
	v_fma_f32 v117, v117, v244, v49
	v_mul_f32_e32 v166, v118, v118
	v_mul_f32_e32 v167, v119, v119
	v_mul_f32_e32 v168, v120, v120
	v_mul_f32_e32 v169, v121, v121
	v_mul_f32_e32 v170, v114, v114
	v_mul_f32_e32 v171, v115, v115
	v_mul_f32_e32 v172, v116, v116
	v_mul_f32_e32 v173, v117, v117
	v_fma_f32 v166, v166, s33, 1.0
	v_fma_f32 v167, v167, s33, 1.0
	v_fma_f32 v168, v168, s33, 1.0
	v_fma_f32 v169, v169, s33, 1.0
	v_fma_f32 v170, v170, s33, 1.0
	v_fma_f32 v171, v171, s33, 1.0
	v_fma_f32 v172, v172, s33, 1.0
	v_fma_f32 v173, v173, s33, 1.0
	v_mul_f32_e32 v166, v166, v118
	v_mul_f32_e32 v167, v167, v119
	v_mul_f32_e32 v168, v168, v120
	v_mul_f32_e32 v169, v169, v121
	v_mul_f32_e32 v170, v170, v114
	v_mul_f32_e32 v171, v171, v115
	v_mul_f32_e32 v172, v172, v116
	v_mul_f32_e32 v173, v173, v117
	v_mul_f32_e32 v166, 0xc0135761, v166
	v_mul_f32_e32 v167, 0xc0135761, v167
	v_mul_f32_e32 v168, 0xc0135761, v168
	v_mul_f32_e32 v169, 0xc0135761, v169
	v_mul_f32_e32 v170, 0xc0135761, v170
	v_mul_f32_e32 v171, 0xc0135761, v171
	v_mul_f32_e32 v172, 0xc0135761, v172
	v_mul_f32_e32 v173, 0xc0135761, v173
	v_exp_f32_e32 v166, v166
	v_exp_f32_e32 v167, v167
	v_exp_f32_e32 v168, v168
	v_exp_f32_e32 v169, v169
	v_exp_f32_e32 v170, v170
; DEV float silu_f(float x) { return x * __builtin_amdgcn_rcpf(1.f + __expf(-x)); }
; DEV float gelu_f(float x) { const float t = 1.5957691216f * (x + 0.044715f * x * x * x); return x * __builtin_amdgcn_rcpf(1.f + __expf(-t)); }
; DEV u32x4 pack8(const float (&f)[8]) { u32x4 w; w.x = cvt_pk_bf16(f[0], f[1]); w.y = cvt_pk_bf16(f[2], f[3]); w.z = cvt_pk_bf16(f[4], f[5]); w.w = cvt_pk_bf16(f[6], f[7]); return w; }
;     DEV void operator()(const f32x4 (&acc)[2][2][4][2], const Unit& u, int wr, int wc, int fr, int fq) const {
;     ...
; #pragma unroll
;         for (int ai = 0; ai < 2; ++ai)
; #pragma unroll
;             for (int m = 0; m < 4; ++m) {
;                 const int row = row0 + ai * 128 + m * 16; float ss = 0.f; const float rstd = rstd8[ai * 4 + m];
; #pragma unroll
;                 for (int bj = 0; bj < 2; ++bj) {
;                     float v[8];
; #pragma unroll
;                     for (int n = 0; n < 2; ++n)
; #pragma unroll
;                         for (int j = 0; j < 4; ++j) { float x = acc[ai][bj][m][n][j] * rstd + sw[bj][n][j]; if (act == 1) x = silu_f(x); else if (act == 2) x = gelu_f(x); v[4 * n + j] = x; ss += x * x; }
;                     *(u32x4*)(Z + (size_t)row * ZW + col0 + bj * 128) = pack8(v);
	v_exp_f32_e32 v171, v171
	v_exp_f32_e32 v172, v172
	v_exp_f32_e32 v173, v173
	v_add_f32_e32 v166, 1.0, v166
	v_add_f32_e32 v167, 1.0, v167
	v_add_f32_e32 v168, 1.0, v168
	v_add_f32_e32 v169, 1.0, v169
	v_add_f32_e32 v170, 1.0, v170
	v_add_f32_e32 v171, 1.0, v171
	v_add_f32_e32 v172, 1.0, v172
	v_add_f32_e32 v173, 1.0, v173
	v_rcp_f32_e32 v166, v166
	v_rcp_f32_e32 v167, v167
	v_rcp_f32_e32 v168, v168
	v_rcp_f32_e32 v169, v169
	v_rcp_f32_e32 v170, v170
	v_rcp_f32_e32 v171, v171
	v_rcp_f32_e32 v172, v172
	v_rcp_f32_e32 v173, v173
	v_mul_f32_e32 v118, v118, v166
	v_mul_f32_e32 v119, v119, v167
	v_mul_f32_e32 v120, v120, v168
	v_mul_f32_e32 v121, v121, v169
	v_mul_f32_e32 v114, v114, v170
	v_mul_f32_e32 v115, v115, v171
	v_mul_f32_e32 v116, v116, v172
	v_mul_f32_e32 v117, v117, v173
	v_fmac_f32_e32 v184, v118, v118
	v_fmac_f32_e32 v184, v119, v119
	v_fmac_f32_e32 v184, v120, v120
	v_fmac_f32_e32 v184, v121, v121
	v_fmac_f32_e32 v184, v114, v114
	v_fmac_f32_e32 v184, v115, v115
	v_fmac_f32_e32 v184, v116, v116
	v_fmac_f32_e32 v184, v117, v117
	v_cvt_pk_bf16_f32 v166, v118, v119
	v_cvt_pk_bf16_f32 v167, v120, v121
	v_cvt_pk_bf16_f32 v168, v114, v115
	v_cvt_pk_bf16_f32 v169, v116, v117
	global_store_dwordx4 v178, v[166:169], s[46:47] offset:256
	s_nop 1
	s_add_u32 s46, s48, 0x2c000
	s_addc_u32 s47, s49, 0
	v_fma_f32 v110, v110, v245, v22
	v_fma_f32 v111, v111, v245, v23
	v_fma_f32 v112, v112, v245, v24
	v_fma_f32 v113, v113, v245, v25
	v_fma_f32 v106, v106, v245, v30
	v_fma_f32 v107, v107, v245, v31
	v_fma_f32 v108, v108, v245, v32
	v_fma_f32 v109, v109, v245, v33
	v_mul_f32_e32 v166, v110, v110
	v_mul_f32_e32 v167, v111, v111
	v_mul_f32_e32 v168, v112, v112
	v_mul_f32_e32 v169, v113, v113
	v_mul_f32_e32 v170, v106, v106
	v_mul_f32_e32 v171, v107, v107
	v_mul_f32_e32 v172, v108, v108
	v_mul_f32_e32 v173, v109, v109
	v_fma_f32 v166, v166, s33, 1.0
	v_fma_f32 v167, v167, s33, 1.0
	v_fma_f32 v168, v168, s33, 1.0
	v_fma_f32 v169, v169, s33, 1.0
	v_fma_f32 v170, v170, s33, 1.0
	v_fma_f32 v171, v171, s33, 1.0
	v_fma_f32 v172, v172, s33, 1.0
	v_fma_f32 v173, v173, s33, 1.0
	v_mul_f32_e32 v166, v166, v110
	v_mul_f32_e32 v167, v167, v111
	v_mul_f32_e32 v168, v168, v112
	v_mul_f32_e32 v169, v169, v113
	v_mul_f32_e32 v170, v170, v106
	v_mul_f32_e32 v171, v171, v107
	v_mul_f32_e32 v172, v172, v108
	v_mul_f32_e32 v173, v173, v109
	v_mul_f32_e32 v166, 0xc0135761, v166
	v_mul_f32_e32 v167, 0xc0135761, v167
	v_mul_f32_e32 v168, 0xc0135761, v168
	v_mul_f32_e32 v169, 0xc0135761, v169
	v_mul_f32_e32 v170, 0xc0135761, v170
	v_mul_f32_e32 v171, 0xc0135761, v171
	v_mul_f32_e32 v172, 0xc0135761, v172
	v_mul_f32_e32 v173, 0xc0135761, v173
	v_exp_f32_e32 v166, v166
	v_exp_f32_e32 v167, v167
	v_exp_f32_e32 v168, v168
	v_exp_f32_e32 v169, v169
	v_exp_f32_e32 v170, v170
	v_exp_f32_e32 v171, v171
	v_exp_f32_e32 v172, v172
	v_exp_f32_e32 v173, v173
	v_add_f32_e32 v166, 1.0, v166
	v_add_f32_e32 v167, 1.0, v167
	v_add_f32_e32 v168, 1.0, v168
	v_add_f32_e32 v169, 1.0, v169
	v_add_f32_e32 v170, 1.0, v170
	v_add_f32_e32 v171, 1.0, v171
	v_add_f32_e32 v172, 1.0, v172
	v_add_f32_e32 v173, 1.0, v173
	v_rcp_f32_e32 v166, v166
	v_rcp_f32_e32 v167, v167
	v_rcp_f32_e32 v168, v168
	v_rcp_f32_e32 v169, v169
	v_rcp_f32_e32 v170, v170
	v_rcp_f32_e32 v171, v171
	v_rcp_f32_e32 v172, v172
	v_rcp_f32_e32 v173, v173
	v_mul_f32_e32 v110, v110, v166
	v_mul_f32_e32 v111, v111, v167
	v_mul_f32_e32 v112, v112, v168
	v_mul_f32_e32 v113, v113, v169
	v_mul_f32_e32 v106, v106, v170
	v_mul_f32_e32 v107, v107, v171
	v_mul_f32_e32 v108, v108, v172
	v_mul_f32_e32 v109, v109, v173
	v_fmac_f32_e32 v185, v110, v110
	v_fmac_f32_e32 v185, v111, v111
	v_fmac_f32_e32 v185, v112, v112
	v_fmac_f32_e32 v185, v113, v113
	v_fmac_f32_e32 v185, v106, v106
	v_fmac_f32_e32 v185, v107, v107
	v_fmac_f32_e32 v185, v108, v108
	v_fmac_f32_e32 v185, v109, v109
	v_cvt_pk_bf16_f32 v166, v110, v111
	v_cvt_pk_bf16_f32 v167, v112, v113
	v_cvt_pk_bf16_f32 v168, v106, v107
	v_cvt_pk_bf16_f32 v169, v108, v109
	global_store_dwordx4 v178, v[166:169], s[46:47] offset:0
	s_nop 1
	v_fma_f32 v102, v102, v245, v38
	v_fma_f32 v103, v103, v245, v39
	v_fma_f32 v104, v104, v245, v40
	v_fma_f32 v105, v105, v245, v41
	v_fma_f32 v98, v98, v245, v46
	v_fma_f32 v99, v99, v245, v47
	v_fma_f32 v100, v100, v245, v48
	v_fma_f32 v101, v101, v245, v49
	v_mul_f32_e32 v166, v102, v102
	v_mul_f32_e32 v167, v103, v103
	v_mul_f32_e32 v168, v104, v104
	v_mul_f32_e32 v169, v105, v105
	v_mul_f32_e32 v170, v98, v98
	v_mul_f32_e32 v171, v99, v99
	v_mul_f32_e32 v172, v100, v100
	v_mul_f32_e32 v173, v101, v101
	v_fma_f32 v166, v166, s33, 1.0
	v_fma_f32 v167, v167, s33, 1.0
	v_fma_f32 v168, v168, s33, 1.0
	v_fma_f32 v169, v169, s33, 1.0
	v_fma_f32 v170, v170, s33, 1.0
	v_fma_f32 v171, v171, s33, 1.0
	v_fma_f32 v172, v172, s33, 1.0
	v_fma_f32 v173, v173, s33, 1.0
	v_mul_f32_e32 v166, v166, v102
	v_mul_f32_e32 v167, v167, v103
	v_mul_f32_e32 v168, v168, v104
	v_mul_f32_e32 v169, v169, v105
	v_mul_f32_e32 v170, v170, v98
	v_mul_f32_e32 v171, v171, v99
	v_mul_f32_e32 v172, v172, v100
	v_mul_f32_e32 v173, v173, v101
	v_mul_f32_e32 v166, 0xc0135761, v166
	v_mul_f32_e32 v167, 0xc0135761, v167
	v_mul_f32_e32 v168, 0xc0135761, v168
	v_mul_f32_e32 v169, 0xc0135761, v169
	v_mul_f32_e32 v170, 0xc0135761, v170
	v_mul_f32_e32 v171, 0xc0135761, v171
	v_mul_f32_e32 v172, 0xc0135761, v172
	v_mul_f32_e32 v173, 0xc0135761, v173
	v_exp_f32_e32 v166, v166
	v_exp_f32_e32 v167, v167
	v_exp_f32_e32 v168, v168
	v_exp_f32_e32 v169, v169
	v_exp_f32_e32 v170, v170
	v_exp_f32_e32 v171, v171
	v_exp_f32_e32 v172, v172
	v_exp_f32_e32 v173, v173
	v_add_f32_e32 v166, 1.0, v166
	v_add_f32_e32 v167, 1.0, v167
; DEV float silu_f(float x) { return x * __builtin_amdgcn_rcpf(1.f + __expf(-x)); }
; DEV float gelu_f(float x) { const float t = 1.5957691216f * (x + 0.044715f * x * x * x); return x * __builtin_amdgcn_rcpf(1.f + __expf(-t)); }
; DEV u32x4 pack8(const float (&f)[8]) { u32x4 w; w.x = cvt_pk_bf16(f[0], f[1]); w.y = cvt_pk_bf16(f[2], f[3]); w.z = cvt_pk_bf16(f[4], f[5]); w.w = cvt_pk_bf16(f[6], f[7]); return w; }
;     DEV void operator()(const f32x4 (&acc)[2][2][4][2], const Unit& u, int wr, int wc, int fr, int fq) const {
;     ...
; #pragma unroll
;         for (int ai = 0; ai < 2; ++ai)
; #pragma unroll
;             for (int m = 0; m < 4; ++m) {
;                 const int row = row0 + ai * 128 + m * 16; float ss = 0.f; const float rstd = rstd8[ai * 4 + m];
; #pragma unroll
;                 for (int bj = 0; bj < 2; ++bj) {
;                     float v[8];
; #pragma unroll
;                     for (int n = 0; n < 2; ++n)
; #pragma unroll
;                         for (int j = 0; j < 4; ++j) { float x = acc[ai][bj][m][n][j] * rstd + sw[bj][n][j]; if (act == 1) x = silu_f(x); else if (act == 2) x = gelu_f(x); v[4 * n + j] = x; ss += x * x; }
;                     *(u32x4*)(Z + (size_t)row * ZW + col0 + bj * 128) = pack8(v);
	v_add_f32_e32 v168, 1.0, v168
	v_add_f32_e32 v169, 1.0, v169
	v_add_f32_e32 v170, 1.0, v170
	v_add_f32_e32 v171, 1.0, v171
	v_add_f32_e32 v172, 1.0, v172
	v_add_f32_e32 v173, 1.0, v173
	v_rcp_f32_e32 v166, v166
	v_rcp_f32_e32 v167, v167
	v_rcp_f32_e32 v168, v168
	v_rcp_f32_e32 v169, v169
	v_rcp_f32_e32 v170, v170
	v_rcp_f32_e32 v171, v171
	v_rcp_f32_e32 v172, v172
	v_rcp_f32_e32 v173, v173
	v_mul_f32_e32 v102, v102, v166
	v_mul_f32_e32 v103, v103, v167
	v_mul_f32_e32 v104, v104, v168
	v_mul_f32_e32 v105, v105, v169
	v_mul_f32_e32 v98, v98, v170
	v_mul_f32_e32 v99, v99, v171
	v_mul_f32_e32 v100, v100, v172
	v_mul_f32_e32 v101, v101, v173
	v_fmac_f32_e32 v185, v102, v102
	v_fmac_f32_e32 v185, v103, v103
	v_fmac_f32_e32 v185, v104, v104
	v_fmac_f32_e32 v185, v105, v105
	v_fmac_f32_e32 v185, v98, v98
	v_fmac_f32_e32 v185, v99, v99
	v_fmac_f32_e32 v185, v100, v100
	v_fmac_f32_e32 v185, v101, v101
	v_cvt_pk_bf16_f32 v166, v102, v103
	v_cvt_pk_bf16_f32 v167, v104, v105
	v_cvt_pk_bf16_f32 v168, v98, v99
	v_cvt_pk_bf16_f32 v169, v100, v101
	global_store_dwordx4 v178, v[166:169], s[46:47] offset:256
	s_nop 1
	s_add_u32 s46, s48, 0x42000
	s_addc_u32 s47, s49, 0
	v_fma_f32 v94, v94, v246, v22
	v_fma_f32 v95, v95, v246, v23
	v_fma_f32 v96, v96, v246, v24
	v_fma_f32 v97, v97, v246, v25
	v_fma_f32 v90, v90, v246, v30
	v_fma_f32 v91, v91, v246, v31
	v_fma_f32 v92, v92, v246, v32
	v_fma_f32 v93, v93, v246, v33
	v_mul_f32_e32 v166, v94, v94
	v_mul_f32_e32 v167, v95, v95
	v_mul_f32_e32 v168, v96, v96
	v_mul_f32_e32 v169, v97, v97
	v_mul_f32_e32 v170, v90, v90
	v_mul_f32_e32 v171, v91, v91
	v_mul_f32_e32 v172, v92, v92
	v_mul_f32_e32 v173, v93, v93
	v_fma_f32 v166, v166, s33, 1.0
	v_fma_f32 v167, v167, s33, 1.0
	v_fma_f32 v168, v168, s33, 1.0
	v_fma_f32 v169, v169, s33, 1.0
	v_fma_f32 v170, v170, s33, 1.0
	v_fma_f32 v171, v171, s33, 1.0
	v_fma_f32 v172, v172, s33, 1.0
	v_fma_f32 v173, v173, s33, 1.0
	v_mul_f32_e32 v166, v166, v94
	v_mul_f32_e32 v167, v167, v95
	v_mul_f32_e32 v168, v168, v96
	v_mul_f32_e32 v169, v169, v97
	v_mul_f32_e32 v170, v170, v90
	v_mul_f32_e32 v171, v171, v91
	v_mul_f32_e32 v172, v172, v92
	v_mul_f32_e32 v173, v173, v93
	v_mul_f32_e32 v166, 0xc0135761, v166
	v_mul_f32_e32 v167, 0xc0135761, v167
	v_mul_f32_e32 v168, 0xc0135761, v168
	v_mul_f32_e32 v169, 0xc0135761, v169
	v_mul_f32_e32 v170, 0xc0135761, v170
	v_mul_f32_e32 v171, 0xc0135761, v171
	v_mul_f32_e32 v172, 0xc0135761, v172
	v_mul_f32_e32 v173, 0xc0135761, v173
	v_exp_f32_e32 v166, v166
	v_exp_f32_e32 v167, v167
	v_exp_f32_e32 v168, v168
	v_exp_f32_e32 v169, v169
	v_exp_f32_e32 v170, v170
	v_exp_f32_e32 v171, v171
	v_exp_f32_e32 v172, v172
	v_exp_f32_e32 v173, v173
	v_add_f32_e32 v166, 1.0, v166
	v_add_f32_e32 v167, 1.0, v167
	v_add_f32_e32 v168, 1.0, v168
	v_add_f32_e32 v169, 1.0, v169
	v_add_f32_e32 v170, 1.0, v170
	v_add_f32_e32 v171, 1.0, v171
	v_add_f32_e32 v172, 1.0, v172
	v_add_f32_e32 v173, 1.0, v173
	v_rcp_f32_e32 v166, v166
	v_rcp_f32_e32 v167, v167
	v_rcp_f32_e32 v168, v168
	v_rcp_f32_e32 v169, v169
	v_rcp_f32_e32 v170, v170
	v_rcp_f32_e32 v171, v171
	v_rcp_f32_e32 v172, v172
	v_rcp_f32_e32 v173, v173
	v_mul_f32_e32 v94, v94, v166
	v_mul_f32_e32 v95, v95, v167
	v_mul_f32_e32 v96, v96, v168
	v_mul_f32_e32 v97, v97, v169
	v_mul_f32_e32 v90, v90, v170
	v_mul_f32_e32 v91, v91, v171
	v_mul_f32_e32 v92, v92, v172
	v_mul_f32_e32 v93, v93, v173
	v_fmac_f32_e32 v186, v94, v94
	v_fmac_f32_e32 v186, v95, v95
	v_fmac_f32_e32 v186, v96, v96
	v_fmac_f32_e32 v186, v97, v97
	v_fmac_f32_e32 v186, v90, v90
	v_fmac_f32_e32 v186, v91, v91
	v_fmac_f32_e32 v186, v92, v92
	v_fmac_f32_e32 v186, v93, v93
	v_cvt_pk_bf16_f32 v166, v94, v95
	v_cvt_pk_bf16_f32 v167, v96, v97
	v_cvt_pk_bf16_f32 v168, v90, v91
	v_cvt_pk_bf16_f32 v169, v92, v93
	global_store_dwordx4 v178, v[166:169], s[46:47] offset:0
	s_nop 1
	v_fma_f32 v86, v86, v246, v38
	v_fma_f32 v87, v87, v246, v39
	v_fma_f32 v88, v88, v246, v40
	v_fma_f32 v89, v89, v246, v41
	v_fma_f32 v82, v82, v246, v46
	v_fma_f32 v83, v83, v246, v47
	v_fma_f32 v84, v84, v246, v48
	v_fma_f32 v85, v85, v246, v49
	v_mul_f32_e32 v166, v86, v86
	v_mul_f32_e32 v167, v87, v87
	v_mul_f32_e32 v168, v88, v88
	v_mul_f32_e32 v169, v89, v89
	v_mul_f32_e32 v170, v82, v82
	v_mul_f32_e32 v171, v83, v83
	v_mul_f32_e32 v172, v84, v84
	v_mul_f32_e32 v173, v85, v85
	v_fma_f32 v166, v166, s33, 1.0
	v_fma_f32 v167, v167, s33, 1.0
	v_fma_f32 v168, v168, s33, 1.0
	v_fma_f32 v169, v169, s33, 1.0
	v_fma_f32 v170, v170, s33, 1.0
	v_fma_f32 v171, v171, s33, 1.0
	v_fma_f32 v172, v172, s33, 1.0
	v_fma_f32 v173, v173, s33, 1.0
	v_mul_f32_e32 v166, v166, v86
	v_mul_f32_e32 v167, v167, v87
	v_mul_f32_e32 v168, v168, v88
	v_mul_f32_e32 v169, v169, v89
	v_mul_f32_e32 v170, v170, v82
	v_mul_f32_e32 v171, v171, v83
	v_mul_f32_e32 v172, v172, v84
	v_mul_f32_e32 v173, v173, v85
	v_mul_f32_e32 v166, 0xc0135761, v166
	v_mul_f32_e32 v167, 0xc0135761, v167
	v_mul_f32_e32 v168, 0xc0135761, v168
	v_mul_f32_e32 v169, 0xc0135761, v169
	v_mul_f32_e32 v170, 0xc0135761, v170
	v_mul_f32_e32 v171, 0xc0135761, v171
	v_mul_f32_e32 v172, 0xc0135761, v172
	v_mul_f32_e32 v173, 0xc0135761, v173
	v_exp_f32_e32 v166, v166
	v_exp_f32_e32 v167, v167
	v_exp_f32_e32 v168, v168
	v_exp_f32_e32 v169, v169
	v_exp_f32_e32 v170, v170
	v_exp_f32_e32 v171, v171
	v_exp_f32_e32 v172, v172
	v_exp_f32_e32 v173, v173
	v_add_f32_e32 v166, 1.0, v166
	v_add_f32_e32 v167, 1.0, v167
	v_add_f32_e32 v168, 1.0, v168
	v_add_f32_e32 v169, 1.0, v169
	v_add_f32_e32 v170, 1.0, v170
	v_add_f32_e32 v171, 1.0, v171
	v_add_f32_e32 v172, 1.0, v172
	v_add_f32_e32 v173, 1.0, v173
	v_rcp_f32_e32 v166, v166
	v_rcp_f32_e32 v167, v167
	v_rcp_f32_e32 v168, v168
; DEV float silu_f(float x) { return x * __builtin_amdgcn_rcpf(1.f + __expf(-x)); }
; DEV float gelu_f(float x) { const float t = 1.5957691216f * (x + 0.044715f * x * x * x); return x * __builtin_amdgcn_rcpf(1.f + __expf(-t)); }
; DEV u32x4 pack8(const float (&f)[8]) { u32x4 w; w.x = cvt_pk_bf16(f[0], f[1]); w.y = cvt_pk_bf16(f[2], f[3]); w.z = cvt_pk_bf16(f[4], f[5]); w.w = cvt_pk_bf16(f[6], f[7]); return w; }
;     DEV void operator()(const f32x4 (&acc)[2][2][4][2], const Unit& u, int wr, int wc, int fr, int fq) const {
;     ...
; #pragma unroll
;         for (int ai = 0; ai < 2; ++ai)
; #pragma unroll
;             for (int m = 0; m < 4; ++m) {
;                 const int row = row0 + ai * 128 + m * 16; float ss = 0.f; const float rstd = rstd8[ai * 4 + m];
; #pragma unroll
;                 for (int bj = 0; bj < 2; ++bj) {
;                     float v[8];
; #pragma unroll
;                     for (int n = 0; n < 2; ++n)
; #pragma unroll
;                         for (int j = 0; j < 4; ++j) { float x = acc[ai][bj][m][n][j] * rstd + sw[bj][n][j]; if (act == 1) x = silu_f(x); else if (act == 2) x = gelu_f(x); v[4 * n + j] = x; ss += x * x; }
;                     *(u32x4*)(Z + (size_t)row * ZW + col0 + bj * 128) = pack8(v);
	v_rcp_f32_e32 v169, v169
	v_rcp_f32_e32 v170, v170
	v_rcp_f32_e32 v171, v171
	v_rcp_f32_e32 v172, v172
	v_rcp_f32_e32 v173, v173
	v_mul_f32_e32 v86, v86, v166
	v_mul_f32_e32 v87, v87, v167
	v_mul_f32_e32 v88, v88, v168
	v_mul_f32_e32 v89, v89, v169
	v_mul_f32_e32 v82, v82, v170
	v_mul_f32_e32 v83, v83, v171
	v_mul_f32_e32 v84, v84, v172
	v_mul_f32_e32 v85, v85, v173
	v_fmac_f32_e32 v186, v86, v86
	v_fmac_f32_e32 v186, v87, v87
	v_fmac_f32_e32 v186, v88, v88
	v_fmac_f32_e32 v186, v89, v89
	v_fmac_f32_e32 v186, v82, v82
	v_fmac_f32_e32 v186, v83, v83
	v_fmac_f32_e32 v186, v84, v84
	v_fmac_f32_e32 v186, v85, v85
	v_cvt_pk_bf16_f32 v166, v86, v87
	v_cvt_pk_bf16_f32 v167, v88, v89
	v_cvt_pk_bf16_f32 v168, v82, v83
	v_cvt_pk_bf16_f32 v169, v84, v85
	global_store_dwordx4 v178, v[166:169], s[46:47] offset:256
	s_nop 1
	s_add_u32 s46, s48, 0xb0000
	s_addc_u32 s47, s49, 0
	v_fma_f32 v78, v78, v247, v22
	v_fma_f32 v79, v79, v247, v23
	v_fma_f32 v80, v80, v247, v24
	v_fma_f32 v81, v81, v247, v25
	v_fma_f32 v74, v74, v247, v30
	v_fma_f32 v75, v75, v247, v31
	v_fma_f32 v76, v76, v247, v32
	v_fma_f32 v77, v77, v247, v33
	v_mul_f32_e32 v166, v78, v78
	v_mul_f32_e32 v167, v79, v79
	v_mul_f32_e32 v168, v80, v80
	v_mul_f32_e32 v169, v81, v81
	v_mul_f32_e32 v170, v74, v74
	v_mul_f32_e32 v171, v75, v75
	v_mul_f32_e32 v172, v76, v76
	v_mul_f32_e32 v173, v77, v77
	v_fma_f32 v166, v166, s33, 1.0
	v_fma_f32 v167, v167, s33, 1.0
	v_fma_f32 v168, v168, s33, 1.0
	v_fma_f32 v169, v169, s33, 1.0
	v_fma_f32 v170, v170, s33, 1.0
	v_fma_f32 v171, v171, s33, 1.0
	v_fma_f32 v172, v172, s33, 1.0
	v_fma_f32 v173, v173, s33, 1.0
	v_mul_f32_e32 v166, v166, v78
	v_mul_f32_e32 v167, v167, v79
	v_mul_f32_e32 v168, v168, v80
	v_mul_f32_e32 v169, v169, v81
	v_mul_f32_e32 v170, v170, v74
	v_mul_f32_e32 v171, v171, v75
	v_mul_f32_e32 v172, v172, v76
	v_mul_f32_e32 v173, v173, v77
	v_mul_f32_e32 v166, 0xc0135761, v166
	v_mul_f32_e32 v167, 0xc0135761, v167
	v_mul_f32_e32 v168, 0xc0135761, v168
	v_mul_f32_e32 v169, 0xc0135761, v169
	v_mul_f32_e32 v170, 0xc0135761, v170
	v_mul_f32_e32 v171, 0xc0135761, v171
	v_mul_f32_e32 v172, 0xc0135761, v172
	v_mul_f32_e32 v173, 0xc0135761, v173
	v_exp_f32_e32 v166, v166
	v_exp_f32_e32 v167, v167
	v_exp_f32_e32 v168, v168
	v_exp_f32_e32 v169, v169
	v_exp_f32_e32 v170, v170
	v_exp_f32_e32 v171, v171
	v_exp_f32_e32 v172, v172
	v_exp_f32_e32 v173, v173
	v_add_f32_e32 v166, 1.0, v166
	v_add_f32_e32 v167, 1.0, v167
	v_add_f32_e32 v168, 1.0, v168
	v_add_f32_e32 v169, 1.0, v169
	v_add_f32_e32 v170, 1.0, v170
	v_add_f32_e32 v171, 1.0, v171
	v_add_f32_e32 v172, 1.0, v172
	v_add_f32_e32 v173, 1.0, v173
	v_rcp_f32_e32 v166, v166
	v_rcp_f32_e32 v167, v167
	v_rcp_f32_e32 v168, v168
	v_rcp_f32_e32 v169, v169
	v_rcp_f32_e32 v170, v170
	v_rcp_f32_e32 v171, v171
	v_rcp_f32_e32 v172, v172
	v_rcp_f32_e32 v173, v173
	v_mul_f32_e32 v78, v78, v166
	v_mul_f32_e32 v79, v79, v167
	v_mul_f32_e32 v80, v80, v168
	v_mul_f32_e32 v81, v81, v169
	v_mul_f32_e32 v74, v74, v170
	v_mul_f32_e32 v75, v75, v171
	v_mul_f32_e32 v76, v76, v172
	v_mul_f32_e32 v77, v77, v173
	v_fmac_f32_e32 v187, v78, v78
	v_fmac_f32_e32 v187, v79, v79
	v_fmac_f32_e32 v187, v80, v80
	v_fmac_f32_e32 v187, v81, v81
	v_fmac_f32_e32 v187, v74, v74
	v_fmac_f32_e32 v187, v75, v75
	v_fmac_f32_e32 v187, v76, v76
	v_fmac_f32_e32 v187, v77, v77
	v_cvt_pk_bf16_f32 v166, v78, v79
	v_cvt_pk_bf16_f32 v167, v80, v81
	v_cvt_pk_bf16_f32 v168, v74, v75
	v_cvt_pk_bf16_f32 v169, v76, v77
	global_store_dwordx4 v178, v[166:169], s[46:47] offset:0
	s_nop 1
	v_fma_f32 v70, v70, v247, v38
	v_fma_f32 v71, v71, v247, v39
	v_fma_f32 v72, v72, v247, v40
	v_fma_f32 v73, v73, v247, v41
	v_fma_f32 v66, v66, v247, v46
	v_fma_f32 v67, v67, v247, v47
	v_fma_f32 v68, v68, v247, v48
	v_fma_f32 v69, v69, v247, v49
	v_mul_f32_e32 v166, v70, v70
	v_mul_f32_e32 v167, v71, v71
	v_mul_f32_e32 v168, v72, v72
	v_mul_f32_e32 v169, v73, v73
	v_mul_f32_e32 v170, v66, v66
	v_mul_f32_e32 v171, v67, v67
	v_mul_f32_e32 v172, v68, v68
	v_mul_f32_e32 v173, v69, v69
	v_fma_f32 v166, v166, s33, 1.0
	v_fma_f32 v167, v167, s33, 1.0
	v_fma_f32 v168, v168, s33, 1.0
	v_fma_f32 v169, v169, s33, 1.0
	v_fma_f32 v170, v170, s33, 1.0
	v_fma_f32 v171, v171, s33, 1.0
	v_fma_f32 v172, v172, s33, 1.0
	v_fma_f32 v173, v173, s33, 1.0
	v_mul_f32_e32 v166, v166, v70
	v_mul_f32_e32 v167, v167, v71
	v_mul_f32_e32 v168, v168, v72
	v_mul_f32_e32 v169, v169, v73
	v_mul_f32_e32 v170, v170, v66
	v_mul_f32_e32 v171, v171, v67
	v_mul_f32_e32 v172, v172, v68
	v_mul_f32_e32 v173, v173, v69
	v_mul_f32_e32 v166, 0xc0135761, v166
	v_mul_f32_e32 v167, 0xc0135761, v167
	v_mul_f32_e32 v168, 0xc0135761, v168
	v_mul_f32_e32 v169, 0xc0135761, v169
	v_mul_f32_e32 v170, 0xc0135761, v170
	v_mul_f32_e32 v171, 0xc0135761, v171
	v_mul_f32_e32 v172, 0xc0135761, v172
	v_mul_f32_e32 v173, 0xc0135761, v173
	v_exp_f32_e32 v166, v166
	v_exp_f32_e32 v167, v167
	v_exp_f32_e32 v168, v168
	v_exp_f32_e32 v169, v169
	v_exp_f32_e32 v170, v170
	v_exp_f32_e32 v171, v171
	v_exp_f32_e32 v172, v172
	v_exp_f32_e32 v173, v173
	v_add_f32_e32 v166, 1.0, v166
	v_add_f32_e32 v167, 1.0, v167
	v_add_f32_e32 v168, 1.0, v168
	v_add_f32_e32 v169, 1.0, v169
	v_add_f32_e32 v170, 1.0, v170
	v_add_f32_e32 v171, 1.0, v171
	v_add_f32_e32 v172, 1.0, v172
	v_add_f32_e32 v173, 1.0, v173
	v_rcp_f32_e32 v166, v166
	v_rcp_f32_e32 v167, v167
	v_rcp_f32_e32 v168, v168
	v_rcp_f32_e32 v169, v169
	v_rcp_f32_e32 v170, v170
	v_rcp_f32_e32 v171, v171
	v_rcp_f32_e32 v172, v172
	v_rcp_f32_e32 v173, v173
	v_mul_f32_e32 v70, v70, v166
	v_mul_f32_e32 v71, v71, v167
	v_mul_f32_e32 v72, v72, v168
	v_mul_f32_e32 v73, v73, v169
	v_mul_f32_e32 v66, v66, v170
; DEV float silu_f(float x) { return x * __builtin_amdgcn_rcpf(1.f + __expf(-x)); }
; DEV float gelu_f(float x) { const float t = 1.5957691216f * (x + 0.044715f * x * x * x); return x * __builtin_amdgcn_rcpf(1.f + __expf(-t)); }
; DEV u32x4 pack8(const float (&f)[8]) { u32x4 w; w.x = cvt_pk_bf16(f[0], f[1]); w.y = cvt_pk_bf16(f[2], f[3]); w.z = cvt_pk_bf16(f[4], f[5]); w.w = cvt_pk_bf16(f[6], f[7]); return w; }
;     DEV void operator()(const f32x4 (&acc)[2][2][4][2], const Unit& u, int wr, int wc, int fr, int fq) const {
;     ...
; #pragma unroll
;         for (int ai = 0; ai < 2; ++ai)
; #pragma unroll
;             for (int m = 0; m < 4; ++m) {
;                 const int row = row0 + ai * 128 + m * 16; float ss = 0.f; const float rstd = rstd8[ai * 4 + m];
; #pragma unroll
;                 for (int bj = 0; bj < 2; ++bj) {
;                     float v[8];
; #pragma unroll
;                     for (int n = 0; n < 2; ++n)
; #pragma unroll
;                         for (int j = 0; j < 4; ++j) { float x = acc[ai][bj][m][n][j] * rstd + sw[bj][n][j]; if (act == 1) x = silu_f(x); else if (act == 2) x = gelu_f(x); v[4 * n + j] = x; ss += x * x; }
;                     *(u32x4*)(Z + (size_t)row * ZW + col0 + bj * 128) = pack8(v);
	v_mul_f32_e32 v67, v67, v171
	v_mul_f32_e32 v68, v68, v172
	v_mul_f32_e32 v69, v69, v173
	v_fmac_f32_e32 v187, v70, v70
	v_fmac_f32_e32 v187, v71, v71
	v_fmac_f32_e32 v187, v72, v72
	v_fmac_f32_e32 v187, v73, v73
	v_fmac_f32_e32 v187, v66, v66
	v_fmac_f32_e32 v187, v67, v67
	v_fmac_f32_e32 v187, v68, v68
	v_fmac_f32_e32 v187, v69, v69
	v_cvt_pk_bf16_f32 v166, v70, v71
	v_cvt_pk_bf16_f32 v167, v72, v73
	v_cvt_pk_bf16_f32 v168, v66, v67
	v_cvt_pk_bf16_f32 v169, v68, v69
	global_store_dwordx4 v178, v[166:169], s[46:47] offset:256
	s_nop 1
	s_add_u32 s46, s48, 0xc6000
	s_addc_u32 s47, s49, 0
	v_fma_f32 v62, v62, v248, v22
	v_fma_f32 v63, v63, v248, v23
	v_fma_f32 v64, v64, v248, v24
	v_fma_f32 v65, v65, v248, v25
	v_fma_f32 v58, v58, v248, v30
	v_fma_f32 v59, v59, v248, v31
	v_fma_f32 v60, v60, v248, v32
	v_fma_f32 v61, v61, v248, v33
	v_mul_f32_e32 v166, v62, v62
	v_mul_f32_e32 v167, v63, v63
	v_mul_f32_e32 v168, v64, v64
	v_mul_f32_e32 v169, v65, v65
	v_mul_f32_e32 v170, v58, v58
	v_mul_f32_e32 v171, v59, v59
	v_mul_f32_e32 v172, v60, v60
	v_mul_f32_e32 v173, v61, v61
	v_fma_f32 v166, v166, s33, 1.0
	v_fma_f32 v167, v167, s33, 1.0
	v_fma_f32 v168, v168, s33, 1.0
	v_fma_f32 v169, v169, s33, 1.0
	v_fma_f32 v170, v170, s33, 1.0
	v_fma_f32 v171, v171, s33, 1.0
	v_fma_f32 v172, v172, s33, 1.0
	v_fma_f32 v173, v173, s33, 1.0
	v_mul_f32_e32 v166, v166, v62
	v_mul_f32_e32 v167, v167, v63
	v_mul_f32_e32 v168, v168, v64
	v_mul_f32_e32 v169, v169, v65
	v_mul_f32_e32 v170, v170, v58
	v_mul_f32_e32 v171, v171, v59
	v_mul_f32_e32 v172, v172, v60
	v_mul_f32_e32 v173, v173, v61
	v_mul_f32_e32 v166, 0xc0135761, v166
	v_mul_f32_e32 v167, 0xc0135761, v167
	v_mul_f32_e32 v168, 0xc0135761, v168
	v_mul_f32_e32 v169, 0xc0135761, v169
	v_mul_f32_e32 v170, 0xc0135761, v170
	v_mul_f32_e32 v171, 0xc0135761, v171
	v_mul_f32_e32 v172, 0xc0135761, v172
	v_mul_f32_e32 v173, 0xc0135761, v173
	v_exp_f32_e32 v166, v166
	v_exp_f32_e32 v167, v167
	v_exp_f32_e32 v168, v168
	v_exp_f32_e32 v169, v169
	v_exp_f32_e32 v170, v170
	v_exp_f32_e32 v171, v171
	v_exp_f32_e32 v172, v172
	v_exp_f32_e32 v173, v173
	v_add_f32_e32 v166, 1.0, v166
	v_add_f32_e32 v167, 1.0, v167
	v_add_f32_e32 v168, 1.0, v168
	v_add_f32_e32 v169, 1.0, v169
	v_add_f32_e32 v170, 1.0, v170
	v_add_f32_e32 v171, 1.0, v171
	v_add_f32_e32 v172, 1.0, v172
	v_add_f32_e32 v173, 1.0, v173
	v_rcp_f32_e32 v166, v166
	v_rcp_f32_e32 v167, v167
	v_rcp_f32_e32 v168, v168
	v_rcp_f32_e32 v169, v169
	v_rcp_f32_e32 v170, v170
	v_rcp_f32_e32 v171, v171
	v_rcp_f32_e32 v172, v172
	v_rcp_f32_e32 v173, v173
	v_mul_f32_e32 v62, v62, v166
	v_mul_f32_e32 v63, v63, v167
	v_mul_f32_e32 v64, v64, v168
	v_mul_f32_e32 v65, v65, v169
	v_mul_f32_e32 v58, v58, v170
	v_mul_f32_e32 v59, v59, v171
	v_mul_f32_e32 v60, v60, v172
	v_mul_f32_e32 v61, v61, v173
	v_fmac_f32_e32 v188, v62, v62
	v_fmac_f32_e32 v188, v63, v63
	v_fmac_f32_e32 v188, v64, v64
	v_fmac_f32_e32 v188, v65, v65
	v_fmac_f32_e32 v188, v58, v58
	v_fmac_f32_e32 v188, v59, v59
	v_fmac_f32_e32 v188, v60, v60
	v_fmac_f32_e32 v188, v61, v61
	v_cvt_pk_bf16_f32 v166, v62, v63
	v_cvt_pk_bf16_f32 v167, v64, v65
	v_cvt_pk_bf16_f32 v168, v58, v59
	v_cvt_pk_bf16_f32 v169, v60, v61
	global_store_dwordx4 v178, v[166:169], s[46:47] offset:0
	s_nop 1
	v_fma_f32 v54, v54, v248, v38
	v_fma_f32 v55, v55, v248, v39
	v_fma_f32 v56, v56, v248, v40
	v_fma_f32 v57, v57, v248, v41
	v_fma_f32 v50, v50, v248, v46
	v_fma_f32 v51, v51, v248, v47
	v_fma_f32 v52, v52, v248, v48
	v_fma_f32 v53, v53, v248, v49
	v_mul_f32_e32 v166, v54, v54
	v_mul_f32_e32 v167, v55, v55
	v_mul_f32_e32 v168, v56, v56
	v_mul_f32_e32 v169, v57, v57
	v_mul_f32_e32 v170, v50, v50
	v_mul_f32_e32 v171, v51, v51
	v_mul_f32_e32 v172, v52, v52
	v_mul_f32_e32 v173, v53, v53
	v_fma_f32 v166, v166, s33, 1.0
	v_fma_f32 v167, v167, s33, 1.0
	v_fma_f32 v168, v168, s33, 1.0
	v_fma_f32 v169, v169, s33, 1.0
	v_fma_f32 v170, v170, s33, 1.0
	v_fma_f32 v171, v171, s33, 1.0
	v_fma_f32 v172, v172, s33, 1.0
	v_fma_f32 v173, v173, s33, 1.0
	v_mul_f32_e32 v166, v166, v54
	v_mul_f32_e32 v167, v167, v55
	v_mul_f32_e32 v168, v168, v56
	v_mul_f32_e32 v169, v169, v57
	v_mul_f32_e32 v170, v170, v50
	v_mul_f32_e32 v171, v171, v51
	v_mul_f32_e32 v172, v172, v52
	v_mul_f32_e32 v173, v173, v53
	v_mul_f32_e32 v166, 0xc0135761, v166
	v_mul_f32_e32 v167, 0xc0135761, v167
	v_mul_f32_e32 v168, 0xc0135761, v168
	v_mul_f32_e32 v169, 0xc0135761, v169
	v_mul_f32_e32 v170, 0xc0135761, v170
	v_mul_f32_e32 v171, 0xc0135761, v171
	v_mul_f32_e32 v172, 0xc0135761, v172
	v_mul_f32_e32 v173, 0xc0135761, v173
	v_exp_f32_e32 v166, v166
	v_exp_f32_e32 v167, v167
	v_exp_f32_e32 v168, v168
	v_exp_f32_e32 v169, v169
	v_exp_f32_e32 v170, v170
	v_exp_f32_e32 v171, v171
	v_exp_f32_e32 v172, v172
	v_exp_f32_e32 v173, v173
	v_add_f32_e32 v166, 1.0, v166
	v_add_f32_e32 v167, 1.0, v167
	v_add_f32_e32 v168, 1.0, v168
	v_add_f32_e32 v169, 1.0, v169
	v_add_f32_e32 v170, 1.0, v170
	v_add_f32_e32 v171, 1.0, v171
	v_add_f32_e32 v172, 1.0, v172
	v_add_f32_e32 v173, 1.0, v173
	v_rcp_f32_e32 v166, v166
	v_rcp_f32_e32 v167, v167
	v_rcp_f32_e32 v168, v168
	v_rcp_f32_e32 v169, v169
	v_rcp_f32_e32 v170, v170
	v_rcp_f32_e32 v171, v171
	v_rcp_f32_e32 v172, v172
	v_rcp_f32_e32 v173, v173
	v_mul_f32_e32 v54, v54, v166
	v_mul_f32_e32 v55, v55, v167
	v_mul_f32_e32 v56, v56, v168
	v_mul_f32_e32 v57, v57, v169
	v_mul_f32_e32 v50, v50, v170
	v_mul_f32_e32 v51, v51, v171
	v_mul_f32_e32 v52, v52, v172
	v_mul_f32_e32 v53, v53, v173
	v_fmac_f32_e32 v188, v54, v54
	v_fmac_f32_e32 v188, v55, v55
	v_fmac_f32_e32 v188, v56, v56
	v_fmac_f32_e32 v188, v57, v57
	v_fmac_f32_e32 v188, v50, v50
	v_fmac_f32_e32 v188, v51, v51
; DEV float silu_f(float x) { return x * __builtin_amdgcn_rcpf(1.f + __expf(-x)); }
; DEV float gelu_f(float x) { const float t = 1.5957691216f * (x + 0.044715f * x * x * x); return x * __builtin_amdgcn_rcpf(1.f + __expf(-t)); }
; DEV u32x4 pack8(const float (&f)[8]) { u32x4 w; w.x = cvt_pk_bf16(f[0], f[1]); w.y = cvt_pk_bf16(f[2], f[3]); w.z = cvt_pk_bf16(f[4], f[5]); w.w = cvt_pk_bf16(f[6], f[7]); return w; }
;     DEV void operator()(const f32x4 (&acc)[2][2][4][2], const Unit& u, int wr, int wc, int fr, int fq) const {
;     ...
; #pragma unroll
;         for (int ai = 0; ai < 2; ++ai)
; #pragma unroll
;             for (int m = 0; m < 4; ++m) {
;                 const int row = row0 + ai * 128 + m * 16; float ss = 0.f; const float rstd = rstd8[ai * 4 + m];
; #pragma unroll
;                 for (int bj = 0; bj < 2; ++bj) {
;                     float v[8];
; #pragma unroll
;                     for (int n = 0; n < 2; ++n)
; #pragma unroll
;                         for (int j = 0; j < 4; ++j) { float x = acc[ai][bj][m][n][j] * rstd + sw[bj][n][j]; if (act == 1) x = silu_f(x); else if (act == 2) x = gelu_f(x); v[4 * n + j] = x; ss += x * x; }
;                     *(u32x4*)(Z + (size_t)row * ZW + col0 + bj * 128) = pack8(v);
	v_fmac_f32_e32 v188, v52, v52
	v_fmac_f32_e32 v188, v53, v53
	v_cvt_pk_bf16_f32 v166, v54, v55
	v_cvt_pk_bf16_f32 v167, v56, v57
	v_cvt_pk_bf16_f32 v168, v50, v51
	v_cvt_pk_bf16_f32 v169, v52, v53
	global_store_dwordx4 v178, v[166:169], s[46:47] offset:256
	s_nop 1
	s_add_u32 s46, s48, 0xdc000
	s_addc_u32 s47, s49, 0
	v_fma_f32 v42, v42, v249, v22
	v_fma_f32 v43, v43, v249, v23
	v_fma_f32 v44, v44, v249, v24
	v_fma_f32 v45, v45, v249, v25
	v_fma_f32 v34, v34, v249, v30
	v_fma_f32 v35, v35, v249, v31
	v_fma_f32 v36, v36, v249, v32
	v_fma_f32 v37, v37, v249, v33
	v_mul_f32_e32 v166, v42, v42
	v_mul_f32_e32 v167, v43, v43
	v_mul_f32_e32 v168, v44, v44
	v_mul_f32_e32 v169, v45, v45
	v_mul_f32_e32 v170, v34, v34
	v_mul_f32_e32 v171, v35, v35
	v_mul_f32_e32 v172, v36, v36
	v_mul_f32_e32 v173, v37, v37
	v_fma_f32 v166, v166, s33, 1.0
	v_fma_f32 v167, v167, s33, 1.0
	v_fma_f32 v168, v168, s33, 1.0
	v_fma_f32 v169, v169, s33, 1.0
	v_fma_f32 v170, v170, s33, 1.0
	v_fma_f32 v171, v171, s33, 1.0
	v_fma_f32 v172, v172, s33, 1.0
	v_fma_f32 v173, v173, s33, 1.0
	v_mul_f32_e32 v166, v166, v42
	v_mul_f32_e32 v167, v167, v43
	v_mul_f32_e32 v168, v168, v44
	v_mul_f32_e32 v169, v169, v45
	v_mul_f32_e32 v170, v170, v34
	v_mul_f32_e32 v171, v171, v35
	v_mul_f32_e32 v172, v172, v36
	v_mul_f32_e32 v173, v173, v37
	v_mul_f32_e32 v166, 0xc0135761, v166
	v_mul_f32_e32 v167, 0xc0135761, v167
	v_mul_f32_e32 v168, 0xc0135761, v168
	v_mul_f32_e32 v169, 0xc0135761, v169
	v_mul_f32_e32 v170, 0xc0135761, v170
	v_mul_f32_e32 v171, 0xc0135761, v171
	v_mul_f32_e32 v172, 0xc0135761, v172
	v_mul_f32_e32 v173, 0xc0135761, v173
	v_exp_f32_e32 v166, v166
	v_exp_f32_e32 v167, v167
	v_exp_f32_e32 v168, v168
	v_exp_f32_e32 v169, v169
	v_exp_f32_e32 v170, v170
	v_exp_f32_e32 v171, v171
	v_exp_f32_e32 v172, v172
	v_exp_f32_e32 v173, v173
	v_add_f32_e32 v166, 1.0, v166
	v_add_f32_e32 v167, 1.0, v167
	v_add_f32_e32 v168, 1.0, v168
	v_add_f32_e32 v169, 1.0, v169
	v_add_f32_e32 v170, 1.0, v170
	v_add_f32_e32 v171, 1.0, v171
	v_add_f32_e32 v172, 1.0, v172
	v_add_f32_e32 v173, 1.0, v173
	v_rcp_f32_e32 v166, v166
	v_rcp_f32_e32 v167, v167
	v_rcp_f32_e32 v168, v168
	v_rcp_f32_e32 v169, v169
	v_rcp_f32_e32 v170, v170
	v_rcp_f32_e32 v171, v171
	v_rcp_f32_e32 v172, v172
	v_rcp_f32_e32 v173, v173
	v_mul_f32_e32 v42, v42, v166
	v_mul_f32_e32 v43, v43, v167
	v_mul_f32_e32 v44, v44, v168
	v_mul_f32_e32 v45, v45, v169
	v_mul_f32_e32 v34, v34, v170
	v_mul_f32_e32 v35, v35, v171
	v_mul_f32_e32 v36, v36, v172
	v_mul_f32_e32 v37, v37, v173
	v_fmac_f32_e32 v189, v42, v42
	v_fmac_f32_e32 v189, v43, v43
	v_fmac_f32_e32 v189, v44, v44
	v_fmac_f32_e32 v189, v45, v45
	v_fmac_f32_e32 v189, v34, v34
	v_fmac_f32_e32 v189, v35, v35
	v_fmac_f32_e32 v189, v36, v36
	v_fmac_f32_e32 v189, v37, v37
	v_cvt_pk_bf16_f32 v166, v42, v43
	v_cvt_pk_bf16_f32 v167, v44, v45
	v_cvt_pk_bf16_f32 v168, v34, v35
	v_cvt_pk_bf16_f32 v169, v36, v37
	global_store_dwordx4 v178, v[166:169], s[46:47] offset:0
	s_nop 1
	v_fma_f32 v26, v26, v249, v38
	v_fma_f32 v27, v27, v249, v39
	v_fma_f32 v28, v28, v249, v40
	v_fma_f32 v29, v29, v249, v41
	v_fma_f32 v18, v18, v249, v46
	v_fma_f32 v19, v19, v249, v47
	v_fma_f32 v20, v20, v249, v48
	v_fma_f32 v21, v21, v249, v49
	v_mul_f32_e32 v166, v26, v26
	v_mul_f32_e32 v167, v27, v27
	v_mul_f32_e32 v168, v28, v28
	v_mul_f32_e32 v169, v29, v29
	v_mul_f32_e32 v170, v18, v18
	v_mul_f32_e32 v171, v19, v19
	v_mul_f32_e32 v172, v20, v20
	v_mul_f32_e32 v173, v21, v21
	v_fma_f32 v166, v166, s33, 1.0
	v_fma_f32 v167, v167, s33, 1.0
	v_fma_f32 v168, v168, s33, 1.0
	v_fma_f32 v169, v169, s33, 1.0
	v_fma_f32 v170, v170, s33, 1.0
	v_fma_f32 v171, v171, s33, 1.0
	v_fma_f32 v172, v172, s33, 1.0
	v_fma_f32 v173, v173, s33, 1.0
	v_mul_f32_e32 v166, v166, v26
	v_mul_f32_e32 v167, v167, v27
	v_mul_f32_e32 v168, v168, v28
	v_mul_f32_e32 v169, v169, v29
	v_mul_f32_e32 v170, v170, v18
	v_mul_f32_e32 v171, v171, v19
	v_mul_f32_e32 v172, v172, v20
	v_mul_f32_e32 v173, v173, v21
	v_mul_f32_e32 v166, 0xc0135761, v166
	v_mul_f32_e32 v167, 0xc0135761, v167
	v_mul_f32_e32 v168, 0xc0135761, v168
	v_mul_f32_e32 v169, 0xc0135761, v169
	v_mul_f32_e32 v170, 0xc0135761, v170
	v_mul_f32_e32 v171, 0xc0135761, v171
	v_mul_f32_e32 v172, 0xc0135761, v172
	v_mul_f32_e32 v173, 0xc0135761, v173
	v_exp_f32_e32 v166, v166
	v_exp_f32_e32 v167, v167
	v_exp_f32_e32 v168, v168
	v_exp_f32_e32 v169, v169
	v_exp_f32_e32 v170, v170
	v_exp_f32_e32 v171, v171
	v_exp_f32_e32 v172, v172
	v_exp_f32_e32 v173, v173
	v_add_f32_e32 v166, 1.0, v166
	v_add_f32_e32 v167, 1.0, v167
	v_add_f32_e32 v168, 1.0, v168
	v_add_f32_e32 v169, 1.0, v169
	v_add_f32_e32 v170, 1.0, v170
	v_add_f32_e32 v171, 1.0, v171
	v_add_f32_e32 v172, 1.0, v172
	v_add_f32_e32 v173, 1.0, v173
	v_rcp_f32_e32 v166, v166
	v_rcp_f32_e32 v167, v167
	v_rcp_f32_e32 v168, v168
	v_rcp_f32_e32 v169, v169
	v_rcp_f32_e32 v170, v170
	v_rcp_f32_e32 v171, v171
	v_rcp_f32_e32 v172, v172
	v_rcp_f32_e32 v173, v173
	v_mul_f32_e32 v26, v26, v166
	v_mul_f32_e32 v27, v27, v167
	v_mul_f32_e32 v28, v28, v168
	v_mul_f32_e32 v29, v29, v169
	v_mul_f32_e32 v18, v18, v170
	v_mul_f32_e32 v19, v19, v171
	v_mul_f32_e32 v20, v20, v172
	v_mul_f32_e32 v21, v21, v173
	v_fmac_f32_e32 v189, v26, v26
	v_fmac_f32_e32 v189, v27, v27
	v_fmac_f32_e32 v189, v28, v28
	v_fmac_f32_e32 v189, v29, v29
	v_fmac_f32_e32 v189, v18, v18
	v_fmac_f32_e32 v189, v19, v19
	v_fmac_f32_e32 v189, v20, v20
	v_fmac_f32_e32 v189, v21, v21
	v_cvt_pk_bf16_f32 v166, v26, v27
	v_cvt_pk_bf16_f32 v167, v28, v29
	v_cvt_pk_bf16_f32 v168, v18, v19
	v_cvt_pk_bf16_f32 v169, v20, v21
	global_store_dwordx4 v178, v[166:169], s[46:47] offset:256
	s_nop 1
	s_add_u32 s46, s48, 0xf2000
; DEV float silu_f(float x) { return x * __builtin_amdgcn_rcpf(1.f + __expf(-x)); }
; DEV float gelu_f(float x) { const float t = 1.5957691216f * (x + 0.044715f * x * x * x); return x * __builtin_amdgcn_rcpf(1.f + __expf(-t)); }
; DEV u32x4 pack8(const float (&f)[8]) { u32x4 w; w.x = cvt_pk_bf16(f[0], f[1]); w.y = cvt_pk_bf16(f[2], f[3]); w.z = cvt_pk_bf16(f[4], f[5]); w.w = cvt_pk_bf16(f[6], f[7]); return w; }
;     DEV void operator()(const f32x4 (&acc)[2][2][4][2], const Unit& u, int wr, int wc, int fr, int fq) const {
;     ...
; #pragma unroll
;         for (int ai = 0; ai < 2; ++ai)
; #pragma unroll
;             for (int m = 0; m < 4; ++m) {
;                 const int row = row0 + ai * 128 + m * 16; float ss = 0.f; const float rstd = rstd8[ai * 4 + m];
; #pragma unroll
;                 for (int bj = 0; bj < 2; ++bj) {
;                     float v[8];
; #pragma unroll
;                     for (int n = 0; n < 2; ++n)
; #pragma unroll
;                         for (int j = 0; j < 4; ++j) { float x = acc[ai][bj][m][n][j] * rstd + sw[bj][n][j]; if (act == 1) x = silu_f(x); else if (act == 2) x = gelu_f(x); v[4 * n + j] = x; ss += x * x; }
;                     *(u32x4*)(Z + (size_t)row * ZW + col0 + bj * 128) = pack8(v);
;                 }
;                 if (stat) { ss += __shfl_xor(ss, 16); ss += __shfl_xor(ss, 32); if (fq == 0) rowss[(size_t)row * 8 + (pn - 8) * 4 + wc] = ss; }
	s_addc_u32 s47, s49, 0
	v_fma_f32 v14, v14, v250, v22
	v_fma_f32 v15, v15, v250, v23
	v_fma_f32 v16, v16, v250, v24
	v_fma_f32 v17, v17, v250, v25
	v_fma_f32 v10, v10, v250, v30
	v_fma_f32 v11, v11, v250, v31
	v_fma_f32 v12, v12, v250, v32
	v_fma_f32 v13, v13, v250, v33
	v_mul_f32_e32 v166, v14, v14
	v_mul_f32_e32 v167, v15, v15
	v_mul_f32_e32 v168, v16, v16
	v_mul_f32_e32 v169, v17, v17
	v_mul_f32_e32 v170, v10, v10
	v_mul_f32_e32 v171, v11, v11
	v_mul_f32_e32 v172, v12, v12
	v_mul_f32_e32 v173, v13, v13
	v_fma_f32 v166, v166, s33, 1.0
	v_fma_f32 v167, v167, s33, 1.0
	v_fma_f32 v168, v168, s33, 1.0
	v_fma_f32 v169, v169, s33, 1.0
	v_fma_f32 v170, v170, s33, 1.0
	v_fma_f32 v171, v171, s33, 1.0
	v_fma_f32 v172, v172, s33, 1.0
	v_fma_f32 v173, v173, s33, 1.0
	v_mul_f32_e32 v166, v166, v14
	v_mul_f32_e32 v167, v167, v15
	v_mul_f32_e32 v168, v168, v16
	v_mul_f32_e32 v169, v169, v17
	v_mul_f32_e32 v170, v170, v10
	v_mul_f32_e32 v171, v171, v11
	v_mul_f32_e32 v172, v172, v12
	v_mul_f32_e32 v173, v173, v13
	v_mul_f32_e32 v166, 0xc0135761, v166
	v_mul_f32_e32 v167, 0xc0135761, v167
	v_mul_f32_e32 v168, 0xc0135761, v168
	v_mul_f32_e32 v169, 0xc0135761, v169
	v_mul_f32_e32 v170, 0xc0135761, v170
	v_mul_f32_e32 v171, 0xc0135761, v171
	v_mul_f32_e32 v172, 0xc0135761, v172
	v_mul_f32_e32 v173, 0xc0135761, v173
	v_exp_f32_e32 v166, v166
	v_exp_f32_e32 v167, v167
	v_exp_f32_e32 v168, v168
	v_exp_f32_e32 v169, v169
	v_exp_f32_e32 v170, v170
	v_exp_f32_e32 v171, v171
	v_exp_f32_e32 v172, v172
	v_exp_f32_e32 v173, v173
	v_add_f32_e32 v166, 1.0, v166
	v_add_f32_e32 v167, 1.0, v167
	v_add_f32_e32 v168, 1.0, v168
	v_add_f32_e32 v169, 1.0, v169
	v_add_f32_e32 v170, 1.0, v170
	v_add_f32_e32 v171, 1.0, v171
	v_add_f32_e32 v172, 1.0, v172
	v_add_f32_e32 v173, 1.0, v173
	v_rcp_f32_e32 v166, v166
	v_rcp_f32_e32 v167, v167
	v_rcp_f32_e32 v168, v168
	v_rcp_f32_e32 v169, v169
	v_rcp_f32_e32 v170, v170
	v_rcp_f32_e32 v171, v171
	v_rcp_f32_e32 v172, v172
	v_rcp_f32_e32 v173, v173
	v_mul_f32_e32 v14, v14, v166
	v_mul_f32_e32 v15, v15, v167
	v_mul_f32_e32 v16, v16, v168
	v_mul_f32_e32 v17, v17, v169
	v_mul_f32_e32 v10, v10, v170
	v_mul_f32_e32 v11, v11, v171
	v_mul_f32_e32 v12, v12, v172
	v_mul_f32_e32 v13, v13, v173
	v_fmac_f32_e32 v190, v14, v14
	v_fmac_f32_e32 v190, v15, v15
	v_fmac_f32_e32 v190, v16, v16
	v_fmac_f32_e32 v190, v17, v17
	v_fmac_f32_e32 v190, v10, v10
	v_fmac_f32_e32 v190, v11, v11
	v_fmac_f32_e32 v190, v12, v12
	v_fmac_f32_e32 v190, v13, v13
	v_cvt_pk_bf16_f32 v166, v14, v15
	v_cvt_pk_bf16_f32 v167, v16, v17
	v_cvt_pk_bf16_f32 v168, v10, v11
	v_cvt_pk_bf16_f32 v169, v12, v13
	global_store_dwordx4 v178, v[166:169], s[46:47] offset:0
	s_nop 1
	v_fma_f32 v6, v6, v250, v38
	v_fma_f32 v7, v7, v250, v39
	v_fma_f32 v8, v8, v250, v40
	v_fma_f32 v9, v9, v250, v41
	v_fma_f32 v2, v2, v250, v46
	v_fma_f32 v3, v3, v250, v47
	v_fma_f32 v4, v4, v250, v48
	v_fma_f32 v5, v5, v250, v49
	v_mul_f32_e32 v166, v6, v6
	v_mul_f32_e32 v167, v7, v7
	v_mul_f32_e32 v168, v8, v8
	v_mul_f32_e32 v169, v9, v9
	v_mul_f32_e32 v170, v2, v2
	v_mul_f32_e32 v171, v3, v3
	v_mul_f32_e32 v172, v4, v4
	v_mul_f32_e32 v173, v5, v5
	v_fma_f32 v166, v166, s33, 1.0
	v_fma_f32 v167, v167, s33, 1.0
	v_fma_f32 v168, v168, s33, 1.0
	v_fma_f32 v169, v169, s33, 1.0
	v_fma_f32 v170, v170, s33, 1.0
	v_fma_f32 v171, v171, s33, 1.0
	v_fma_f32 v172, v172, s33, 1.0
	v_fma_f32 v173, v173, s33, 1.0
	v_mul_f32_e32 v166, v166, v6
	v_mul_f32_e32 v167, v167, v7
	v_mul_f32_e32 v168, v168, v8
	v_mul_f32_e32 v169, v169, v9
	v_mul_f32_e32 v170, v170, v2
	v_mul_f32_e32 v171, v171, v3
	v_mul_f32_e32 v172, v172, v4
	v_mul_f32_e32 v173, v173, v5
	v_mul_f32_e32 v166, 0xc0135761, v166
	v_mul_f32_e32 v167, 0xc0135761, v167
	v_mul_f32_e32 v168, 0xc0135761, v168
	v_mul_f32_e32 v169, 0xc0135761, v169
	v_mul_f32_e32 v170, 0xc0135761, v170
	v_mul_f32_e32 v171, 0xc0135761, v171
	v_mul_f32_e32 v172, 0xc0135761, v172
	v_mul_f32_e32 v173, 0xc0135761, v173
	v_exp_f32_e32 v166, v166
	v_exp_f32_e32 v167, v167
	v_exp_f32_e32 v168, v168
	v_exp_f32_e32 v169, v169
	v_exp_f32_e32 v170, v170
	v_exp_f32_e32 v171, v171
	v_exp_f32_e32 v172, v172
	v_exp_f32_e32 v173, v173
	v_add_f32_e32 v166, 1.0, v166
	v_add_f32_e32 v167, 1.0, v167
	v_add_f32_e32 v168, 1.0, v168
	v_add_f32_e32 v169, 1.0, v169
	v_add_f32_e32 v170, 1.0, v170
	v_add_f32_e32 v171, 1.0, v171
	v_add_f32_e32 v172, 1.0, v172
	v_add_f32_e32 v173, 1.0, v173
	v_rcp_f32_e32 v166, v166
	v_rcp_f32_e32 v167, v167
	v_rcp_f32_e32 v168, v168
	v_rcp_f32_e32 v169, v169
	v_rcp_f32_e32 v170, v170
	v_rcp_f32_e32 v171, v171
	v_rcp_f32_e32 v172, v172
	v_rcp_f32_e32 v173, v173
	v_mul_f32_e32 v6, v6, v166
	v_mul_f32_e32 v7, v7, v167
	v_mul_f32_e32 v8, v8, v168
	v_mul_f32_e32 v9, v9, v169
	v_mul_f32_e32 v2, v2, v170
	v_mul_f32_e32 v3, v3, v171
	v_mul_f32_e32 v4, v4, v172
	v_mul_f32_e32 v5, v5, v173
	v_fmac_f32_e32 v190, v6, v6
	v_fmac_f32_e32 v190, v7, v7
	v_fmac_f32_e32 v190, v8, v8
	v_fmac_f32_e32 v190, v9, v9
	v_fmac_f32_e32 v190, v2, v2
	v_fmac_f32_e32 v190, v3, v3
	v_fmac_f32_e32 v190, v4, v4
	v_fmac_f32_e32 v190, v5, v5
	v_cvt_pk_bf16_f32 v166, v6, v7
	v_cvt_pk_bf16_f32 v167, v8, v9
	v_cvt_pk_bf16_f32 v168, v2, v3
	v_cvt_pk_bf16_f32 v169, v4, v5
	global_store_dwordx4 v178, v[166:169], s[46:47] offset:256
	s_nop 1
	s_cmp_lt_i32 s10, 8
	s_cbranch_scc1 .Lp5_done
; DEV float silu_f(float x) { return x * __builtin_amdgcn_rcpf(1.f + __expf(-x)); }
; DEV float gelu_f(float x) { const float t = 1.5957691216f * (x + 0.044715f * x * x * x); return x * __builtin_amdgcn_rcpf(1.f + __expf(-t)); }
; DEV u32x4 pack8(const float (&f)[8]) { u32x4 w; w.x = cvt_pk_bf16(f[0], f[1]); w.y = cvt_pk_bf16(f[2], f[3]); w.z = cvt_pk_bf16(f[4], f[5]); w.w = cvt_pk_bf16(f[6], f[7]); return w; }
;     DEV void operator()(const f32x4 (&acc)[2][2][4][2], const Unit& u, int wr, int wc, int fr, int fq) const {
;     ...
;                         for (int j = 0; j < 4; ++j) { float x = acc[ai][bj][m][n][j] * rstd + sw[bj][n][j]; if (act == 1) x = silu_f(x); else if (act == 2) x = gelu_f(x); v[4 * n + j] = x; ss += x * x; }
;                     *(u32x4*)(Z + (size_t)row * ZW + col0 + bj * 128) = pack8(v);
;     ...
;                 if (stat) { ss += __shfl_xor(ss, 16); ss += __shfl_xor(ss, 32); if (fq == 0) rowss[(size_t)row * 8 + (pn - 8) * 4 + wc] = ss; }
	v_xor_b32_e32 v180, 16, v204
	v_xor_b32_e32 v181, 32, v204
	v_lshlrev_b32_e32 v180, 2, v180
	v_lshlrev_b32_e32 v181, 2, v181
	ds_bpermute_b32 v191, v180, v183
	ds_bpermute_b32 v192, v180, v184
	ds_bpermute_b32 v193, v180, v185
	ds_bpermute_b32 v194, v180, v186
	ds_bpermute_b32 v195, v180, v187
	ds_bpermute_b32 v196, v180, v188
	ds_bpermute_b32 v197, v180, v189
	ds_bpermute_b32 v198, v180, v190
	s_waitcnt lgkmcnt(0)
	v_add_f32_e32 v183, v183, v191
	v_add_f32_e32 v184, v184, v192
	v_add_f32_e32 v185, v185, v193
	v_add_f32_e32 v186, v186, v194
	v_add_f32_e32 v187, v187, v195
	v_add_f32_e32 v188, v188, v196
	v_add_f32_e32 v189, v189, v197
	v_add_f32_e32 v190, v190, v198
	ds_bpermute_b32 v191, v181, v183
	ds_bpermute_b32 v192, v181, v184
	ds_bpermute_b32 v193, v181, v185
	ds_bpermute_b32 v194, v181, v186
	ds_bpermute_b32 v195, v181, v187
	ds_bpermute_b32 v196, v181, v188
	ds_bpermute_b32 v197, v181, v189
	ds_bpermute_b32 v198, v181, v190
	s_waitcnt lgkmcnt(0)
	v_add_f32_e32 v183, v183, v191
	v_add_f32_e32 v184, v184, v192
	v_add_f32_e32 v185, v185, v193
	v_add_f32_e32 v186, v186, v194
	v_add_f32_e32 v187, v187, v195
	v_add_f32_e32 v188, v188, v196
	v_add_f32_e32 v189, v189, v197
	v_add_f32_e32 v190, v190, v198
	v_lshlrev_b32_e32 v182, 5, v177
	s_sub_u32 s7, s10, 8
	s_lshl_b32 s7, s7, 2
	s_add_u32 s7, s7, s72
	s_lshl_b32 s7, s7, 2
	s_add_u32 s46, s88, 0x3c600000
	s_addc_u32 s47, s89, 0
	s_add_u32 s46, s46, s7
	s_addc_u32 s47, s47, 0
	v_cmp_eq_u32_e32 vcc, 0, v165
	s_nop 4
	s_and_saveexec_b64 s[100:101], vcc
	global_store_dword v182, v183, s[46:47] offset:0
	global_store_dword v182, v184, s[46:47] offset:512
	global_store_dword v182, v185, s[46:47] offset:1024
	global_store_dword v182, v186, s[46:47] offset:1536
	s_add_u32 s46, s46, 0x1000
	s_addc_u32 s47, s47, 0
	global_store_dword v182, v187, s[46:47] offset:0
	global_store_dword v182, v188, s[46:47] offset:512
	global_store_dword v182, v189, s[46:47] offset:1024
	global_store_dword v182, v190, s[46:47] offset:1536
	s_or_b64 exec, exec, s[100:101]
	s_branch .Lp5_done
.Lp5_act1:
	v_fma_f32 v142, v142, v243, v22
	v_fma_f32 v143, v143, v243, v23
	v_fma_f32 v144, v144, v243, v24
	v_fma_f32 v145, v145, v243, v25
	v_fma_f32 v138, v138, v243, v30
	v_fma_f32 v139, v139, v243, v31
	v_fma_f32 v140, v140, v243, v32
	v_fma_f32 v141, v141, v243, v33
	v_mul_f32_e32 v166, 0xbfb8aa3b, v142
	v_mul_f32_e32 v167, 0xbfb8aa3b, v143
	v_mul_f32_e32 v168, 0xbfb8aa3b, v144
	v_mul_f32_e32 v169, 0xbfb8aa3b, v145
	v_mul_f32_e32 v170, 0xbfb8aa3b, v138
	v_mul_f32_e32 v171, 0xbfb8aa3b, v139
	v_mul_f32_e32 v172, 0xbfb8aa3b, v140
	v_mul_f32_e32 v173, 0xbfb8aa3b, v141
	v_exp_f32_e32 v166, v166
	v_exp_f32_e32 v167, v167
	v_exp_f32_e32 v168, v168
	v_exp_f32_e32 v169, v169
	v_exp_f32_e32 v170, v170
	v_exp_f32_e32 v171, v171
	v_exp_f32_e32 v172, v172
	v_exp_f32_e32 v173, v173
	v_add_f32_e32 v166, 1.0, v166
	v_add_f32_e32 v167, 1.0, v167
	v_add_f32_e32 v168, 1.0, v168
	v_add_f32_e32 v169, 1.0, v169
	v_add_f32_e32 v170, 1.0, v170
	v_add_f32_e32 v171, 1.0, v171
	v_add_f32_e32 v172, 1.0, v172
	v_add_f32_e32 v173, 1.0, v173
	v_rcp_f32_e32 v166, v166
	v_rcp_f32_e32 v167, v167
	v_rcp_f32_e32 v168, v168
	v_rcp_f32_e32 v169, v169
	v_rcp_f32_e32 v170, v170
	v_rcp_f32_e32 v171, v171
	v_rcp_f32_e32 v172, v172
	v_rcp_f32_e32 v173, v173
	v_mul_f32_e32 v142, v142, v166
	v_mul_f32_e32 v143, v143, v167
	v_mul_f32_e32 v144, v144, v168
	v_mul_f32_e32 v145, v145, v169
	v_mul_f32_e32 v138, v138, v170
	v_mul_f32_e32 v139, v139, v171
	v_mul_f32_e32 v140, v140, v172
	v_mul_f32_e32 v141, v141, v173
	v_cvt_pk_bf16_f32 v166, v142, v143
	v_cvt_pk_bf16_f32 v167, v144, v145
	v_cvt_pk_bf16_f32 v168, v138, v139
	v_cvt_pk_bf16_f32 v169, v140, v141
	global_store_dwordx4 v178, v[166:169], s[48:49] offset:0
	s_nop 1
	v_fma_f32 v134, v134, v243, v38
	v_fma_f32 v135, v135, v243, v39
	v_fma_f32 v136, v136, v243, v40
	v_fma_f32 v137, v137, v243, v41
	v_fma_f32 v130, v130, v243, v46
	v_fma_f32 v131, v131, v243, v47
	v_fma_f32 v132, v132, v243, v48
	v_fma_f32 v133, v133, v243, v49
	v_mul_f32_e32 v166, 0xbfb8aa3b, v134
	v_mul_f32_e32 v167, 0xbfb8aa3b, v135
	v_mul_f32_e32 v168, 0xbfb8aa3b, v136
	v_mul_f32_e32 v169, 0xbfb8aa3b, v137
	v_mul_f32_e32 v170, 0xbfb8aa3b, v130
	v_mul_f32_e32 v171, 0xbfb8aa3b, v131
	v_mul_f32_e32 v172, 0xbfb8aa3b, v132
	v_mul_f32_e32 v173, 0xbfb8aa3b, v133
	v_exp_f32_e32 v166, v166
	v_exp_f32_e32 v167, v167
	v_exp_f32_e32 v168, v168
	v_exp_f32_e32 v169, v169
	v_exp_f32_e32 v170, v170
	v_exp_f32_e32 v171, v171
	v_exp_f32_e32 v172, v172
	v_exp_f32_e32 v173, v173
	v_add_f32_e32 v166, 1.0, v166
	v_add_f32_e32 v167, 1.0, v167
	v_add_f32_e32 v168, 1.0, v168
	v_add_f32_e32 v169, 1.0, v169
	v_add_f32_e32 v170, 1.0, v170
	v_add_f32_e32 v171, 1.0, v171
	v_add_f32_e32 v172, 1.0, v172
	v_add_f32_e32 v173, 1.0, v173
	v_rcp_f32_e32 v166, v166
	v_rcp_f32_e32 v167, v167
	v_rcp_f32_e32 v168, v168
	v_rcp_f32_e32 v169, v169
	v_rcp_f32_e32 v170, v170
	v_rcp_f32_e32 v171, v171
	v_rcp_f32_e32 v172, v172
	v_rcp_f32_e32 v173, v173
	v_mul_f32_e32 v134, v134, v166
	v_mul_f32_e32 v135, v135, v167
	v_mul_f32_e32 v136, v136, v168
	v_mul_f32_e32 v137, v137, v169
	v_mul_f32_e32 v130, v130, v170
	v_mul_f32_e32 v131, v131, v171
	v_mul_f32_e32 v132, v132, v172
	v_mul_f32_e32 v133, v133, v173
	v_cvt_pk_bf16_f32 v166, v134, v135
	v_cvt_pk_bf16_f32 v167, v136, v137
	v_cvt_pk_bf16_f32 v168, v130, v131
	v_cvt_pk_bf16_f32 v169, v132, v133
	global_store_dwordx4 v178, v[166:169], s[48:49] offset:256
	s_nop 1
	s_add_u32 s46, s48, 0x16000
	s_addc_u32 s47, s49, 0
	v_fma_f32 v126, v126, v244, v22
	v_fma_f32 v127, v127, v244, v23
	v_fma_f32 v128, v128, v244, v24
	v_fma_f32 v129, v129, v244, v25
; DEV float silu_f(float x) { return x * __builtin_amdgcn_rcpf(1.f + __expf(-x)); }
; DEV float gelu_f(float x) { const float t = 1.5957691216f * (x + 0.044715f * x * x * x); return x * __builtin_amdgcn_rcpf(1.f + __expf(-t)); }
; DEV u32x4 pack8(const float (&f)[8]) { u32x4 w; w.x = cvt_pk_bf16(f[0], f[1]); w.y = cvt_pk_bf16(f[2], f[3]); w.z = cvt_pk_bf16(f[4], f[5]); w.w = cvt_pk_bf16(f[6], f[7]); return w; }
;     DEV void operator()(const f32x4 (&acc)[2][2][4][2], const Unit& u, int wr, int wc, int fr, int fq) const {
;     ...
;                         for (int j = 0; j < 4; ++j) { float x = acc[ai][bj][m][n][j] * rstd + sw[bj][n][j]; if (act == 1) x = silu_f(x); else if (act == 2) x = gelu_f(x); v[4 * n + j] = x; ss += x * x; }
;                     *(u32x4*)(Z + (size_t)row * ZW + col0 + bj * 128) = pack8(v);
	v_fma_f32 v122, v122, v244, v30
	v_fma_f32 v123, v123, v244, v31
	v_fma_f32 v124, v124, v244, v32
	v_fma_f32 v125, v125, v244, v33
	v_mul_f32_e32 v166, 0xbfb8aa3b, v126
	v_mul_f32_e32 v167, 0xbfb8aa3b, v127
	v_mul_f32_e32 v168, 0xbfb8aa3b, v128
	v_mul_f32_e32 v169, 0xbfb8aa3b, v129
	v_mul_f32_e32 v170, 0xbfb8aa3b, v122
	v_mul_f32_e32 v171, 0xbfb8aa3b, v123
	v_mul_f32_e32 v172, 0xbfb8aa3b, v124
	v_mul_f32_e32 v173, 0xbfb8aa3b, v125
	v_exp_f32_e32 v166, v166
	v_exp_f32_e32 v167, v167
	v_exp_f32_e32 v168, v168
	v_exp_f32_e32 v169, v169
	v_exp_f32_e32 v170, v170
	v_exp_f32_e32 v171, v171
	v_exp_f32_e32 v172, v172
	v_exp_f32_e32 v173, v173
	v_add_f32_e32 v166, 1.0, v166
	v_add_f32_e32 v167, 1.0, v167
	v_add_f32_e32 v168, 1.0, v168
	v_add_f32_e32 v169, 1.0, v169
	v_add_f32_e32 v170, 1.0, v170
	v_add_f32_e32 v171, 1.0, v171
	v_add_f32_e32 v172, 1.0, v172
	v_add_f32_e32 v173, 1.0, v173
	v_rcp_f32_e32 v166, v166
	v_rcp_f32_e32 v167, v167
	v_rcp_f32_e32 v168, v168
	v_rcp_f32_e32 v169, v169
	v_rcp_f32_e32 v170, v170
	v_rcp_f32_e32 v171, v171
	v_rcp_f32_e32 v172, v172
	v_rcp_f32_e32 v173, v173
	v_mul_f32_e32 v126, v126, v166
	v_mul_f32_e32 v127, v127, v167
	v_mul_f32_e32 v128, v128, v168
	v_mul_f32_e32 v129, v129, v169
	v_mul_f32_e32 v122, v122, v170
	v_mul_f32_e32 v123, v123, v171
	v_mul_f32_e32 v124, v124, v172
	v_mul_f32_e32 v125, v125, v173
	v_cvt_pk_bf16_f32 v166, v126, v127
	v_cvt_pk_bf16_f32 v167, v128, v129
	v_cvt_pk_bf16_f32 v168, v122, v123
	v_cvt_pk_bf16_f32 v169, v124, v125
	global_store_dwordx4 v178, v[166:169], s[46:47] offset:0
	s_nop 1
	v_fma_f32 v118, v118, v244, v38
	v_fma_f32 v119, v119, v244, v39
	v_fma_f32 v120, v120, v244, v40
	v_fma_f32 v121, v121, v244, v41
	v_fma_f32 v114, v114, v244, v46
	v_fma_f32 v115, v115, v244, v47
	v_fma_f32 v116, v116, v244, v48
	v_fma_f32 v117, v117, v244, v49
	v_mul_f32_e32 v166, 0xbfb8aa3b, v118
	v_mul_f32_e32 v167, 0xbfb8aa3b, v119
	v_mul_f32_e32 v168, 0xbfb8aa3b, v120
	v_mul_f32_e32 v169, 0xbfb8aa3b, v121
	v_mul_f32_e32 v170, 0xbfb8aa3b, v114
	v_mul_f32_e32 v171, 0xbfb8aa3b, v115
	v_mul_f32_e32 v172, 0xbfb8aa3b, v116
	v_mul_f32_e32 v173, 0xbfb8aa3b, v117
	v_exp_f32_e32 v166, v166
	v_exp_f32_e32 v167, v167
	v_exp_f32_e32 v168, v168
	v_exp_f32_e32 v169, v169
	v_exp_f32_e32 v170, v170
	v_exp_f32_e32 v171, v171
	v_exp_f32_e32 v172, v172
	v_exp_f32_e32 v173, v173
	v_add_f32_e32 v166, 1.0, v166
	v_add_f32_e32 v167, 1.0, v167
	v_add_f32_e32 v168, 1.0, v168
	v_add_f32_e32 v169, 1.0, v169
	v_add_f32_e32 v170, 1.0, v170
	v_add_f32_e32 v171, 1.0, v171
	v_add_f32_e32 v172, 1.0, v172
	v_add_f32_e32 v173, 1.0, v173
	v_rcp_f32_e32 v166, v166
	v_rcp_f32_e32 v167, v167
	v_rcp_f32_e32 v168, v168
	v_rcp_f32_e32 v169, v169
	v_rcp_f32_e32 v170, v170
	v_rcp_f32_e32 v171, v171
	v_rcp_f32_e32 v172, v172
	v_rcp_f32_e32 v173, v173
	v_mul_f32_e32 v118, v118, v166
	v_mul_f32_e32 v119, v119, v167
	v_mul_f32_e32 v120, v120, v168
	v_mul_f32_e32 v121, v121, v169
	v_mul_f32_e32 v114, v114, v170
	v_mul_f32_e32 v115, v115, v171
	v_mul_f32_e32 v116, v116, v172
	v_mul_f32_e32 v117, v117, v173
	v_cvt_pk_bf16_f32 v166, v118, v119
	v_cvt_pk_bf16_f32 v167, v120, v121
	v_cvt_pk_bf16_f32 v168, v114, v115
	v_cvt_pk_bf16_f32 v169, v116, v117
	global_store_dwordx4 v178, v[166:169], s[46:47] offset:256
	s_nop 1
	s_add_u32 s46, s48, 0x2c000
	s_addc_u32 s47, s49, 0
	v_fma_f32 v110, v110, v245, v22
	v_fma_f32 v111, v111, v245, v23
	v_fma_f32 v112, v112, v245, v24
	v_fma_f32 v113, v113, v245, v25
	v_fma_f32 v106, v106, v245, v30
	v_fma_f32 v107, v107, v245, v31
	v_fma_f32 v108, v108, v245, v32
	v_fma_f32 v109, v109, v245, v33
	v_mul_f32_e32 v166, 0xbfb8aa3b, v110
	v_mul_f32_e32 v167, 0xbfb8aa3b, v111
	v_mul_f32_e32 v168, 0xbfb8aa3b, v112
	v_mul_f32_e32 v169, 0xbfb8aa3b, v113
	v_mul_f32_e32 v170, 0xbfb8aa3b, v106
	v_mul_f32_e32 v171, 0xbfb8aa3b, v107
	v_mul_f32_e32 v172, 0xbfb8aa3b, v108
	v_mul_f32_e32 v173, 0xbfb8aa3b, v109
	v_exp_f32_e32 v166, v166
	v_exp_f32_e32 v167, v167
	v_exp_f32_e32 v168, v168
	v_exp_f32_e32 v169, v169
	v_exp_f32_e32 v170, v170
	v_exp_f32_e32 v171, v171
	v_exp_f32_e32 v172, v172
	v_exp_f32_e32 v173, v173
	v_add_f32_e32 v166, 1.0, v166
	v_add_f32_e32 v167, 1.0, v167
	v_add_f32_e32 v168, 1.0, v168
	v_add_f32_e32 v169, 1.0, v169
	v_add_f32_e32 v170, 1.0, v170
	v_add_f32_e32 v171, 1.0, v171
	v_add_f32_e32 v172, 1.0, v172
	v_add_f32_e32 v173, 1.0, v173
	v_rcp_f32_e32 v166, v166
	v_rcp_f32_e32 v167, v167
	v_rcp_f32_e32 v168, v168
	v_rcp_f32_e32 v169, v169
	v_rcp_f32_e32 v170, v170
	v_rcp_f32_e32 v171, v171
	v_rcp_f32_e32 v172, v172
	v_rcp_f32_e32 v173, v173
	v_mul_f32_e32 v110, v110, v166
	v_mul_f32_e32 v111, v111, v167
	v_mul_f32_e32 v112, v112, v168
	v_mul_f32_e32 v113, v113, v169
	v_mul_f32_e32 v106, v106, v170
	v_mul_f32_e32 v107, v107, v171
	v_mul_f32_e32 v108, v108, v172
	v_mul_f32_e32 v109, v109, v173
	v_cvt_pk_bf16_f32 v166, v110, v111
	v_cvt_pk_bf16_f32 v167, v112, v113
	v_cvt_pk_bf16_f32 v168, v106, v107
	v_cvt_pk_bf16_f32 v169, v108, v109
	global_store_dwordx4 v178, v[166:169], s[46:47] offset:0
	s_nop 1
	v_fma_f32 v102, v102, v245, v38
	v_fma_f32 v103, v103, v245, v39
	v_fma_f32 v104, v104, v245, v40
	v_fma_f32 v105, v105, v245, v41
	v_fma_f32 v98, v98, v245, v46
	v_fma_f32 v99, v99, v245, v47
	v_fma_f32 v100, v100, v245, v48
	v_fma_f32 v101, v101, v245, v49
	v_mul_f32_e32 v166, 0xbfb8aa3b, v102
	v_mul_f32_e32 v167, 0xbfb8aa3b, v103
	v_mul_f32_e32 v168, 0xbfb8aa3b, v104
	v_mul_f32_e32 v169, 0xbfb8aa3b, v105
	v_mul_f32_e32 v170, 0xbfb8aa3b, v98
	v_mul_f32_e32 v171, 0xbfb8aa3b, v99
	v_mul_f32_e32 v172, 0xbfb8aa3b, v100
	v_mul_f32_e32 v173, 0xbfb8aa3b, v101
	v_exp_f32_e32 v166, v166
	v_exp_f32_e32 v167, v167
; DEV float silu_f(float x) { return x * __builtin_amdgcn_rcpf(1.f + __expf(-x)); }
; DEV float gelu_f(float x) { const float t = 1.5957691216f * (x + 0.044715f * x * x * x); return x * __builtin_amdgcn_rcpf(1.f + __expf(-t)); }
; DEV u32x4 pack8(const float (&f)[8]) { u32x4 w; w.x = cvt_pk_bf16(f[0], f[1]); w.y = cvt_pk_bf16(f[2], f[3]); w.z = cvt_pk_bf16(f[4], f[5]); w.w = cvt_pk_bf16(f[6], f[7]); return w; }
;     DEV void operator()(const f32x4 (&acc)[2][2][4][2], const Unit& u, int wr, int wc, int fr, int fq) const {
;     ...
;                         for (int j = 0; j < 4; ++j) { float x = acc[ai][bj][m][n][j] * rstd + sw[bj][n][j]; if (act == 1) x = silu_f(x); else if (act == 2) x = gelu_f(x); v[4 * n + j] = x; ss += x * x; }
;                     *(u32x4*)(Z + (size_t)row * ZW + col0 + bj * 128) = pack8(v);
	v_exp_f32_e32 v168, v168
	v_exp_f32_e32 v169, v169
	v_exp_f32_e32 v170, v170
	v_exp_f32_e32 v171, v171
	v_exp_f32_e32 v172, v172
	v_exp_f32_e32 v173, v173
	v_add_f32_e32 v166, 1.0, v166
	v_add_f32_e32 v167, 1.0, v167
	v_add_f32_e32 v168, 1.0, v168
	v_add_f32_e32 v169, 1.0, v169
	v_add_f32_e32 v170, 1.0, v170
	v_add_f32_e32 v171, 1.0, v171
	v_add_f32_e32 v172, 1.0, v172
	v_add_f32_e32 v173, 1.0, v173
	v_rcp_f32_e32 v166, v166
	v_rcp_f32_e32 v167, v167
	v_rcp_f32_e32 v168, v168
	v_rcp_f32_e32 v169, v169
	v_rcp_f32_e32 v170, v170
	v_rcp_f32_e32 v171, v171
	v_rcp_f32_e32 v172, v172
	v_rcp_f32_e32 v173, v173
	v_mul_f32_e32 v102, v102, v166
	v_mul_f32_e32 v103, v103, v167
	v_mul_f32_e32 v104, v104, v168
	v_mul_f32_e32 v105, v105, v169
	v_mul_f32_e32 v98, v98, v170
	v_mul_f32_e32 v99, v99, v171
	v_mul_f32_e32 v100, v100, v172
	v_mul_f32_e32 v101, v101, v173
	v_cvt_pk_bf16_f32 v166, v102, v103
	v_cvt_pk_bf16_f32 v167, v104, v105
	v_cvt_pk_bf16_f32 v168, v98, v99
	v_cvt_pk_bf16_f32 v169, v100, v101
	global_store_dwordx4 v178, v[166:169], s[46:47] offset:256
	s_nop 1
	s_add_u32 s46, s48, 0x42000
	s_addc_u32 s47, s49, 0
	v_fma_f32 v94, v94, v246, v22
	v_fma_f32 v95, v95, v246, v23
	v_fma_f32 v96, v96, v246, v24
	v_fma_f32 v97, v97, v246, v25
	v_fma_f32 v90, v90, v246, v30
	v_fma_f32 v91, v91, v246, v31
	v_fma_f32 v92, v92, v246, v32
	v_fma_f32 v93, v93, v246, v33
	v_mul_f32_e32 v166, 0xbfb8aa3b, v94
	v_mul_f32_e32 v167, 0xbfb8aa3b, v95
	v_mul_f32_e32 v168, 0xbfb8aa3b, v96
	v_mul_f32_e32 v169, 0xbfb8aa3b, v97
	v_mul_f32_e32 v170, 0xbfb8aa3b, v90
	v_mul_f32_e32 v171, 0xbfb8aa3b, v91
	v_mul_f32_e32 v172, 0xbfb8aa3b, v92
	v_mul_f32_e32 v173, 0xbfb8aa3b, v93
	v_exp_f32_e32 v166, v166
	v_exp_f32_e32 v167, v167
	v_exp_f32_e32 v168, v168
	v_exp_f32_e32 v169, v169
	v_exp_f32_e32 v170, v170
	v_exp_f32_e32 v171, v171
	v_exp_f32_e32 v172, v172
	v_exp_f32_e32 v173, v173
	v_add_f32_e32 v166, 1.0, v166
	v_add_f32_e32 v167, 1.0, v167
	v_add_f32_e32 v168, 1.0, v168
	v_add_f32_e32 v169, 1.0, v169
	v_add_f32_e32 v170, 1.0, v170
	v_add_f32_e32 v171, 1.0, v171
	v_add_f32_e32 v172, 1.0, v172
	v_add_f32_e32 v173, 1.0, v173
	v_rcp_f32_e32 v166, v166
	v_rcp_f32_e32 v167, v167
	v_rcp_f32_e32 v168, v168
	v_rcp_f32_e32 v169, v169
	v_rcp_f32_e32 v170, v170
	v_rcp_f32_e32 v171, v171
	v_rcp_f32_e32 v172, v172
	v_rcp_f32_e32 v173, v173
	v_mul_f32_e32 v94, v94, v166
	v_mul_f32_e32 v95, v95, v167
	v_mul_f32_e32 v96, v96, v168
	v_mul_f32_e32 v97, v97, v169
	v_mul_f32_e32 v90, v90, v170
	v_mul_f32_e32 v91, v91, v171
	v_mul_f32_e32 v92, v92, v172
	v_mul_f32_e32 v93, v93, v173
	v_cvt_pk_bf16_f32 v166, v94, v95
	v_cvt_pk_bf16_f32 v167, v96, v97
	v_cvt_pk_bf16_f32 v168, v90, v91
	v_cvt_pk_bf16_f32 v169, v92, v93
	global_store_dwordx4 v178, v[166:169], s[46:47] offset:0
	s_nop 1
	v_fma_f32 v86, v86, v246, v38
	v_fma_f32 v87, v87, v246, v39
	v_fma_f32 v88, v88, v246, v40
	v_fma_f32 v89, v89, v246, v41
	v_fma_f32 v82, v82, v246, v46
	v_fma_f32 v83, v83, v246, v47
	v_fma_f32 v84, v84, v246, v48
	v_fma_f32 v85, v85, v246, v49
	v_mul_f32_e32 v166, 0xbfb8aa3b, v86
	v_mul_f32_e32 v167, 0xbfb8aa3b, v87
	v_mul_f32_e32 v168, 0xbfb8aa3b, v88
	v_mul_f32_e32 v169, 0xbfb8aa3b, v89
	v_mul_f32_e32 v170, 0xbfb8aa3b, v82
	v_mul_f32_e32 v171, 0xbfb8aa3b, v83
	v_mul_f32_e32 v172, 0xbfb8aa3b, v84
	v_mul_f32_e32 v173, 0xbfb8aa3b, v85
	v_exp_f32_e32 v166, v166
	v_exp_f32_e32 v167, v167
	v_exp_f32_e32 v168, v168
	v_exp_f32_e32 v169, v169
	v_exp_f32_e32 v170, v170
	v_exp_f32_e32 v171, v171
	v_exp_f32_e32 v172, v172
	v_exp_f32_e32 v173, v173
	v_add_f32_e32 v166, 1.0, v166
	v_add_f32_e32 v167, 1.0, v167
	v_add_f32_e32 v168, 1.0, v168
	v_add_f32_e32 v169, 1.0, v169
	v_add_f32_e32 v170, 1.0, v170
	v_add_f32_e32 v171, 1.0, v171
	v_add_f32_e32 v172, 1.0, v172
	v_add_f32_e32 v173, 1.0, v173
	v_rcp_f32_e32 v166, v166
	v_rcp_f32_e32 v167, v167
	v_rcp_f32_e32 v168, v168
	v_rcp_f32_e32 v169, v169
	v_rcp_f32_e32 v170, v170
	v_rcp_f32_e32 v171, v171
	v_rcp_f32_e32 v172, v172
	v_rcp_f32_e32 v173, v173
	v_mul_f32_e32 v86, v86, v166
	v_mul_f32_e32 v87, v87, v167
	v_mul_f32_e32 v88, v88, v168
	v_mul_f32_e32 v89, v89, v169
	v_mul_f32_e32 v82, v82, v170
	v_mul_f32_e32 v83, v83, v171
	v_mul_f32_e32 v84, v84, v172
	v_mul_f32_e32 v85, v85, v173
	v_cvt_pk_bf16_f32 v166, v86, v87
	v_cvt_pk_bf16_f32 v167, v88, v89
	v_cvt_pk_bf16_f32 v168, v82, v83
	v_cvt_pk_bf16_f32 v169, v84, v85
	global_store_dwordx4 v178, v[166:169], s[46:47] offset:256
	s_nop 1
	s_add_u32 s46, s48, 0xb0000
	s_addc_u32 s47, s49, 0
	v_fma_f32 v78, v78, v247, v22
	v_fma_f32 v79, v79, v247, v23
	v_fma_f32 v80, v80, v247, v24
	v_fma_f32 v81, v81, v247, v25
	v_fma_f32 v74, v74, v247, v30
	v_fma_f32 v75, v75, v247, v31
	v_fma_f32 v76, v76, v247, v32
	v_fma_f32 v77, v77, v247, v33
	v_mul_f32_e32 v166, 0xbfb8aa3b, v78
	v_mul_f32_e32 v167, 0xbfb8aa3b, v79
	v_mul_f32_e32 v168, 0xbfb8aa3b, v80
	v_mul_f32_e32 v169, 0xbfb8aa3b, v81
	v_mul_f32_e32 v170, 0xbfb8aa3b, v74
	v_mul_f32_e32 v171, 0xbfb8aa3b, v75
	v_mul_f32_e32 v172, 0xbfb8aa3b, v76
	v_mul_f32_e32 v173, 0xbfb8aa3b, v77
	v_exp_f32_e32 v166, v166
	v_exp_f32_e32 v167, v167
	v_exp_f32_e32 v168, v168
	v_exp_f32_e32 v169, v169
	v_exp_f32_e32 v170, v170
	v_exp_f32_e32 v171, v171
	v_exp_f32_e32 v172, v172
	v_exp_f32_e32 v173, v173
	v_add_f32_e32 v166, 1.0, v166
	v_add_f32_e32 v167, 1.0, v167
	v_add_f32_e32 v168, 1.0, v168
	v_add_f32_e32 v169, 1.0, v169
	v_add_f32_e32 v170, 1.0, v170
	v_add_f32_e32 v171, 1.0, v171
	v_add_f32_e32 v172, 1.0, v172
	v_add_f32_e32 v173, 1.0, v173
	v_rcp_f32_e32 v166, v166
	v_rcp_f32_e32 v167, v167
	v_rcp_f32_e32 v168, v168
	v_rcp_f32_e32 v169, v169
	v_rcp_f32_e32 v170, v170
	v_rcp_f32_e32 v171, v171
; DEV float silu_f(float x) { return x * __builtin_amdgcn_rcpf(1.f + __expf(-x)); }
; DEV float gelu_f(float x) { const float t = 1.5957691216f * (x + 0.044715f * x * x * x); return x * __builtin_amdgcn_rcpf(1.f + __expf(-t)); }
; DEV u32x4 pack8(const float (&f)[8]) { u32x4 w; w.x = cvt_pk_bf16(f[0], f[1]); w.y = cvt_pk_bf16(f[2], f[3]); w.z = cvt_pk_bf16(f[4], f[5]); w.w = cvt_pk_bf16(f[6], f[7]); return w; }
;     DEV void operator()(const f32x4 (&acc)[2][2][4][2], const Unit& u, int wr, int wc, int fr, int fq) const {
;     ...
;                         for (int j = 0; j < 4; ++j) { float x = acc[ai][bj][m][n][j] * rstd + sw[bj][n][j]; if (act == 1) x = silu_f(x); else if (act == 2) x = gelu_f(x); v[4 * n + j] = x; ss += x * x; }
;                     *(u32x4*)(Z + (size_t)row * ZW + col0 + bj * 128) = pack8(v);
	v_rcp_f32_e32 v172, v172
	v_rcp_f32_e32 v173, v173
	v_mul_f32_e32 v78, v78, v166
	v_mul_f32_e32 v79, v79, v167
	v_mul_f32_e32 v80, v80, v168
	v_mul_f32_e32 v81, v81, v169
	v_mul_f32_e32 v74, v74, v170
	v_mul_f32_e32 v75, v75, v171
	v_mul_f32_e32 v76, v76, v172
	v_mul_f32_e32 v77, v77, v173
	v_cvt_pk_bf16_f32 v166, v78, v79
	v_cvt_pk_bf16_f32 v167, v80, v81
	v_cvt_pk_bf16_f32 v168, v74, v75
	v_cvt_pk_bf16_f32 v169, v76, v77
	global_store_dwordx4 v178, v[166:169], s[46:47] offset:0
	s_nop 1
	v_fma_f32 v70, v70, v247, v38
	v_fma_f32 v71, v71, v247, v39
	v_fma_f32 v72, v72, v247, v40
	v_fma_f32 v73, v73, v247, v41
	v_fma_f32 v66, v66, v247, v46
	v_fma_f32 v67, v67, v247, v47
	v_fma_f32 v68, v68, v247, v48
	v_fma_f32 v69, v69, v247, v49
	v_mul_f32_e32 v166, 0xbfb8aa3b, v70
	v_mul_f32_e32 v167, 0xbfb8aa3b, v71
	v_mul_f32_e32 v168, 0xbfb8aa3b, v72
	v_mul_f32_e32 v169, 0xbfb8aa3b, v73
	v_mul_f32_e32 v170, 0xbfb8aa3b, v66
	v_mul_f32_e32 v171, 0xbfb8aa3b, v67
	v_mul_f32_e32 v172, 0xbfb8aa3b, v68
	v_mul_f32_e32 v173, 0xbfb8aa3b, v69
	v_exp_f32_e32 v166, v166
	v_exp_f32_e32 v167, v167
	v_exp_f32_e32 v168, v168
	v_exp_f32_e32 v169, v169
	v_exp_f32_e32 v170, v170
	v_exp_f32_e32 v171, v171
	v_exp_f32_e32 v172, v172
	v_exp_f32_e32 v173, v173
	v_add_f32_e32 v166, 1.0, v166
	v_add_f32_e32 v167, 1.0, v167
	v_add_f32_e32 v168, 1.0, v168
	v_add_f32_e32 v169, 1.0, v169
	v_add_f32_e32 v170, 1.0, v170
	v_add_f32_e32 v171, 1.0, v171
	v_add_f32_e32 v172, 1.0, v172
	v_add_f32_e32 v173, 1.0, v173
	v_rcp_f32_e32 v166, v166
	v_rcp_f32_e32 v167, v167
	v_rcp_f32_e32 v168, v168
	v_rcp_f32_e32 v169, v169
	v_rcp_f32_e32 v170, v170
	v_rcp_f32_e32 v171, v171
	v_rcp_f32_e32 v172, v172
	v_rcp_f32_e32 v173, v173
	v_mul_f32_e32 v70, v70, v166
	v_mul_f32_e32 v71, v71, v167
	v_mul_f32_e32 v72, v72, v168
	v_mul_f32_e32 v73, v73, v169
	v_mul_f32_e32 v66, v66, v170
	v_mul_f32_e32 v67, v67, v171
	v_mul_f32_e32 v68, v68, v172
	v_mul_f32_e32 v69, v69, v173
	v_cvt_pk_bf16_f32 v166, v70, v71
	v_cvt_pk_bf16_f32 v167, v72, v73
	v_cvt_pk_bf16_f32 v168, v66, v67
	v_cvt_pk_bf16_f32 v169, v68, v69
	global_store_dwordx4 v178, v[166:169], s[46:47] offset:256
	s_nop 1
	s_add_u32 s46, s48, 0xc6000
	s_addc_u32 s47, s49, 0
	v_fma_f32 v62, v62, v248, v22
	v_fma_f32 v63, v63, v248, v23
	v_fma_f32 v64, v64, v248, v24
	v_fma_f32 v65, v65, v248, v25
	v_fma_f32 v58, v58, v248, v30
	v_fma_f32 v59, v59, v248, v31
	v_fma_f32 v60, v60, v248, v32
	v_fma_f32 v61, v61, v248, v33
	v_mul_f32_e32 v166, 0xbfb8aa3b, v62
	v_mul_f32_e32 v167, 0xbfb8aa3b, v63
	v_mul_f32_e32 v168, 0xbfb8aa3b, v64
	v_mul_f32_e32 v169, 0xbfb8aa3b, v65
	v_mul_f32_e32 v170, 0xbfb8aa3b, v58
	v_mul_f32_e32 v171, 0xbfb8aa3b, v59
	v_mul_f32_e32 v172, 0xbfb8aa3b, v60
	v_mul_f32_e32 v173, 0xbfb8aa3b, v61
	v_exp_f32_e32 v166, v166
	v_exp_f32_e32 v167, v167
	v_exp_f32_e32 v168, v168
	v_exp_f32_e32 v169, v169
	v_exp_f32_e32 v170, v170
	v_exp_f32_e32 v171, v171
	v_exp_f32_e32 v172, v172
	v_exp_f32_e32 v173, v173
	v_add_f32_e32 v166, 1.0, v166
	v_add_f32_e32 v167, 1.0, v167
	v_add_f32_e32 v168, 1.0, v168
	v_add_f32_e32 v169, 1.0, v169
	v_add_f32_e32 v170, 1.0, v170
	v_add_f32_e32 v171, 1.0, v171
	v_add_f32_e32 v172, 1.0, v172
	v_add_f32_e32 v173, 1.0, v173
	v_rcp_f32_e32 v166, v166
	v_rcp_f32_e32 v167, v167
	v_rcp_f32_e32 v168, v168
	v_rcp_f32_e32 v169, v169
	v_rcp_f32_e32 v170, v170
	v_rcp_f32_e32 v171, v171
	v_rcp_f32_e32 v172, v172
	v_rcp_f32_e32 v173, v173
	v_mul_f32_e32 v62, v62, v166
	v_mul_f32_e32 v63, v63, v167
	v_mul_f32_e32 v64, v64, v168
	v_mul_f32_e32 v65, v65, v169
	v_mul_f32_e32 v58, v58, v170
	v_mul_f32_e32 v59, v59, v171
	v_mul_f32_e32 v60, v60, v172
	v_mul_f32_e32 v61, v61, v173
	v_cvt_pk_bf16_f32 v166, v62, v63
	v_cvt_pk_bf16_f32 v167, v64, v65
	v_cvt_pk_bf16_f32 v168, v58, v59
	v_cvt_pk_bf16_f32 v169, v60, v61
	global_store_dwordx4 v178, v[166:169], s[46:47] offset:0
	s_nop 1
	v_fma_f32 v54, v54, v248, v38
	v_fma_f32 v55, v55, v248, v39
	v_fma_f32 v56, v56, v248, v40
	v_fma_f32 v57, v57, v248, v41
	v_fma_f32 v50, v50, v248, v46
	v_fma_f32 v51, v51, v248, v47
	v_fma_f32 v52, v52, v248, v48
	v_fma_f32 v53, v53, v248, v49
	v_mul_f32_e32 v166, 0xbfb8aa3b, v54
	v_mul_f32_e32 v167, 0xbfb8aa3b, v55
	v_mul_f32_e32 v168, 0xbfb8aa3b, v56
	v_mul_f32_e32 v169, 0xbfb8aa3b, v57
	v_mul_f32_e32 v170, 0xbfb8aa3b, v50
	v_mul_f32_e32 v171, 0xbfb8aa3b, v51
	v_mul_f32_e32 v172, 0xbfb8aa3b, v52
	v_mul_f32_e32 v173, 0xbfb8aa3b, v53
	v_exp_f32_e32 v166, v166
	v_exp_f32_e32 v167, v167
	v_exp_f32_e32 v168, v168
	v_exp_f32_e32 v169, v169
	v_exp_f32_e32 v170, v170
	v_exp_f32_e32 v171, v171
	v_exp_f32_e32 v172, v172
	v_exp_f32_e32 v173, v173
	v_add_f32_e32 v166, 1.0, v166
	v_add_f32_e32 v167, 1.0, v167
	v_add_f32_e32 v168, 1.0, v168
	v_add_f32_e32 v169, 1.0, v169
	v_add_f32_e32 v170, 1.0, v170
	v_add_f32_e32 v171, 1.0, v171
	v_add_f32_e32 v172, 1.0, v172
	v_add_f32_e32 v173, 1.0, v173
	v_rcp_f32_e32 v166, v166
	v_rcp_f32_e32 v167, v167
	v_rcp_f32_e32 v168, v168
	v_rcp_f32_e32 v169, v169
	v_rcp_f32_e32 v170, v170
	v_rcp_f32_e32 v171, v171
	v_rcp_f32_e32 v172, v172
	v_rcp_f32_e32 v173, v173
	v_mul_f32_e32 v54, v54, v166
	v_mul_f32_e32 v55, v55, v167
	v_mul_f32_e32 v56, v56, v168
	v_mul_f32_e32 v57, v57, v169
	v_mul_f32_e32 v50, v50, v170
	v_mul_f32_e32 v51, v51, v171
	v_mul_f32_e32 v52, v52, v172
	v_mul_f32_e32 v53, v53, v173
	v_cvt_pk_bf16_f32 v166, v54, v55
	v_cvt_pk_bf16_f32 v167, v56, v57
	v_cvt_pk_bf16_f32 v168, v50, v51
	v_cvt_pk_bf16_f32 v169, v52, v53
	global_store_dwordx4 v178, v[166:169], s[46:47] offset:256
	s_nop 1
	s_add_u32 s46, s48, 0xdc000
	s_addc_u32 s47, s49, 0
	v_fma_f32 v42, v42, v249, v22
	v_fma_f32 v43, v43, v249, v23
	v_fma_f32 v44, v44, v249, v24
; DEV float silu_f(float x) { return x * __builtin_amdgcn_rcpf(1.f + __expf(-x)); }
; DEV float gelu_f(float x) { const float t = 1.5957691216f * (x + 0.044715f * x * x * x); return x * __builtin_amdgcn_rcpf(1.f + __expf(-t)); }
; DEV u32x4 pack8(const float (&f)[8]) { u32x4 w; w.x = cvt_pk_bf16(f[0], f[1]); w.y = cvt_pk_bf16(f[2], f[3]); w.z = cvt_pk_bf16(f[4], f[5]); w.w = cvt_pk_bf16(f[6], f[7]); return w; }
;     DEV void operator()(const f32x4 (&acc)[2][2][4][2], const Unit& u, int wr, int wc, int fr, int fq) const {
;     ...
;                         for (int j = 0; j < 4; ++j) { float x = acc[ai][bj][m][n][j] * rstd + sw[bj][n][j]; if (act == 1) x = silu_f(x); else if (act == 2) x = gelu_f(x); v[4 * n + j] = x; ss += x * x; }
;                     *(u32x4*)(Z + (size_t)row * ZW + col0 + bj * 128) = pack8(v);
	v_fma_f32 v45, v45, v249, v25
	v_fma_f32 v34, v34, v249, v30
	v_fma_f32 v35, v35, v249, v31
	v_fma_f32 v36, v36, v249, v32
	v_fma_f32 v37, v37, v249, v33
	v_mul_f32_e32 v166, 0xbfb8aa3b, v42
	v_mul_f32_e32 v167, 0xbfb8aa3b, v43
	v_mul_f32_e32 v168, 0xbfb8aa3b, v44
	v_mul_f32_e32 v169, 0xbfb8aa3b, v45
	v_mul_f32_e32 v170, 0xbfb8aa3b, v34
	v_mul_f32_e32 v171, 0xbfb8aa3b, v35
	v_mul_f32_e32 v172, 0xbfb8aa3b, v36
	v_mul_f32_e32 v173, 0xbfb8aa3b, v37
	v_exp_f32_e32 v166, v166
	v_exp_f32_e32 v167, v167
	v_exp_f32_e32 v168, v168
	v_exp_f32_e32 v169, v169
	v_exp_f32_e32 v170, v170
	v_exp_f32_e32 v171, v171
	v_exp_f32_e32 v172, v172
	v_exp_f32_e32 v173, v173
	v_add_f32_e32 v166, 1.0, v166
	v_add_f32_e32 v167, 1.0, v167
	v_add_f32_e32 v168, 1.0, v168
	v_add_f32_e32 v169, 1.0, v169
	v_add_f32_e32 v170, 1.0, v170
	v_add_f32_e32 v171, 1.0, v171
	v_add_f32_e32 v172, 1.0, v172
	v_add_f32_e32 v173, 1.0, v173
	v_rcp_f32_e32 v166, v166
	v_rcp_f32_e32 v167, v167
	v_rcp_f32_e32 v168, v168
	v_rcp_f32_e32 v169, v169
	v_rcp_f32_e32 v170, v170
	v_rcp_f32_e32 v171, v171
	v_rcp_f32_e32 v172, v172
	v_rcp_f32_e32 v173, v173
	v_mul_f32_e32 v42, v42, v166
	v_mul_f32_e32 v43, v43, v167
	v_mul_f32_e32 v44, v44, v168
	v_mul_f32_e32 v45, v45, v169
	v_mul_f32_e32 v34, v34, v170
	v_mul_f32_e32 v35, v35, v171
	v_mul_f32_e32 v36, v36, v172
	v_mul_f32_e32 v37, v37, v173
	v_cvt_pk_bf16_f32 v166, v42, v43
	v_cvt_pk_bf16_f32 v167, v44, v45
	v_cvt_pk_bf16_f32 v168, v34, v35
	v_cvt_pk_bf16_f32 v169, v36, v37
	global_store_dwordx4 v178, v[166:169], s[46:47] offset:0
	s_nop 1
	v_fma_f32 v26, v26, v249, v38
	v_fma_f32 v27, v27, v249, v39
	v_fma_f32 v28, v28, v249, v40
	v_fma_f32 v29, v29, v249, v41
	v_fma_f32 v18, v18, v249, v46
	v_fma_f32 v19, v19, v249, v47
	v_fma_f32 v20, v20, v249, v48
	v_fma_f32 v21, v21, v249, v49
	v_mul_f32_e32 v166, 0xbfb8aa3b, v26
	v_mul_f32_e32 v167, 0xbfb8aa3b, v27
	v_mul_f32_e32 v168, 0xbfb8aa3b, v28
	v_mul_f32_e32 v169, 0xbfb8aa3b, v29
	v_mul_f32_e32 v170, 0xbfb8aa3b, v18
	v_mul_f32_e32 v171, 0xbfb8aa3b, v19
	v_mul_f32_e32 v172, 0xbfb8aa3b, v20
	v_mul_f32_e32 v173, 0xbfb8aa3b, v21
	v_exp_f32_e32 v166, v166
	v_exp_f32_e32 v167, v167
	v_exp_f32_e32 v168, v168
	v_exp_f32_e32 v169, v169
	v_exp_f32_e32 v170, v170
	v_exp_f32_e32 v171, v171
	v_exp_f32_e32 v172, v172
	v_exp_f32_e32 v173, v173
	v_add_f32_e32 v166, 1.0, v166
	v_add_f32_e32 v167, 1.0, v167
	v_add_f32_e32 v168, 1.0, v168
	v_add_f32_e32 v169, 1.0, v169
	v_add_f32_e32 v170, 1.0, v170
	v_add_f32_e32 v171, 1.0, v171
	v_add_f32_e32 v172, 1.0, v172
	v_add_f32_e32 v173, 1.0, v173
	v_rcp_f32_e32 v166, v166
	v_rcp_f32_e32 v167, v167
	v_rcp_f32_e32 v168, v168
	v_rcp_f32_e32 v169, v169
	v_rcp_f32_e32 v170, v170
	v_rcp_f32_e32 v171, v171
	v_rcp_f32_e32 v172, v172
	v_rcp_f32_e32 v173, v173
	v_mul_f32_e32 v26, v26, v166
	v_mul_f32_e32 v27, v27, v167
	v_mul_f32_e32 v28, v28, v168
	v_mul_f32_e32 v29, v29, v169
	v_mul_f32_e32 v18, v18, v170
	v_mul_f32_e32 v19, v19, v171
	v_mul_f32_e32 v20, v20, v172
	v_mul_f32_e32 v21, v21, v173
	v_cvt_pk_bf16_f32 v166, v26, v27
	v_cvt_pk_bf16_f32 v167, v28, v29
	v_cvt_pk_bf16_f32 v168, v18, v19
	v_cvt_pk_bf16_f32 v169, v20, v21
	global_store_dwordx4 v178, v[166:169], s[46:47] offset:256
	s_nop 1
	s_add_u32 s46, s48, 0xf2000
	s_addc_u32 s47, s49, 0
	v_fma_f32 v14, v14, v250, v22
	v_fma_f32 v15, v15, v250, v23
	v_fma_f32 v16, v16, v250, v24
	v_fma_f32 v17, v17, v250, v25
	v_fma_f32 v10, v10, v250, v30
	v_fma_f32 v11, v11, v250, v31
	v_fma_f32 v12, v12, v250, v32
	v_fma_f32 v13, v13, v250, v33
	v_mul_f32_e32 v166, 0xbfb8aa3b, v14
	v_mul_f32_e32 v167, 0xbfb8aa3b, v15
	v_mul_f32_e32 v168, 0xbfb8aa3b, v16
	v_mul_f32_e32 v169, 0xbfb8aa3b, v17
	v_mul_f32_e32 v170, 0xbfb8aa3b, v10
	v_mul_f32_e32 v171, 0xbfb8aa3b, v11
	v_mul_f32_e32 v172, 0xbfb8aa3b, v12
	v_mul_f32_e32 v173, 0xbfb8aa3b, v13
	v_exp_f32_e32 v166, v166
	v_exp_f32_e32 v167, v167
	v_exp_f32_e32 v168, v168
	v_exp_f32_e32 v169, v169
	v_exp_f32_e32 v170, v170
	v_exp_f32_e32 v171, v171
	v_exp_f32_e32 v172, v172
	v_exp_f32_e32 v173, v173
	v_add_f32_e32 v166, 1.0, v166
	v_add_f32_e32 v167, 1.0, v167
	v_add_f32_e32 v168, 1.0, v168
	v_add_f32_e32 v169, 1.0, v169
	v_add_f32_e32 v170, 1.0, v170
	v_add_f32_e32 v171, 1.0, v171
	v_add_f32_e32 v172, 1.0, v172
	v_add_f32_e32 v173, 1.0, v173
	v_rcp_f32_e32 v166, v166
	v_rcp_f32_e32 v167, v167
	v_rcp_f32_e32 v168, v168
	v_rcp_f32_e32 v169, v169
	v_rcp_f32_e32 v170, v170
	v_rcp_f32_e32 v171, v171
	v_rcp_f32_e32 v172, v172
	v_rcp_f32_e32 v173, v173
	v_mul_f32_e32 v14, v14, v166
	v_mul_f32_e32 v15, v15, v167
	v_mul_f32_e32 v16, v16, v168
	v_mul_f32_e32 v17, v17, v169
	v_mul_f32_e32 v10, v10, v170
	v_mul_f32_e32 v11, v11, v171
	v_mul_f32_e32 v12, v12, v172
	v_mul_f32_e32 v13, v13, v173
	v_cvt_pk_bf16_f32 v166, v14, v15
	v_cvt_pk_bf16_f32 v167, v16, v17
	v_cvt_pk_bf16_f32 v168, v10, v11
	v_cvt_pk_bf16_f32 v169, v12, v13
	global_store_dwordx4 v178, v[166:169], s[46:47] offset:0
	s_nop 1
	v_fma_f32 v6, v6, v250, v38
	v_fma_f32 v7, v7, v250, v39
	v_fma_f32 v8, v8, v250, v40
	v_fma_f32 v9, v9, v250, v41
	v_fma_f32 v2, v2, v250, v46
	v_fma_f32 v3, v3, v250, v47
	v_fma_f32 v4, v4, v250, v48
	v_fma_f32 v5, v5, v250, v49
	v_mul_f32_e32 v166, 0xbfb8aa3b, v6
	v_mul_f32_e32 v167, 0xbfb8aa3b, v7
	v_mul_f32_e32 v168, 0xbfb8aa3b, v8
	v_mul_f32_e32 v169, 0xbfb8aa3b, v9
	v_mul_f32_e32 v170, 0xbfb8aa3b, v2
	v_mul_f32_e32 v171, 0xbfb8aa3b, v3
	v_mul_f32_e32 v172, 0xbfb8aa3b, v4
	v_mul_f32_e32 v173, 0xbfb8aa3b, v5
	v_exp_f32_e32 v166, v166
	v_exp_f32_e32 v167, v167
	v_exp_f32_e32 v168, v168
	v_exp_f32_e32 v169, v169
	v_exp_f32_e32 v170, v170
	v_exp_f32_e32 v171, v171
	v_exp_f32_e32 v172, v172
	v_exp_f32_e32 v173, v173
	v_add_f32_e32 v166, 1.0, v166
	v_add_f32_e32 v167, 1.0, v167
	v_add_f32_e32 v168, 1.0, v168
	v_add_f32_e32 v169, 1.0, v169
	v_add_f32_e32 v170, 1.0, v170
	v_add_f32_e32 v171, 1.0, v171
	v_add_f32_e32 v172, 1.0, v172
	v_add_f32_e32 v173, 1.0, v173
	v_rcp_f32_e32 v166, v166
	v_rcp_f32_e32 v167, v167
	v_rcp_f32_e32 v168, v168
	v_rcp_f32_e32 v169, v169
	v_rcp_f32_e32 v170, v170
	v_rcp_f32_e32 v171, v171
	v_rcp_f32_e32 v172, v172
	v_rcp_f32_e32 v173, v173
	v_mul_f32_e32 v6, v6, v166
	v_mul_f32_e32 v7, v7, v167
	v_mul_f32_e32 v8, v8, v168
	v_mul_f32_e32 v9, v9, v169
	v_mul_f32_e32 v2, v2, v170
	v_mul_f32_e32 v3, v3, v171
	v_mul_f32_e32 v4, v4, v172
	v_mul_f32_e32 v5, v5, v173
	v_cvt_pk_bf16_f32 v166, v6, v7
	v_cvt_pk_bf16_f32 v167, v8, v9
	v_cvt_pk_bf16_f32 v168, v2, v3
	v_cvt_pk_bf16_f32 v169, v4, v5
	global_store_dwordx4 v178, v[166:169], s[46:47] offset:256
	s_nop 1
	s_branch .Lp5_done
; DEV float silu_f(float x) { return x * __builtin_amdgcn_rcpf(1.f + __expf(-x)); }
; DEV float gelu_f(float x) { const float t = 1.5957691216f * (x + 0.044715f * x * x * x); return x * __builtin_amdgcn_rcpf(1.f + __expf(-t)); }
; DEV u32x4 pack8(const float (&f)[8]) { u32x4 w; w.x = cvt_pk_bf16(f[0], f[1]); w.y = cvt_pk_bf16(f[2], f[3]); w.z = cvt_pk_bf16(f[4], f[5]); w.w = cvt_pk_bf16(f[6], f[7]); return w; }
;     DEV void operator()(const f32x4 (&acc)[2][2][4][2], const Unit& u, int wr, int wc, int fr, int fq) const {
;     ...
;                         for (int j = 0; j < 4; ++j) { float x = acc[ai][bj][m][n][j] * rstd + sw[bj][n][j]; if (act == 1) x = silu_f(x); else if (act == 2) x = gelu_f(x); v[4 * n + j] = x; ss += x * x; }
;                     *(u32x4*)(Z + (size_t)row * ZW + col0 + bj * 128) = pack8(v);
.Lp5_act0:
	v_fma_f32 v142, v142, v243, v22
	v_fma_f32 v143, v143, v243, v23
	v_fma_f32 v144, v144, v243, v24
	v_fma_f32 v145, v145, v243, v25
	v_fma_f32 v138, v138, v243, v30
	v_fma_f32 v139, v139, v243, v31
	v_fma_f32 v140, v140, v243, v32
	v_fma_f32 v141, v141, v243, v33
	v_cvt_pk_bf16_f32 v166, v142, v143
	v_cvt_pk_bf16_f32 v167, v144, v145
	v_cvt_pk_bf16_f32 v168, v138, v139
	v_cvt_pk_bf16_f32 v169, v140, v141
	global_store_dwordx4 v178, v[166:169], s[48:49] offset:0
	s_nop 1
	v_fma_f32 v134, v134, v243, v38
	v_fma_f32 v135, v135, v243, v39
	v_fma_f32 v136, v136, v243, v40
	v_fma_f32 v137, v137, v243, v41
	v_fma_f32 v130, v130, v243, v46
	v_fma_f32 v131, v131, v243, v47
	v_fma_f32 v132, v132, v243, v48
	v_fma_f32 v133, v133, v243, v49
	v_cvt_pk_bf16_f32 v166, v134, v135
	v_cvt_pk_bf16_f32 v167, v136, v137
	v_cvt_pk_bf16_f32 v168, v130, v131
	v_cvt_pk_bf16_f32 v169, v132, v133
	global_store_dwordx4 v178, v[166:169], s[48:49] offset:256
	s_nop 1
	s_add_u32 s46, s48, 0x16000
	s_addc_u32 s47, s49, 0
	v_fma_f32 v126, v126, v244, v22
	v_fma_f32 v127, v127, v244, v23
	v_fma_f32 v128, v128, v244, v24
	v_fma_f32 v129, v129, v244, v25
	v_fma_f32 v122, v122, v244, v30
	v_fma_f32 v123, v123, v244, v31
	v_fma_f32 v124, v124, v244, v32
	v_fma_f32 v125, v125, v244, v33
	v_cvt_pk_bf16_f32 v166, v126, v127
	v_cvt_pk_bf16_f32 v167, v128, v129
	v_cvt_pk_bf16_f32 v168, v122, v123
	v_cvt_pk_bf16_f32 v169, v124, v125
	global_store_dwordx4 v178, v[166:169], s[46:47] offset:0
	s_nop 1
	v_fma_f32 v118, v118, v244, v38
	v_fma_f32 v119, v119, v244, v39
	v_fma_f32 v120, v120, v244, v40
	v_fma_f32 v121, v121, v244, v41
	v_fma_f32 v114, v114, v244, v46
	v_fma_f32 v115, v115, v244, v47
	v_fma_f32 v116, v116, v244, v48
	v_fma_f32 v117, v117, v244, v49
	v_cvt_pk_bf16_f32 v166, v118, v119
	v_cvt_pk_bf16_f32 v167, v120, v121
	v_cvt_pk_bf16_f32 v168, v114, v115
	v_cvt_pk_bf16_f32 v169, v116, v117
	global_store_dwordx4 v178, v[166:169], s[46:47] offset:256
	s_nop 1
	s_add_u32 s46, s48, 0x2c000
	s_addc_u32 s47, s49, 0
	v_fma_f32 v110, v110, v245, v22
	v_fma_f32 v111, v111, v245, v23
	v_fma_f32 v112, v112, v245, v24
	v_fma_f32 v113, v113, v245, v25
	v_fma_f32 v106, v106, v245, v30
	v_fma_f32 v107, v107, v245, v31
	v_fma_f32 v108, v108, v245, v32
	v_fma_f32 v109, v109, v245, v33
	v_cvt_pk_bf16_f32 v166, v110, v111
	v_cvt_pk_bf16_f32 v167, v112, v113
	v_cvt_pk_bf16_f32 v168, v106, v107
	v_cvt_pk_bf16_f32 v169, v108, v109
	global_store_dwordx4 v178, v[166:169], s[46:47] offset:0
	s_nop 1
	v_fma_f32 v102, v102, v245, v38
	v_fma_f32 v103, v103, v245, v39
	v_fma_f32 v104, v104, v245, v40
	v_fma_f32 v105, v105, v245, v41
	v_fma_f32 v98, v98, v245, v46
	v_fma_f32 v99, v99, v245, v47
	v_fma_f32 v100, v100, v245, v48
	v_fma_f32 v101, v101, v245, v49
	v_cvt_pk_bf16_f32 v166, v102, v103
	v_cvt_pk_bf16_f32 v167, v104, v105
	v_cvt_pk_bf16_f32 v168, v98, v99
	v_cvt_pk_bf16_f32 v169, v100, v101
	global_store_dwordx4 v178, v[166:169], s[46:47] offset:256
	s_nop 1
	s_add_u32 s46, s48, 0x42000
	s_addc_u32 s47, s49, 0
	v_fma_f32 v94, v94, v246, v22
	v_fma_f32 v95, v95, v246, v23
	v_fma_f32 v96, v96, v246, v24
	v_fma_f32 v97, v97, v246, v25
	v_fma_f32 v90, v90, v246, v30
	v_fma_f32 v91, v91, v246, v31
	v_fma_f32 v92, v92, v246, v32
	v_fma_f32 v93, v93, v246, v33
	v_cvt_pk_bf16_f32 v166, v94, v95
	v_cvt_pk_bf16_f32 v167, v96, v97
	v_cvt_pk_bf16_f32 v168, v90, v91
	v_cvt_pk_bf16_f32 v169, v92, v93
	global_store_dwordx4 v178, v[166:169], s[46:47] offset:0
	s_nop 1
	v_fma_f32 v86, v86, v246, v38
	v_fma_f32 v87, v87, v246, v39
	v_fma_f32 v88, v88, v246, v40
	v_fma_f32 v89, v89, v246, v41
	v_fma_f32 v82, v82, v246, v46
	v_fma_f32 v83, v83, v246, v47
	v_fma_f32 v84, v84, v246, v48
	v_fma_f32 v85, v85, v246, v49
	v_cvt_pk_bf16_f32 v166, v86, v87
	v_cvt_pk_bf16_f32 v167, v88, v89
	v_cvt_pk_bf16_f32 v168, v82, v83
	v_cvt_pk_bf16_f32 v169, v84, v85
	global_store_dwordx4 v178, v[166:169], s[46:47] offset:256
	s_nop 1
	s_add_u32 s46, s48, 0xb0000
; #define PG8_BAR __builtin_amdgcn_s_barrier()
; DEV float silu_f(float x) { return x * __builtin_amdgcn_rcpf(1.f + __expf(-x)); }
; DEV float gelu_f(float x) { const float t = 1.5957691216f * (x + 0.044715f * x * x * x); return x * __builtin_amdgcn_rcpf(1.f + __expf(-t)); }
; DEV u32x4 pack8(const float (&f)[8]) { u32x4 w; w.x = cvt_pk_bf16(f[0], f[1]); w.y = cvt_pk_bf16(f[2], f[3]); w.z = cvt_pk_bf16(f[4], f[5]); w.w = cvt_pk_bf16(f[6], f[7]); return w; }
; template <class Epi, class Sched, bool ALIGN_EPI = false, bool SP2 = false>
; __device__ __forceinline__ void gemm_phase(PG8_LAS unsigned char* lds, const Gemm g, const Sched& S, const Epi& E) {
;     ...
;         if constexpr (ALIGN_EPI) { if (wr == 1) PG8_BAR; }
;     DEV void operator()(const f32x4 (&acc)[2][2][4][2], const Unit& u, int wr, int wc, int fr, int fq) const {
;     ...
;                         for (int j = 0; j < 4; ++j) { float x = acc[ai][bj][m][n][j] * rstd + sw[bj][n][j]; if (act == 1) x = silu_f(x); else if (act == 2) x = gelu_f(x); v[4 * n + j] = x; ss += x * x; }
;                     *(u32x4*)(Z + (size_t)row * ZW + col0 + bj * 128) = pack8(v);
	s_addc_u32 s47, s49, 0
	v_fma_f32 v78, v78, v247, v22
	v_fma_f32 v79, v79, v247, v23
	v_fma_f32 v80, v80, v247, v24
	v_fma_f32 v81, v81, v247, v25
	v_fma_f32 v74, v74, v247, v30
	v_fma_f32 v75, v75, v247, v31
	v_fma_f32 v76, v76, v247, v32
	v_fma_f32 v77, v77, v247, v33
	v_cvt_pk_bf16_f32 v166, v78, v79
	v_cvt_pk_bf16_f32 v167, v80, v81
	v_cvt_pk_bf16_f32 v168, v74, v75
	v_cvt_pk_bf16_f32 v169, v76, v77
	global_store_dwordx4 v178, v[166:169], s[46:47] offset:0
	s_nop 1
	v_fma_f32 v70, v70, v247, v38
	v_fma_f32 v71, v71, v247, v39
	v_fma_f32 v72, v72, v247, v40
	v_fma_f32 v73, v73, v247, v41
	v_fma_f32 v66, v66, v247, v46
	v_fma_f32 v67, v67, v247, v47
	v_fma_f32 v68, v68, v247, v48
	v_fma_f32 v69, v69, v247, v49
	v_cvt_pk_bf16_f32 v166, v70, v71
	v_cvt_pk_bf16_f32 v167, v72, v73
	v_cvt_pk_bf16_f32 v168, v66, v67
	v_cvt_pk_bf16_f32 v169, v68, v69
	global_store_dwordx4 v178, v[166:169], s[46:47] offset:256
	s_nop 1
	s_add_u32 s46, s48, 0xc6000
	s_addc_u32 s47, s49, 0
	v_fma_f32 v62, v62, v248, v22
	v_fma_f32 v63, v63, v248, v23
	v_fma_f32 v64, v64, v248, v24
	v_fma_f32 v65, v65, v248, v25
	v_fma_f32 v58, v58, v248, v30
	v_fma_f32 v59, v59, v248, v31
	v_fma_f32 v60, v60, v248, v32
	v_fma_f32 v61, v61, v248, v33
	v_cvt_pk_bf16_f32 v166, v62, v63
	v_cvt_pk_bf16_f32 v167, v64, v65
	v_cvt_pk_bf16_f32 v168, v58, v59
	v_cvt_pk_bf16_f32 v169, v60, v61
	global_store_dwordx4 v178, v[166:169], s[46:47] offset:0
	s_nop 1
	v_fma_f32 v54, v54, v248, v38
	v_fma_f32 v55, v55, v248, v39
	v_fma_f32 v56, v56, v248, v40
	v_fma_f32 v57, v57, v248, v41
	v_fma_f32 v50, v50, v248, v46
	v_fma_f32 v51, v51, v248, v47
	v_fma_f32 v52, v52, v248, v48
	v_fma_f32 v53, v53, v248, v49
	v_cvt_pk_bf16_f32 v166, v54, v55
	v_cvt_pk_bf16_f32 v167, v56, v57
	v_cvt_pk_bf16_f32 v168, v50, v51
	v_cvt_pk_bf16_f32 v169, v52, v53
	global_store_dwordx4 v178, v[166:169], s[46:47] offset:256
	s_nop 1
	s_add_u32 s46, s48, 0xdc000
	s_addc_u32 s47, s49, 0
	v_fma_f32 v42, v42, v249, v22
	v_fma_f32 v43, v43, v249, v23
	v_fma_f32 v44, v44, v249, v24
	v_fma_f32 v45, v45, v249, v25
	v_fma_f32 v34, v34, v249, v30
	v_fma_f32 v35, v35, v249, v31
	v_fma_f32 v36, v36, v249, v32
	v_fma_f32 v37, v37, v249, v33
	v_cvt_pk_bf16_f32 v166, v42, v43
	v_cvt_pk_bf16_f32 v167, v44, v45
	v_cvt_pk_bf16_f32 v168, v34, v35
	v_cvt_pk_bf16_f32 v169, v36, v37
	global_store_dwordx4 v178, v[166:169], s[46:47] offset:0
	s_nop 1
	v_fma_f32 v26, v26, v249, v38
	v_fma_f32 v27, v27, v249, v39
	v_fma_f32 v28, v28, v249, v40
	v_fma_f32 v29, v29, v249, v41
	v_fma_f32 v18, v18, v249, v46
	v_fma_f32 v19, v19, v249, v47
	v_fma_f32 v20, v20, v249, v48
	v_fma_f32 v21, v21, v249, v49
	v_cvt_pk_bf16_f32 v166, v26, v27
	v_cvt_pk_bf16_f32 v167, v28, v29
	v_cvt_pk_bf16_f32 v168, v18, v19
	v_cvt_pk_bf16_f32 v169, v20, v21
	global_store_dwordx4 v178, v[166:169], s[46:47] offset:256
	s_nop 1
	s_add_u32 s46, s48, 0xf2000
	s_addc_u32 s47, s49, 0
	v_fma_f32 v14, v14, v250, v22
	v_fma_f32 v15, v15, v250, v23
	v_fma_f32 v16, v16, v250, v24
	v_fma_f32 v17, v17, v250, v25
	v_fma_f32 v10, v10, v250, v30
	v_fma_f32 v11, v11, v250, v31
	v_fma_f32 v12, v12, v250, v32
	v_fma_f32 v13, v13, v250, v33
	v_cvt_pk_bf16_f32 v166, v14, v15
	v_cvt_pk_bf16_f32 v167, v16, v17
	v_cvt_pk_bf16_f32 v168, v10, v11
	v_cvt_pk_bf16_f32 v169, v12, v13
	global_store_dwordx4 v178, v[166:169], s[46:47] offset:0
	s_nop 1
	v_fma_f32 v6, v6, v250, v38
	v_fma_f32 v7, v7, v250, v39
	v_fma_f32 v8, v8, v250, v40
	v_fma_f32 v9, v9, v250, v41
	v_fma_f32 v2, v2, v250, v46
	v_fma_f32 v3, v3, v250, v47
	v_fma_f32 v4, v4, v250, v48
	v_fma_f32 v5, v5, v250, v49
	v_cvt_pk_bf16_f32 v166, v6, v7
	v_cvt_pk_bf16_f32 v167, v8, v9
	v_cvt_pk_bf16_f32 v168, v2, v3
	v_cvt_pk_bf16_f32 v169, v4, v5
	global_store_dwordx4 v178, v[166:169], s[46:47] offset:256
	s_nop 1
.Lp5_done:
.LBB0_1286:
	s_andn2_b64 vcc, exec, s[4:5]
	s_mov_b64 s[4:5], -1
	s_cbranch_vccnz .LBB0_477
	s_andn2_b64 vcc, exec, s[24:25]
	s_cbranch_vccnz .LBB0_476
	s_barrier
	s_branch .LBB0_476
